# MFMA-segment slimming: all 192 s_setprio flips and 48 redundant post-barrier lgkmcnt(0) waits removed from GEMM K-loops (on boff+ntK)
# speedup vs baseline: 1.0075x; 1.0075x over previous
; #define PG8_STAGE(bufoff, gbase, voff) do { _Pragma("unroll") for (int _i = 0; _i < 2; ++_i) \
;         __builtin_amdgcn_global_load_lds((const unsigned*)((const char*)(gbase) + (voff)[_i]), (PG8_LAS unsigned*)(lds + (bufoff) + ldsw + _i * 8192), 16, 0, 0); } while (0)
; #define PG8_LDA(dst, b, h) do { _Pragma("unroll") for (int m = 0; m < 4; ++m) _Pragma("unroll") for (int k = 0; k < 2; ++k) dst[m][k] = *(const PG8_LAS bf16x8*)(lds + PG8_SA(b, h) + aoff + m * 2048 + k * 1024); } while (0)
; #define PG8_LDB(dst, b, h) do { _Pragma("unroll") for (int n = 0; n < 2; ++n) _Pragma("unroll") for (int k = 0; k < 2; ++k) dst[n][k] = *(const PG8_LAS bf16x8*)(lds + PG8_SB(b, h) + boff + n * 2048 + k * 1024); } while (0)
; #define PG8_WAIT_V(n) asm volatile("s_waitcnt vmcnt(" #n ")" ::: "memory")
; #define PG8_WAIT_L(n) asm volatile("s_waitcnt lgkmcnt(" #n ")" ::: "memory")
; #define PG8_BAR __builtin_amdgcn_s_barrier()
; #define PG8_SCHED __builtin_amdgcn_sched_barrier(0)
; template <class Epi, class Sched, bool ALIGN_EPI = false, bool SP2 = false>
; __device__ __forceinline__ void gemm_phase(PG8_LAS unsigned char* lds, const Gemm g, const Sched& S, const Epi& E) {
;     ...
;         const char* nA = has_next ? (const char*)g.A + (size_t)nxt.pm * tstep : cA; const char* nB = has_next ? (const char*)g.Bt + (size_t)nxt.pn * tstep : cB;
;         for (int t = 0; t < nt; t += 2) {
;             const bool last = (t == nt - 2);
;             const char* a1 = cA + (size_t)(t + 1) * kstep;
;             const char* a2 = last ? nA : cA + (size_t)(t + 2) * kstep; const char* b2 = last ? nB : cB + (size_t)(t + 2) * kstep;
;             const char* a3 = a2 + kstep; const char* b3 = b2 + kstep;
;             if (last && has_next) S.a_ready(nxt);
;             if constexpr (SP2) {
;             PG8_LDB(B0, 0, 0); PG8_LDB(B1, 0, 1); PG8_SCHED; PG8_LDA(At, 0, 0); PG8_STAGE(PG8_SA(1, 1), a1 + hstep, voffA);
;             PG8_WAIT_V(8); PG8_WAIT_L(0); PG8_BAR; PG8_MMA(0, 0, At, B0); PG8_MMA(0, 1, At, B1); PG8_BAR; PG8_SCHED;
;             PG8_LDA(At, 0, 1); PG8_STAGE(PG8_SB(0, 0), b2, voffB); PG8_STAGE(PG8_SB(0, 1), b2 + hstep, voffB); PG8_STAGE(PG8_SA(0, 0), a2, voffA);
;             PG8_WAIT_V(8); PG8_WAIT_L(0); PG8_BAR; PG8_MMA(1, 0, At, B0); PG8_MMA(1, 1, At, B1); PG8_BAR; PG8_SCHED;
.Lboff_skip_B:
.LBB0_247:
	s_add_u32 s16, s18, 0xfffc0080
	s_addc_u32 s17, s19, -1
	s_add_i32 s52, 0, 0x10000
	s_cmp_eq_u32 s50, 12
	s_cselect_b32 s21, s11, s17
	s_cselect_b32 s20, s46, s16
	v_add_u32_e32 v0, s52, v147
	s_cselect_b32 s17, s9, vcc_hi
	s_cselect_b32 s16, s57, vcc_lo
	s_add_i32 s63, 0, 0x14000
	ds_read_b128 v[158:161], v0
	ds_read_b128 v[162:165], v0 offset:1024
	ds_read_b128 v[166:169], v0 offset:2048
	ds_read_b128 v[170:173], v0 offset:3072
	v_add_u32_e32 v0, s63, v147
	ds_read_b128 v[174:177], v0
	ds_read_b128 v[178:181], v0 offset:1024
	ds_read_b128 v[182:185], v0 offset:2048
	ds_read_b128 v[186:189], v0 offset:3072
	v_lshl_add_u64 v[210:211], s[18:19], 0, v[142:143]
	s_add_i32 m0, s27, 0xc000
	ds_read_b128 v[190:193], v156
	ds_read_b128 v[194:197], v156 offset:1024
	ds_read_b128 v[198:201], v156 offset:2048
	ds_read_b128 v[202:205], v156 offset:3072
	ds_read_b128 v[206:209], v156 offset:4096
	ds_read_b128 v[220:223], v156 offset:5120
	ds_read_b128 v[224:227], v156 offset:6144
	ds_read_b128 v[228:231], v156 offset:7168
	global_load_lds_dwordx4 v[210:211], off
	v_lshl_add_u64 v[210:211], s[18:19], 0, v[144:145]
	s_add_i32 m0, s27, 0xe000
	s_nop 0
	global_load_lds_dwordx4 v[210:211], off
	s_waitcnt vmcnt(8)
	s_waitcnt lgkmcnt(0)
	s_barrier
	v_mfma_f32_16x16x32_bf16 v[126:129], v[158:161], v[190:193], v[126:129]
	v_mfma_f32_16x16x32_bf16 v[122:125], v[166:169], v[190:193], v[122:125]
	v_mfma_f32_16x16x32_bf16 v[118:121], v[158:161], v[198:201], v[118:121]
	v_mfma_f32_16x16x32_bf16 v[110:113], v[166:169], v[198:201], v[110:113]
	v_mfma_f32_16x16x32_bf16 v[102:105], v[158:161], v[206:209], v[102:105]
	v_mfma_f32_16x16x32_bf16 v[94:97], v[166:169], v[206:209], v[94:97]
	v_mfma_f32_16x16x32_bf16 v[86:89], v[158:161], v[224:227], v[86:89]
	v_mfma_f32_16x16x32_bf16 v[78:81], v[166:169], v[224:227], v[78:81]
	v_mfma_f32_16x16x32_bf16 v[126:129], v[162:165], v[194:197], v[126:129]
	v_mfma_f32_16x16x32_bf16 v[122:125], v[170:173], v[194:197], v[122:125]
	v_mfma_f32_16x16x32_bf16 v[118:121], v[162:165], v[202:205], v[118:121]
	v_mfma_f32_16x16x32_bf16 v[110:113], v[170:173], v[202:205], v[110:113]
	v_mfma_f32_16x16x32_bf16 v[102:105], v[162:165], v[220:223], v[102:105]
	v_mfma_f32_16x16x32_bf16 v[94:97], v[170:173], v[220:223], v[94:97]
	v_mfma_f32_16x16x32_bf16 v[86:89], v[162:165], v[228:231], v[86:89]
	v_mfma_f32_16x16x32_bf16 v[78:81], v[170:173], v[228:231], v[78:81]
	v_mfma_f32_16x16x32_bf16 v[114:117], v[174:177], v[190:193], v[114:117]
	v_mfma_f32_16x16x32_bf16 v[106:109], v[182:185], v[190:193], v[106:109]
	v_mfma_f32_16x16x32_bf16 v[98:101], v[174:177], v[198:201], v[98:101]
	v_mfma_f32_16x16x32_bf16 v[90:93], v[182:185], v[198:201], v[90:93]
	v_mfma_f32_16x16x32_bf16 v[82:85], v[174:177], v[206:209], v[82:85]
	v_mfma_f32_16x16x32_bf16 v[74:77], v[182:185], v[206:209], v[74:77]
	v_mfma_f32_16x16x32_bf16 v[70:73], v[174:177], v[224:227], v[70:73]
	v_mfma_f32_16x16x32_bf16 v[66:69], v[182:185], v[224:227], v[66:69]
	v_mfma_f32_16x16x32_bf16 v[114:117], v[178:181], v[194:197], v[114:117]
	v_mfma_f32_16x16x32_bf16 v[106:109], v[186:189], v[194:197], v[106:109]
	v_mfma_f32_16x16x32_bf16 v[98:101], v[178:181], v[202:205], v[98:101]
	v_mfma_f32_16x16x32_bf16 v[90:93], v[186:189], v[202:205], v[90:93]
	v_mfma_f32_16x16x32_bf16 v[82:85], v[178:181], v[220:223], v[82:85]
	v_mfma_f32_16x16x32_bf16 v[74:77], v[186:189], v[220:223], v[74:77]
	v_mfma_f32_16x16x32_bf16 v[70:73], v[178:181], v[228:231], v[70:73]
	v_mfma_f32_16x16x32_bf16 v[66:69], v[186:189], v[228:231], v[66:69]
	s_barrier
	s_add_i32 s52, s52, s26
	v_lshl_add_u64 v[210:211], s[16:17], 0, v[134:135]
	s_mov_b32 m0, s52
	ds_read_b128 v[190:193], v156 offset:16384
	ds_read_b128 v[194:197], v156 offset:17408
	ds_read_b128 v[198:201], v156 offset:18432
	ds_read_b128 v[202:205], v156 offset:19456
	ds_read_b128 v[206:209], v156 offset:20480
	ds_read_b128 v[220:223], v156 offset:21504
	ds_read_b128 v[224:227], v156 offset:22528
	ds_read_b128 v[228:231], v156 offset:23552
	global_load_lds_dwordx4 v[210:211], off
	s_add_i32 m0, s52, 0x2000
	s_add_u32 s52, s16, 0x40000
	v_lshl_add_u64 v[212:213], s[16:17], 0, v[130:131]
	s_addc_u32 s53, s17, 0
	s_add_i32 s63, s63, s26
	global_load_lds_dwordx4 v[212:213], off
	v_lshl_add_u64 v[214:215], s[52:53], 0, v[134:135]
	s_mov_b32 m0, s63
	v_lshl_add_u64 v[216:217], s[20:21], 0, v[132:133]
	global_load_lds_dwordx4 v[214:215], off
	v_lshl_add_u64 v[214:215], s[52:53], 0, v[130:131]
	s_add_i32 m0, s63, 0x2000
	s_nop 0
	global_load_lds_dwordx4 v[214:215], off
	v_lshl_add_u64 v[214:215], s[20:21], 0, v[136:137]
	s_mov_b32 m0, s27
	s_nop 0
	global_load_lds_dwordx4 v[214:215], off
	s_mov_b32 m0, s28
	s_nop 0
	global_load_lds_dwordx4 v[216:217], off
	s_waitcnt vmcnt(8)
	s_waitcnt lgkmcnt(0)
	s_barrier
; #define PG8_STAGE(bufoff, gbase, voff) do { _Pragma("unroll") for (int _i = 0; _i < 2; ++_i) \
;         __builtin_amdgcn_global_load_lds((const unsigned*)((const char*)(gbase) + (voff)[_i]), (PG8_LAS unsigned*)(lds + (bufoff) + ldsw + _i * 8192), 16, 0, 0); } while (0)
; #define PG8_LDA(dst, b, h) do { _Pragma("unroll") for (int m = 0; m < 4; ++m) _Pragma("unroll") for (int k = 0; k < 2; ++k) dst[m][k] = *(const PG8_LAS bf16x8*)(lds + PG8_SA(b, h) + aoff + m * 2048 + k * 1024); } while (0)
; #define PG8_LDB(dst, b, h) do { _Pragma("unroll") for (int n = 0; n < 2; ++n) _Pragma("unroll") for (int k = 0; k < 2; ++k) dst[n][k] = *(const PG8_LAS bf16x8*)(lds + PG8_SB(b, h) + boff + n * 2048 + k * 1024); } while (0)
; #define PG8_MMA(ai, bj, At, Bt) do { __builtin_amdgcn_s_setprio(1); _Pragma("unroll") for (int m = 0; m < 4; ++m) _Pragma("unroll") for (int n = 0; n < 2; ++n) _Pragma("unroll") for (int k = 0; k < 2; ++k) \
;         acc[ai][bj][m][n] = __builtin_amdgcn_mfma_f32_16x16x32_bf16(Bt[n][k], At[m][k], acc[ai][bj][m][n], 0, 0, 0); __builtin_amdgcn_s_setprio(0); } while (0)
; #define PG8_WAIT_V(n) asm volatile("s_waitcnt vmcnt(" #n ")" ::: "memory")
; #define PG8_WAIT_L(n) asm volatile("s_waitcnt lgkmcnt(" #n ")" ::: "memory")
; #define PG8_BAR __builtin_amdgcn_s_barrier()
; #define PG8_SCHED __builtin_amdgcn_sched_barrier(0)
; template <class Epi, class Sched, bool ALIGN_EPI = false, bool SP2 = false>
; __device__ __forceinline__ void gemm_phase(PG8_LAS unsigned char* lds, const Gemm g, const Sched& S, const Epi& E) {
;     ...
;             PG8_WAIT_V(8); PG8_WAIT_L(0); PG8_BAR; PG8_MMA(1, 0, At, B0); PG8_MMA(1, 1, At, B1); PG8_BAR; PG8_SCHED;
;             PG8_LDB(B0, 1, 0); PG8_LDB(B1, 1, 1); PG8_SCHED; PG8_LDA(At, 1, 0); PG8_STAGE(PG8_SA(0, 1), a2 + hstep, voffA);
;             PG8_WAIT_V(8); PG8_WAIT_L(0); PG8_BAR; PG8_MMA(0, 0, At, B0); PG8_MMA(0, 1, At, B1); PG8_BAR; PG8_SCHED;
	v_mfma_f32_16x16x32_bf16 v[62:65], v[158:161], v[190:193], v[62:65]
	v_mfma_f32_16x16x32_bf16 v[58:61], v[166:169], v[190:193], v[58:61]
	v_mfma_f32_16x16x32_bf16 v[54:57], v[158:161], v[198:201], v[54:57]
	v_mfma_f32_16x16x32_bf16 v[46:49], v[166:169], v[198:201], v[46:49]
	v_mfma_f32_16x16x32_bf16 v[38:41], v[158:161], v[206:209], v[38:41]
	v_mfma_f32_16x16x32_bf16 v[30:33], v[166:169], v[206:209], v[30:33]
	v_mfma_f32_16x16x32_bf16 v[22:25], v[158:161], v[224:227], v[22:25]
	v_mfma_f32_16x16x32_bf16 v[14:17], v[166:169], v[224:227], v[14:17]
	v_mfma_f32_16x16x32_bf16 v[62:65], v[162:165], v[194:197], v[62:65]
	v_mfma_f32_16x16x32_bf16 v[58:61], v[170:173], v[194:197], v[58:61]
	v_mfma_f32_16x16x32_bf16 v[54:57], v[162:165], v[202:205], v[54:57]
	v_mfma_f32_16x16x32_bf16 v[46:49], v[170:173], v[202:205], v[46:49]
	v_mfma_f32_16x16x32_bf16 v[38:41], v[162:165], v[220:223], v[38:41]
	v_mfma_f32_16x16x32_bf16 v[30:33], v[170:173], v[220:223], v[30:33]
	v_mfma_f32_16x16x32_bf16 v[22:25], v[162:165], v[228:231], v[22:25]
	v_mfma_f32_16x16x32_bf16 v[14:17], v[170:173], v[228:231], v[14:17]
	v_mfma_f32_16x16x32_bf16 v[50:53], v[174:177], v[190:193], v[50:53]
	v_mfma_f32_16x16x32_bf16 v[42:45], v[182:185], v[190:193], v[42:45]
	v_mfma_f32_16x16x32_bf16 v[34:37], v[174:177], v[198:201], v[34:37]
	v_mfma_f32_16x16x32_bf16 v[26:29], v[182:185], v[198:201], v[26:29]
	v_mfma_f32_16x16x32_bf16 v[18:21], v[174:177], v[206:209], v[18:21]
	v_mfma_f32_16x16x32_bf16 v[10:13], v[182:185], v[206:209], v[10:13]
	v_mfma_f32_16x16x32_bf16 v[6:9], v[174:177], v[224:227], v[6:9]
	v_mfma_f32_16x16x32_bf16 v[2:5], v[182:185], v[224:227], v[2:5]
	v_mfma_f32_16x16x32_bf16 v[50:53], v[178:181], v[194:197], v[50:53]
	v_mfma_f32_16x16x32_bf16 v[42:45], v[186:189], v[194:197], v[42:45]
	v_mfma_f32_16x16x32_bf16 v[34:37], v[178:181], v[202:205], v[34:37]
	v_mfma_f32_16x16x32_bf16 v[26:29], v[186:189], v[202:205], v[26:29]
	v_mfma_f32_16x16x32_bf16 v[18:21], v[178:181], v[220:223], v[18:21]
	v_mfma_f32_16x16x32_bf16 v[10:13], v[186:189], v[220:223], v[10:13]
	v_mfma_f32_16x16x32_bf16 v[6:9], v[178:181], v[228:231], v[6:9]
	v_mfma_f32_16x16x32_bf16 v[2:5], v[186:189], v[228:231], v[2:5]
	s_barrier
	s_add_i32 s52, 0, 0x18000
	v_add_u32_e32 v0, s52, v147
	s_add_i32 s53, 0, 0x1c000
	ds_read_b128 v[158:161], v0
	ds_read_b128 v[162:165], v0 offset:1024
	ds_read_b128 v[166:169], v0 offset:2048
	ds_read_b128 v[170:173], v0 offset:3072
	v_add_u32_e32 v0, s53, v147
	ds_read_b128 v[174:177], v0
	ds_read_b128 v[178:181], v0 offset:1024
	ds_read_b128 v[182:185], v0 offset:2048
	ds_read_b128 v[186:189], v0 offset:3072
	s_add_u32 s20, s20, 0x40000
	s_addc_u32 s21, s21, 0
	s_mov_b32 m0, s29
	v_lshl_add_u64 v[232:233], s[20:21], 0, v[136:137]
	ds_read_b128 v[190:193], v156 offset:32768
	ds_read_b128 v[194:197], v156 offset:33792
	ds_read_b128 v[198:201], v156 offset:34816
	ds_read_b128 v[202:205], v156 offset:35840
	ds_read_b128 v[206:209], v156 offset:36864
	ds_read_b128 v[220:223], v156 offset:37888
	ds_read_b128 v[224:227], v156 offset:38912
	ds_read_b128 v[228:231], v156 offset:39936
	global_load_lds_dwordx4 v[232:233], off
	v_lshl_add_u64 v[232:233], s[20:21], 0, v[132:133]
	s_mov_b32 m0, s30
	s_nop 0
	global_load_lds_dwordx4 v[232:233], off
	s_waitcnt vmcnt(8)
	s_waitcnt lgkmcnt(0)
	s_barrier
	v_mfma_f32_16x16x32_bf16 v[126:129], v[158:161], v[190:193], v[126:129]
	v_mfma_f32_16x16x32_bf16 v[122:125], v[166:169], v[190:193], v[122:125]
	v_mfma_f32_16x16x32_bf16 v[118:121], v[158:161], v[198:201], v[118:121]
	v_mfma_f32_16x16x32_bf16 v[110:113], v[166:169], v[198:201], v[110:113]
	v_mfma_f32_16x16x32_bf16 v[102:105], v[158:161], v[206:209], v[102:105]
	v_mfma_f32_16x16x32_bf16 v[94:97], v[166:169], v[206:209], v[94:97]
	v_mfma_f32_16x16x32_bf16 v[86:89], v[158:161], v[224:227], v[86:89]
	v_mfma_f32_16x16x32_bf16 v[78:81], v[166:169], v[224:227], v[78:81]
	v_mfma_f32_16x16x32_bf16 v[126:129], v[162:165], v[194:197], v[126:129]
	v_mfma_f32_16x16x32_bf16 v[122:125], v[170:173], v[194:197], v[122:125]
	v_mfma_f32_16x16x32_bf16 v[118:121], v[162:165], v[202:205], v[118:121]
	v_mfma_f32_16x16x32_bf16 v[110:113], v[170:173], v[202:205], v[110:113]
	v_mfma_f32_16x16x32_bf16 v[102:105], v[162:165], v[220:223], v[102:105]
	v_mfma_f32_16x16x32_bf16 v[94:97], v[170:173], v[220:223], v[94:97]
	v_mfma_f32_16x16x32_bf16 v[86:89], v[162:165], v[228:231], v[86:89]
	v_mfma_f32_16x16x32_bf16 v[78:81], v[170:173], v[228:231], v[78:81]
	v_mfma_f32_16x16x32_bf16 v[114:117], v[174:177], v[190:193], v[114:117]
	v_mfma_f32_16x16x32_bf16 v[106:109], v[182:185], v[190:193], v[106:109]
	v_mfma_f32_16x16x32_bf16 v[98:101], v[174:177], v[198:201], v[98:101]
	v_mfma_f32_16x16x32_bf16 v[90:93], v[182:185], v[198:201], v[90:93]
	v_mfma_f32_16x16x32_bf16 v[82:85], v[174:177], v[206:209], v[82:85]
	v_mfma_f32_16x16x32_bf16 v[74:77], v[182:185], v[206:209], v[74:77]
	v_mfma_f32_16x16x32_bf16 v[70:73], v[174:177], v[224:227], v[70:73]
	v_mfma_f32_16x16x32_bf16 v[66:69], v[182:185], v[224:227], v[66:69]
	v_mfma_f32_16x16x32_bf16 v[114:117], v[178:181], v[194:197], v[114:117]
	v_mfma_f32_16x16x32_bf16 v[106:109], v[186:189], v[194:197], v[106:109]
	v_mfma_f32_16x16x32_bf16 v[98:101], v[178:181], v[202:205], v[98:101]
	v_mfma_f32_16x16x32_bf16 v[90:93], v[186:189], v[202:205], v[90:93]
	v_mfma_f32_16x16x32_bf16 v[82:85], v[178:181], v[220:223], v[82:85]
	v_mfma_f32_16x16x32_bf16 v[74:77], v[186:189], v[220:223], v[74:77]
	v_mfma_f32_16x16x32_bf16 v[70:73], v[178:181], v[228:231], v[70:73]
	v_mfma_f32_16x16x32_bf16 v[66:69], v[186:189], v[228:231], v[66:69]
	s_barrier
; #define PG8_STAGE(bufoff, gbase, voff) do { _Pragma("unroll") for (int _i = 0; _i < 2; ++_i) \
;         __builtin_amdgcn_global_load_lds((const unsigned*)((const char*)(gbase) + (voff)[_i]), (PG8_LAS unsigned*)(lds + (bufoff) + ldsw + _i * 8192), 16, 0, 0); } while (0)
; #define PG8_LDA(dst, b, h) do { _Pragma("unroll") for (int m = 0; m < 4; ++m) _Pragma("unroll") for (int k = 0; k < 2; ++k) dst[m][k] = *(const PG8_LAS bf16x8*)(lds + PG8_SA(b, h) + aoff + m * 2048 + k * 1024); } while (0)
; #define PG8_MMA(ai, bj, At, Bt) do { __builtin_amdgcn_s_setprio(1); _Pragma("unroll") for (int m = 0; m < 4; ++m) _Pragma("unroll") for (int n = 0; n < 2; ++n) _Pragma("unroll") for (int k = 0; k < 2; ++k) \
;         acc[ai][bj][m][n] = __builtin_amdgcn_mfma_f32_16x16x32_bf16(Bt[n][k], At[m][k], acc[ai][bj][m][n], 0, 0, 0); __builtin_amdgcn_s_setprio(0); } while (0)
; #define PG8_WAIT_V(n) asm volatile("s_waitcnt vmcnt(" #n ")" ::: "memory")
; #define PG8_WAIT_L(n) asm volatile("s_waitcnt lgkmcnt(" #n ")" ::: "memory")
; #define PG8_BAR __builtin_amdgcn_s_barrier()
; #define PG8_SCHED __builtin_amdgcn_sched_barrier(0)
; template <class Epi, class Sched, bool ALIGN_EPI = false, bool SP2 = false>
; __device__ __forceinline__ void gemm_phase(PG8_LAS unsigned char* lds, const Gemm g, const Sched& S, const Epi& E) {
;     ...
;         for (int t = 0; t < nt; t += 2) {
;             const bool last = (t == nt - 2);
;             const char* a1 = cA + (size_t)(t + 1) * kstep;
;             const char* a2 = last ? nA : cA + (size_t)(t + 2) * kstep; const char* b2 = last ? nB : cB + (size_t)(t + 2) * kstep;
;     ...
;             PG8_LDA(At, 1, 1); PG8_STAGE(PG8_SB(1, 0), b3, voffB); PG8_STAGE(PG8_SB(1, 1), b3 + hstep, voffB); PG8_STAGE(PG8_SA(1, 0), a3, voffA);
;             PG8_WAIT_V(8); PG8_WAIT_L(0); PG8_BAR; PG8_MMA(1, 0, At, B0); PG8_MMA(1, 1, At, B1); PG8_BAR; PG8_SCHED;
;     ...
;         if constexpr (ALIGN_EPI) { if (wr == 0) PG8_BAR; }
	s_add_i32 s20, s52, s26
	v_lshl_add_u64 v[210:211], v[210:211], 0, s[94:95]
	s_mov_b32 m0, s20
	ds_read_b128 v[190:193], v156 offset:49152
	ds_read_b128 v[194:197], v156 offset:50176
	ds_read_b128 v[198:201], v156 offset:51200
	ds_read_b128 v[202:205], v156 offset:52224
	ds_read_b128 v[206:209], v156 offset:53248
	ds_read_b128 v[220:223], v156 offset:54272
	ds_read_b128 v[224:227], v156 offset:55296
	ds_read_b128 v[228:231], v156 offset:56320
	global_load_lds_dwordx4 v[210:211], off
	s_add_i32 m0, s20, 0x2000
	s_add_u32 s16, s16, 0x40080
	v_lshl_add_u64 v[210:211], v[212:213], 0, s[94:95]
	s_addc_u32 s17, s17, 0
	s_add_i32 s20, s53, s26
	global_load_lds_dwordx4 v[210:211], off
	v_lshl_add_u64 v[210:211], s[16:17], 0, v[134:135]
	s_mov_b32 m0, s20
	s_nop 0
	global_load_lds_dwordx4 v[210:211], off
	v_lshl_add_u64 v[210:211], s[16:17], 0, v[130:131]
	s_add_i32 m0, s20, 0x2000
	s_nop 0
	global_load_lds_dwordx4 v[210:211], off
	v_lshl_add_u64 v[210:211], v[214:215], 0, s[94:95]
	s_mov_b32 m0, s38
	s_nop 0
	global_load_lds_dwordx4 v[210:211], off
	v_lshl_add_u64 v[210:211], v[216:217], 0, s[94:95]
	s_mov_b32 m0, s39
	s_nop 0
	global_load_lds_dwordx4 v[210:211], off
	s_waitcnt vmcnt(8)
	s_waitcnt lgkmcnt(0)
	s_barrier
	v_mfma_f32_16x16x32_bf16 v[62:65], v[158:161], v[190:193], v[62:65]
	v_mfma_f32_16x16x32_bf16 v[58:61], v[166:169], v[190:193], v[58:61]
	v_mfma_f32_16x16x32_bf16 v[54:57], v[158:161], v[198:201], v[54:57]
	v_mfma_f32_16x16x32_bf16 v[46:49], v[166:169], v[198:201], v[46:49]
	v_mfma_f32_16x16x32_bf16 v[38:41], v[158:161], v[206:209], v[38:41]
	v_mfma_f32_16x16x32_bf16 v[30:33], v[166:169], v[206:209], v[30:33]
	v_mfma_f32_16x16x32_bf16 v[22:25], v[158:161], v[224:227], v[22:25]
	v_mfma_f32_16x16x32_bf16 v[14:17], v[166:169], v[224:227], v[14:17]
	v_mfma_f32_16x16x32_bf16 v[62:65], v[162:165], v[194:197], v[62:65]
	v_mfma_f32_16x16x32_bf16 v[58:61], v[170:173], v[194:197], v[58:61]
	v_mfma_f32_16x16x32_bf16 v[54:57], v[162:165], v[202:205], v[54:57]
	v_mfma_f32_16x16x32_bf16 v[46:49], v[170:173], v[202:205], v[46:49]
	v_mfma_f32_16x16x32_bf16 v[38:41], v[162:165], v[220:223], v[38:41]
	v_mfma_f32_16x16x32_bf16 v[30:33], v[170:173], v[220:223], v[30:33]
	v_mfma_f32_16x16x32_bf16 v[22:25], v[162:165], v[228:231], v[22:25]
	v_mfma_f32_16x16x32_bf16 v[14:17], v[170:173], v[228:231], v[14:17]
	v_mfma_f32_16x16x32_bf16 v[50:53], v[174:177], v[190:193], v[50:53]
	v_mfma_f32_16x16x32_bf16 v[42:45], v[182:185], v[190:193], v[42:45]
	v_mfma_f32_16x16x32_bf16 v[34:37], v[174:177], v[198:201], v[34:37]
	v_mfma_f32_16x16x32_bf16 v[26:29], v[182:185], v[198:201], v[26:29]
	v_mfma_f32_16x16x32_bf16 v[18:21], v[174:177], v[206:209], v[18:21]
	v_mfma_f32_16x16x32_bf16 v[10:13], v[182:185], v[206:209], v[10:13]
	v_mfma_f32_16x16x32_bf16 v[6:9], v[174:177], v[224:227], v[6:9]
	v_mfma_f32_16x16x32_bf16 v[2:5], v[182:185], v[224:227], v[2:5]
	v_mfma_f32_16x16x32_bf16 v[50:53], v[178:181], v[194:197], v[50:53]
	v_mfma_f32_16x16x32_bf16 v[42:45], v[186:189], v[194:197], v[42:45]
	v_mfma_f32_16x16x32_bf16 v[34:37], v[178:181], v[202:205], v[34:37]
	v_mfma_f32_16x16x32_bf16 v[26:29], v[186:189], v[202:205], v[26:29]
	v_mfma_f32_16x16x32_bf16 v[18:21], v[178:181], v[220:223], v[18:21]
	v_mfma_f32_16x16x32_bf16 v[10:13], v[186:189], v[220:223], v[10:13]
	v_mfma_f32_16x16x32_bf16 v[6:9], v[178:181], v[228:231], v[6:9]
	v_mfma_f32_16x16x32_bf16 v[2:5], v[186:189], v[228:231], v[2:5]
	s_barrier
	s_add_i32 s50, s50, 2
	s_add_u32 s18, s18, 0x100
	s_addc_u32 s19, s19, 0
	s_add_u32 vcc_lo, vcc_lo, 0x100
	s_addc_u32 vcc_hi, vcc_hi, 0
	s_cmp_gt_u32 s50, 13
	s_cbranch_scc0 .LBB0_247
	s_and_b64 vcc, exec, s[6:7]
	s_cbranch_vccz .LBB0_252
	s_barrier
	s_cmp_gt_i32 s56, 5
	s_mov_b64 s[16:17], -1
	s_cbranch_scc1 .LBB0_253

; #define PG8_STAGE(bufoff, gbase, voff) do { _Pragma("unroll") for (int _i = 0; _i < 2; ++_i) \
;         __builtin_amdgcn_global_load_lds((const unsigned*)((const char*)(gbase) + (voff)[_i]), (PG8_LAS unsigned*)(lds + (bufoff) + ldsw + _i * 8192), 16, 0, 0); } while (0)
; #define PG8_LDA(dst, b, h) do { _Pragma("unroll") for (int m = 0; m < 4; ++m) _Pragma("unroll") for (int k = 0; k < 2; ++k) dst[m][k] = *(const PG8_LAS bf16x8*)(lds + PG8_SA(b, h) + aoff + m * 2048 + k * 1024); } while (0)
; #define PG8_LDB(dst, b, h) do { _Pragma("unroll") for (int n = 0; n < 2; ++n) _Pragma("unroll") for (int k = 0; k < 2; ++k) dst[n][k] = *(const PG8_LAS bf16x8*)(lds + PG8_SB(b, h) + boff + n * 2048 + k * 1024); } while (0)
; #define PG8_MMA(ai, bj, At, Bt) do { __builtin_amdgcn_s_setprio(1); _Pragma("unroll") for (int m = 0; m < 4; ++m) _Pragma("unroll") for (int n = 0; n < 2; ++n) _Pragma("unroll") for (int k = 0; k < 2; ++k) \
;         acc[ai][bj][m][n] = __builtin_amdgcn_mfma_f32_16x16x32_bf16(Bt[n][k], At[m][k], acc[ai][bj][m][n], 0, 0, 0); __builtin_amdgcn_s_setprio(0); } while (0)
; #define PG8_WAIT_V(n) asm volatile("s_waitcnt vmcnt(" #n ")" ::: "memory")
;     __device__ __forceinline__ void operator()(const f32x4 (&acc)[2][2][4][2], const Unit& u, int wr, int wc, int fr, int fq) const {
;         EPI_LOOP_BEGIN if (bj == 0) { float* d = SLOC + (size_t)row * 128 + ct; *(f32x4*)d = v0; *(f32x4*)(d + 4) = v1; } EPI_LOOP_END
; template <class Epi, class Sched, bool ALIGN_EPI = false, bool SP2 = false>
; __device__ __forceinline__ void gemm_phase(PG8_LAS unsigned char* lds, const Gemm g, const Sched& S, const Epi& E) {
;     ...
;             PG8_LDB(B0, 0, 0); PG8_LDB(B1, 0, 1); PG8_SCHED; PG8_LDA(At, 0, 0); PG8_STAGE(PG8_SA(1, 1), a1 + hstep, voffA);
;             PG8_WAIT_V(8); PG8_WAIT_L(0); PG8_BAR; PG8_MMA(0, 0, At, B0); PG8_MMA(0, 1, At, B1); PG8_BAR; PG8_SCHED;
;             PG8_LDA(At, 0, 1); PG8_STAGE(PG8_SB(0, 0), b2, voffB); PG8_STAGE(PG8_SB(0, 1), b2 + hstep, voffB); PG8_STAGE(PG8_SA(0, 0), a2, voffA);
;             PG8_WAIT_V(8); PG8_WAIT_L(0); PG8_BAR; PG8_MMA(1, 0, At, B0); PG8_MMA(1, 1, At, B1); PG8_BAR; PG8_SCHED;
;             PG8_LDB(B0, 1, 0); PG8_LDB(B1, 1, 1); PG8_SCHED; PG8_LDA(At, 1, 0); PG8_STAGE(PG8_SA(0, 1), a2 + hstep, voffA);
;             PG8_WAIT_V(8); PG8_WAIT_L(0); PG8_BAR; PG8_MMA(0, 0, At, B0); PG8_MMA(0, 1, At, B1); PG8_BAR; PG8_SCHED;
.LBB0_317:
	s_add_i32 s38, 0, 0x10000
	v_add_u32_e32 v138, s38, v75
	ds_read_b128 v[2:5], v138
	ds_read_b128 v[6:9], v138 offset:1024
	ds_read_b128 v[10:13], v138 offset:2048
	ds_read_b128 v[14:17], v138 offset:3072
	s_add_u32 s36, s14, 0x18080
	s_addc_u32 s37, s15, 0
	s_add_i32 s39, s21, 0xc000
	v_lshl_add_u64 v[50:51], s[36:37], 0, v[70:71]
	s_mov_b32 m0, s39
	s_add_i32 s35, s21, 0xe000
	ds_read_b128 v[18:21], v79
	ds_read_b128 v[22:25], v79 offset:1024
	ds_read_b128 v[26:29], v79 offset:2048
	ds_read_b128 v[30:33], v79 offset:3072
	ds_read_b128 v[34:37], v79 offset:4096
	ds_read_b128 v[38:41], v79 offset:5120
	ds_read_b128 v[42:45], v79 offset:6144
	ds_read_b128 v[46:49], v79 offset:7168
	global_load_lds_dwordx4 v[50:51], off
	v_lshl_add_u64 v[50:51], s[36:37], 0, v[68:69]
	s_mov_b32 m0, s35
	s_nop 0
	global_load_lds_dwordx4 v[50:51], off
	s_waitcnt vmcnt(8)
	s_waitcnt lgkmcnt(0)
	s_barrier
	v_mfma_f32_16x16x32_bf16 v[50:53], v[2:5], v[18:21], 0
	v_mfma_f32_16x16x32_bf16 v[18:21], v[10:13], v[18:21], 0
	v_mfma_f32_16x16x32_bf16 v[50:53], v[6:9], v[22:25], v[50:53]
	v_mfma_f32_16x16x32_bf16 v[18:21], v[14:17], v[22:25], v[18:21]
	v_mfma_f32_16x16x32_bf16 v[22:25], v[2:5], v[26:29], 0
	v_mfma_f32_16x16x32_bf16 v[26:29], v[10:13], v[26:29], 0
	v_mfma_f32_16x16x32_bf16 v[22:25], v[6:9], v[30:33], v[22:25]
	v_mfma_f32_16x16x32_bf16 v[26:29], v[14:17], v[30:33], v[26:29]
	v_mfma_f32_16x16x32_bf16 v[30:33], v[2:5], v[34:37], 0
	v_mfma_f32_16x16x32_bf16 v[34:37], v[10:13], v[34:37], 0
	v_mfma_f32_16x16x32_bf16 v[30:33], v[6:9], v[38:41], v[30:33]
	v_mfma_f32_16x16x32_bf16 v[34:37], v[14:17], v[38:41], v[34:37]
	v_mfma_f32_16x16x32_bf16 v[38:41], v[2:5], v[42:45], 0
	v_mfma_f32_16x16x32_bf16 v[42:45], v[10:13], v[42:45], 0
	v_mfma_f32_16x16x32_bf16 v[38:41], v[6:9], v[46:49], v[38:41]
	v_mfma_f32_16x16x32_bf16 v[42:45], v[14:17], v[46:49], v[42:45]
	s_barrier
	s_add_i32 s38, s38, s20
	v_lshl_add_u64 v[128:129], s[16:17], 0, v[0:1]
	s_add_i32 s36, s38, 0x2000
	v_lshl_add_u64 v[96:97], v[128:129], 0, s[90:91]
	s_mov_b32 m0, s38
	v_lshl_add_u64 v[130:131], s[16:17], 0, v[66:67]
	s_add_u32 s52, s16, 0x18100
	ds_read_b128 v[46:49], v79 offset:16384
	ds_read_b128 v[54:57], v79 offset:17408
	ds_read_b128 v[58:61], v79 offset:18432
	ds_read_b128 v[62:65], v79 offset:19456
	ds_read_b128 v[80:83], v79 offset:20480
	ds_read_b128 v[84:87], v79 offset:21504
	ds_read_b128 v[88:91], v79 offset:22528
	ds_read_b128 v[92:95], v79 offset:23552
	global_load_lds_dwordx4 v[96:97], off
	v_lshl_add_u64 v[96:97], v[130:131], 0, s[90:91]
	s_mov_b32 m0, s36
	s_addc_u32 s53, s17, 0
	global_load_lds_dwordx4 v[96:97], off
	v_lshl_add_u64 v[96:97], s[52:53], 0, v[0:1]
	s_mov_b32 m0, s22
	v_lshl_add_u64 v[132:133], s[14:15], 0, v[70:71]
	global_load_lds_dwordx4 v[96:97], off
	v_lshl_add_u64 v[96:97], s[52:53], 0, v[66:67]
	s_mov_b32 m0, s23
	v_lshl_add_u64 v[134:135], s[14:15], 0, v[68:69]
	global_load_lds_dwordx4 v[96:97], off
	v_lshl_add_u64 v[96:97], v[132:133], 0, s[90:91]
	s_mov_b32 m0, s21
	s_nop 0
	global_load_lds_dwordx4 v[96:97], off
	v_lshl_add_u64 v[96:97], v[134:135], 0, s[90:91]
	s_mov_b32 m0, s24
	s_nop 0
	global_load_lds_dwordx4 v[96:97], off
	s_waitcnt vmcnt(8)
	s_waitcnt lgkmcnt(0)
	s_barrier
	v_mfma_f32_16x16x32_bf16 v[96:99], v[2:5], v[46:49], 0
	v_mfma_f32_16x16x32_bf16 v[46:49], v[10:13], v[46:49], 0
	v_mfma_f32_16x16x32_bf16 v[96:99], v[6:9], v[54:57], v[96:99]
	v_mfma_f32_16x16x32_bf16 v[46:49], v[14:17], v[54:57], v[46:49]
	v_mfma_f32_16x16x32_bf16 v[54:57], v[2:5], v[58:61], 0
	v_mfma_f32_16x16x32_bf16 v[58:61], v[10:13], v[58:61], 0
	v_mfma_f32_16x16x32_bf16 v[54:57], v[6:9], v[62:65], v[54:57]
	v_mfma_f32_16x16x32_bf16 v[58:61], v[14:17], v[62:65], v[58:61]
	v_mfma_f32_16x16x32_bf16 v[62:65], v[2:5], v[80:83], 0
	v_mfma_f32_16x16x32_bf16 v[2:5], v[2:5], v[88:91], 0
	v_mfma_f32_16x16x32_bf16 v[62:65], v[6:9], v[84:87], v[62:65]
	v_mfma_f32_16x16x32_bf16 v[2:5], v[6:9], v[92:95], v[2:5]
	v_mfma_f32_16x16x32_bf16 v[6:9], v[10:13], v[88:91], 0
	v_mfma_f32_16x16x32_bf16 v[80:83], v[10:13], v[80:83], 0
	v_mfma_f32_16x16x32_bf16 v[6:9], v[14:17], v[92:95], v[6:9]
	v_mfma_f32_16x16x32_bf16 v[80:83], v[14:17], v[84:87], v[80:83]
	s_barrier
	s_add_i32 s46, 0, 0x18000
	v_add_u32_e32 v139, s46, v75
	ds_read_b128 v[10:13], v139
	ds_read_b128 v[14:17], v139 offset:1024
	ds_read_b128 v[84:87], v139 offset:2048
	ds_read_b128 v[88:91], v139 offset:3072
	s_add_u32 s52, s14, 0x18100
	s_addc_u32 s53, s15, 0
	s_mov_b32 m0, s25
	v_lshl_add_u64 v[136:137], s[52:53], 0, v[70:71]
	ds_read_b128 v[92:95], v79 offset:32768
	ds_read_b128 v[100:103], v79 offset:33792
	ds_read_b128 v[104:107], v79 offset:34816
	ds_read_b128 v[108:111], v79 offset:35840
	ds_read_b128 v[112:115], v79 offset:36864
	ds_read_b128 v[116:119], v79 offset:37888
	ds_read_b128 v[120:123], v79 offset:38912
	ds_read_b128 v[124:127], v79 offset:39936
	global_load_lds_dwordx4 v[136:137], off
	v_lshl_add_u64 v[136:137], s[52:53], 0, v[68:69]
	s_mov_b32 m0, s26
	s_nop 0
	global_load_lds_dwordx4 v[136:137], off
	s_waitcnt vmcnt(8)
	s_waitcnt lgkmcnt(0)
	s_barrier
	v_mfma_f32_16x16x32_bf16 v[50:53], v[10:13], v[92:95], v[50:53]
	v_mfma_f32_16x16x32_bf16 v[18:21], v[84:87], v[92:95], v[18:21]
	v_mfma_f32_16x16x32_bf16 v[22:25], v[10:13], v[104:107], v[22:25]
	v_mfma_f32_16x16x32_bf16 v[26:29], v[84:87], v[104:107], v[26:29]
	v_mfma_f32_16x16x32_bf16 v[30:33], v[10:13], v[112:115], v[30:33]
	v_mfma_f32_16x16x32_bf16 v[34:37], v[84:87], v[112:115], v[34:37]
	v_mfma_f32_16x16x32_bf16 v[38:41], v[10:13], v[120:123], v[38:41]
	v_mfma_f32_16x16x32_bf16 v[42:45], v[84:87], v[120:123], v[42:45]
	v_mfma_f32_16x16x32_bf16 v[50:53], v[14:17], v[100:103], v[50:53]
	v_mfma_f32_16x16x32_bf16 v[18:21], v[88:91], v[100:103], v[18:21]
	v_mfma_f32_16x16x32_bf16 v[22:25], v[14:17], v[108:111], v[22:25]
	v_mfma_f32_16x16x32_bf16 v[26:29], v[88:91], v[108:111], v[26:29]
	v_mfma_f32_16x16x32_bf16 v[30:33], v[14:17], v[116:119], v[30:33]
	v_mfma_f32_16x16x32_bf16 v[34:37], v[88:91], v[116:119], v[34:37]
	v_mfma_f32_16x16x32_bf16 v[38:41], v[14:17], v[124:127], v[38:41]
	v_mfma_f32_16x16x32_bf16 v[42:45], v[88:91], v[124:127], v[42:45]
	s_barrier
; #define PG8_STAGE(bufoff, gbase, voff) do { _Pragma("unroll") for (int _i = 0; _i < 2; ++_i) \
;         __builtin_amdgcn_global_load_lds((const unsigned*)((const char*)(gbase) + (voff)[_i]), (PG8_LAS unsigned*)(lds + (bufoff) + ldsw + _i * 8192), 16, 0, 0); } while (0)
; #define PG8_LDA(dst, b, h) do { _Pragma("unroll") for (int m = 0; m < 4; ++m) _Pragma("unroll") for (int k = 0; k < 2; ++k) dst[m][k] = *(const PG8_LAS bf16x8*)(lds + PG8_SA(b, h) + aoff + m * 2048 + k * 1024); } while (0)
; #define PG8_LDB(dst, b, h) do { _Pragma("unroll") for (int n = 0; n < 2; ++n) _Pragma("unroll") for (int k = 0; k < 2; ++k) dst[n][k] = *(const PG8_LAS bf16x8*)(lds + PG8_SB(b, h) + boff + n * 2048 + k * 1024); } while (0)
; #define PG8_MMA(ai, bj, At, Bt) do { __builtin_amdgcn_s_setprio(1); _Pragma("unroll") for (int m = 0; m < 4; ++m) _Pragma("unroll") for (int n = 0; n < 2; ++n) _Pragma("unroll") for (int k = 0; k < 2; ++k) \
;         acc[ai][bj][m][n] = __builtin_amdgcn_mfma_f32_16x16x32_bf16(Bt[n][k], At[m][k], acc[ai][bj][m][n], 0, 0, 0); __builtin_amdgcn_s_setprio(0); } while (0)
; #define PG8_WAIT_V(n) asm volatile("s_waitcnt vmcnt(" #n ")" ::: "memory")
; template <class Epi, class Sched, bool ALIGN_EPI = false, bool SP2 = false>
; __device__ __forceinline__ void gemm_phase(PG8_LAS unsigned char* lds, const Gemm g, const Sched& S, const Epi& E) {
;     ...
;             PG8_LDB(B0, 0, 0); PG8_LDB(B1, 0, 1); PG8_SCHED; PG8_LDA(At, 0, 0); PG8_STAGE(PG8_SA(1, 1), a1 + hstep, voffA);
;             PG8_WAIT_V(8); PG8_WAIT_L(0); PG8_BAR; PG8_MMA(0, 0, At, B0); PG8_MMA(0, 1, At, B1); PG8_BAR; PG8_SCHED;
;             PG8_LDA(At, 0, 1); PG8_STAGE(PG8_SB(0, 0), b2, voffB); PG8_STAGE(PG8_SB(0, 1), b2 + hstep, voffB); PG8_STAGE(PG8_SA(0, 0), a2, voffA);
;             PG8_WAIT_V(8); PG8_WAIT_L(0); PG8_BAR; PG8_MMA(1, 0, At, B0); PG8_MMA(1, 1, At, B1); PG8_BAR; PG8_SCHED;
;             PG8_LDB(B0, 1, 0); PG8_LDB(B1, 1, 1); PG8_SCHED; PG8_LDA(At, 1, 0); PG8_STAGE(PG8_SA(0, 1), a2 + hstep, voffA);
;             PG8_WAIT_V(8); PG8_WAIT_L(0); PG8_BAR; PG8_MMA(0, 0, At, B0); PG8_MMA(0, 1, At, B1); PG8_BAR; PG8_SCHED;
;             PG8_LDA(At, 1, 1); PG8_STAGE(PG8_SB(1, 0), b3, voffB); PG8_STAGE(PG8_SB(1, 1), b3 + hstep, voffB); PG8_STAGE(PG8_SA(1, 0), a3, voffA);
;             PG8_WAIT_V(8); PG8_WAIT_L(0); PG8_BAR; PG8_MMA(1, 0, At, B0); PG8_MMA(1, 1, At, B1); PG8_BAR; PG8_SCHED;
	s_add_i32 s46, s46, s20
	s_add_i32 s37, s46, 0x2000
	v_lshl_add_u64 v[128:129], v[128:129], 0, s[76:77]
	s_mov_b32 m0, s46
	s_add_u32 s16, s16, 0x18180
	ds_read_b128 v[92:95], v79 offset:49152
	ds_read_b128 v[100:103], v79 offset:50176
	ds_read_b128 v[104:107], v79 offset:51200
	ds_read_b128 v[108:111], v79 offset:52224
	ds_read_b128 v[112:115], v79 offset:53248
	ds_read_b128 v[116:119], v79 offset:54272
	ds_read_b128 v[120:123], v79 offset:55296
	ds_read_b128 v[124:127], v79 offset:56320
	global_load_lds_dwordx4 v[128:129], off
	v_lshl_add_u64 v[128:129], v[130:131], 0, s[76:77]
	s_mov_b32 m0, s37
	s_addc_u32 s17, s17, 0
	global_load_lds_dwordx4 v[128:129], off
	v_lshl_add_u64 v[128:129], s[16:17], 0, v[0:1]
	s_mov_b32 m0, s29
	s_nop 0
	global_load_lds_dwordx4 v[128:129], off
	v_lshl_add_u64 v[128:129], s[16:17], 0, v[66:67]
	s_mov_b32 m0, s30
	s_nop 0
	global_load_lds_dwordx4 v[128:129], off
	v_lshl_add_u64 v[128:129], v[132:133], 0, s[76:77]
	s_mov_b32 m0, s27
	s_nop 0
	global_load_lds_dwordx4 v[128:129], off
	v_lshl_add_u64 v[128:129], v[134:135], 0, s[76:77]
	s_mov_b32 m0, s28
	s_nop 0
	global_load_lds_dwordx4 v[128:129], off
	s_waitcnt vmcnt(8)
	s_waitcnt lgkmcnt(0)
	s_barrier
	v_mfma_f32_16x16x32_bf16 v[46:49], v[84:87], v[92:95], v[46:49]
	v_mfma_f32_16x16x32_bf16 v[54:57], v[10:13], v[104:107], v[54:57]
	v_mfma_f32_16x16x32_bf16 v[58:61], v[84:87], v[104:107], v[58:61]
	v_mfma_f32_16x16x32_bf16 v[62:65], v[10:13], v[112:115], v[62:65]
	v_mfma_f32_16x16x32_bf16 v[2:5], v[10:13], v[120:123], v[2:5]
	v_mfma_f32_16x16x32_bf16 v[6:9], v[84:87], v[120:123], v[6:9]
	v_mfma_f32_16x16x32_bf16 v[96:99], v[10:13], v[92:95], v[96:99]
	v_mfma_f32_16x16x32_bf16 v[46:49], v[88:91], v[100:103], v[46:49]
	v_mfma_f32_16x16x32_bf16 v[54:57], v[14:17], v[108:111], v[54:57]
	v_mfma_f32_16x16x32_bf16 v[58:61], v[88:91], v[108:111], v[58:61]
	v_mfma_f32_16x16x32_bf16 v[62:65], v[14:17], v[116:119], v[62:65]
	v_mfma_f32_16x16x32_bf16 v[80:83], v[84:87], v[112:115], v[80:83]
	v_mfma_f32_16x16x32_bf16 v[2:5], v[14:17], v[124:127], v[2:5]
	v_mfma_f32_16x16x32_bf16 v[6:9], v[88:91], v[124:127], v[6:9]
	v_mfma_f32_16x16x32_bf16 v[96:99], v[14:17], v[100:103], v[96:99]
	v_mfma_f32_16x16x32_bf16 v[80:83], v[88:91], v[116:119], v[80:83]
	s_barrier
	ds_read_b128 v[10:13], v138
	ds_read_b128 v[14:17], v138 offset:1024
	ds_read_b128 v[84:87], v138 offset:2048
	ds_read_b128 v[88:91], v138 offset:3072
	s_add_u32 s14, s14, 0x18180
	s_addc_u32 s15, s15, 0
	s_mov_b32 m0, s39
	v_lshl_add_u64 v[128:129], s[14:15], 0, v[70:71]
	ds_read_b128 v[92:95], v79
	ds_read_b128 v[100:103], v79 offset:1024
	ds_read_b128 v[104:107], v79 offset:2048
	ds_read_b128 v[108:111], v79 offset:3072
	ds_read_b128 v[112:115], v79 offset:4096
	ds_read_b128 v[116:119], v79 offset:5120
	ds_read_b128 v[120:123], v79 offset:6144
	ds_read_b128 v[124:127], v79 offset:7168
	global_load_lds_dwordx4 v[128:129], off
	v_lshl_add_u64 v[128:129], s[14:15], 0, v[68:69]
	s_mov_b32 m0, s35
	s_nop 0
	global_load_lds_dwordx4 v[128:129], off
	s_waitcnt vmcnt(8)
	s_waitcnt lgkmcnt(0)
	s_barrier
	v_mfma_f32_16x16x32_bf16 v[26:29], v[84:87], v[104:107], v[26:29]
	v_mfma_f32_16x16x32_bf16 v[50:53], v[10:13], v[92:95], v[50:53]
	v_mfma_f32_16x16x32_bf16 v[18:21], v[84:87], v[92:95], v[18:21]
	v_mfma_f32_16x16x32_bf16 v[92:95], v[88:91], v[108:111], v[26:29]
	v_mfma_f32_16x16x32_bf16 v[26:29], v[10:13], v[112:115], v[30:33]
	v_mfma_f32_16x16x32_bf16 v[50:53], v[14:17], v[100:103], v[50:53]
	v_mfma_f32_16x16x32_bf16 v[18:21], v[88:91], v[100:103], v[18:21]
	v_mfma_f32_16x16x32_bf16 v[100:103], v[14:17], v[116:119], v[26:29]
	v_mfma_f32_16x16x32_bf16 v[26:29], v[84:87], v[112:115], v[34:37]
	v_mfma_f32_16x16x32_bf16 v[34:37], v[88:91], v[116:119], v[26:29]
	v_mfma_f32_16x16x32_bf16 v[26:29], v[10:13], v[120:123], v[38:41]
	v_mfma_f32_16x16x32_bf16 v[22:25], v[10:13], v[104:107], v[22:25]
	v_mfma_f32_16x16x32_bf16 v[38:41], v[14:17], v[124:127], v[26:29]
	v_mfma_f32_16x16x32_bf16 v[26:29], v[84:87], v[120:123], v[42:45]
	v_mfma_f32_16x16x32_bf16 v[22:25], v[14:17], v[108:111], v[22:25]
	v_mfma_f32_16x16x32_bf16 v[42:45], v[88:91], v[124:127], v[26:29]
	s_barrier
	s_mov_b32 m0, s38
	v_lshl_add_u64 v[140:141], s[12:13], 0, v[0:1]
	s_add_u32 s14, s12, 0x18000
	ds_read_b128 v[26:29], v79 offset:16384
	ds_read_b128 v[30:33], v79 offset:17408
	ds_read_b128 v[104:107], v79 offset:18432
	ds_read_b128 v[108:111], v79 offset:19456
	ds_read_b128 v[112:115], v79 offset:20480
	ds_read_b128 v[116:119], v79 offset:21504
	ds_read_b128 v[120:123], v79 offset:22528
	ds_read_b128 v[124:127], v79 offset:23552
	global_load_lds_dwordx4 v[140:141], off
	v_lshl_add_u64 v[142:143], s[12:13], 0, v[66:67]
	s_mov_b32 m0, s36
	s_addc_u32 s15, s13, 0
	global_load_lds_dwordx4 v[142:143], off
	v_lshl_add_u64 v[128:129], s[14:15], 0, v[0:1]
	s_mov_b32 m0, s22
	v_lshl_add_u64 v[144:145], s[10:11], 0, v[70:71]
	global_load_lds_dwordx4 v[128:129], off
	v_lshl_add_u64 v[128:129], s[14:15], 0, v[66:67]
	s_mov_b32 m0, s23
	v_lshl_add_u64 v[146:147], s[10:11], 0, v[68:69]
	global_load_lds_dwordx4 v[128:129], off
	s_mov_b32 m0, s21
	s_nop 0
	global_load_lds_dwordx4 v[144:145], off
	s_mov_b32 m0, s24
	s_nop 0
	global_load_lds_dwordx4 v[146:147], off
	s_waitcnt vmcnt(8)
	s_waitcnt lgkmcnt(0)
	s_barrier
; #define PG8_STAGE(bufoff, gbase, voff) do { _Pragma("unroll") for (int _i = 0; _i < 2; ++_i) \
;         __builtin_amdgcn_global_load_lds((const unsigned*)((const char*)(gbase) + (voff)[_i]), (PG8_LAS unsigned*)(lds + (bufoff) + ldsw + _i * 8192), 16, 0, 0); } while (0)
; #define PG8_LDA(dst, b, h) do { _Pragma("unroll") for (int m = 0; m < 4; ++m) _Pragma("unroll") for (int k = 0; k < 2; ++k) dst[m][k] = *(const PG8_LAS bf16x8*)(lds + PG8_SA(b, h) + aoff + m * 2048 + k * 1024); } while (0)
; #define PG8_LDB(dst, b, h) do { _Pragma("unroll") for (int n = 0; n < 2; ++n) _Pragma("unroll") for (int k = 0; k < 2; ++k) dst[n][k] = *(const PG8_LAS bf16x8*)(lds + PG8_SB(b, h) + boff + n * 2048 + k * 1024); } while (0)
; #define PG8_MMA(ai, bj, At, Bt) do { __builtin_amdgcn_s_setprio(1); _Pragma("unroll") for (int m = 0; m < 4; ++m) _Pragma("unroll") for (int n = 0; n < 2; ++n) _Pragma("unroll") for (int k = 0; k < 2; ++k) \
;         acc[ai][bj][m][n] = __builtin_amdgcn_mfma_f32_16x16x32_bf16(Bt[n][k], At[m][k], acc[ai][bj][m][n], 0, 0, 0); __builtin_amdgcn_s_setprio(0); } while (0)
; #define PG8_WAIT_V(n) asm volatile("s_waitcnt vmcnt(" #n ")" ::: "memory")
; #define PG8_WAIT_L(n) asm volatile("s_waitcnt lgkmcnt(" #n ")" ::: "memory")
; #define PG8_BAR __builtin_amdgcn_s_barrier()
; #define PG8_SCHED __builtin_amdgcn_sched_barrier(0)
; template <class Epi, class Sched, bool ALIGN_EPI = false, bool SP2 = false>
; __device__ __forceinline__ void gemm_phase(PG8_LAS unsigned char* lds, const Gemm g, const Sched& S, const Epi& E) {
;     ...
;             PG8_WAIT_V(8); PG8_WAIT_L(0); PG8_BAR; PG8_MMA(1, 0, At, B0); PG8_MMA(1, 1, At, B1); PG8_BAR; PG8_SCHED;
;             PG8_LDB(B0, 1, 0); PG8_LDB(B1, 1, 1); PG8_SCHED; PG8_LDA(At, 1, 0); PG8_STAGE(PG8_SA(0, 1), a2 + hstep, voffA);
;             PG8_WAIT_V(8); PG8_WAIT_L(0); PG8_BAR; PG8_MMA(0, 0, At, B0); PG8_MMA(0, 1, At, B1); PG8_BAR; PG8_SCHED;
;             PG8_LDA(At, 1, 1); PG8_STAGE(PG8_SB(1, 0), b3, voffB); PG8_STAGE(PG8_SB(1, 1), b3 + hstep, voffB); PG8_STAGE(PG8_SA(1, 0), a3, voffA);
;             PG8_WAIT_V(8); PG8_WAIT_L(0); PG8_BAR; PG8_MMA(1, 0, At, B0); PG8_MMA(1, 1, At, B1); PG8_BAR; PG8_SCHED;
;     ...
;         if constexpr (ALIGN_EPI) { if (wr == 0) PG8_BAR; }
	v_mfma_f32_16x16x32_bf16 v[96:99], v[10:13], v[26:29], v[96:99]
	v_mfma_f32_16x16x32_bf16 v[26:29], v[84:87], v[26:29], v[46:49]
	v_mfma_f32_16x16x32_bf16 v[46:49], v[88:91], v[30:33], v[26:29]
	v_mfma_f32_16x16x32_bf16 v[26:29], v[10:13], v[104:107], v[54:57]
	v_mfma_f32_16x16x32_bf16 v[54:57], v[14:17], v[108:111], v[26:29]
	v_mfma_f32_16x16x32_bf16 v[26:29], v[84:87], v[104:107], v[58:61]
	v_mfma_f32_16x16x32_bf16 v[104:107], v[88:91], v[108:111], v[26:29]
	v_mfma_f32_16x16x32_bf16 v[26:29], v[10:13], v[112:115], v[62:65]
	v_mfma_f32_16x16x32_bf16 v[2:5], v[10:13], v[120:123], v[2:5]
	v_mfma_f32_16x16x32_bf16 v[108:111], v[14:17], v[116:119], v[26:29]
	v_mfma_f32_16x16x32_bf16 v[26:29], v[84:87], v[112:115], v[80:83]
	v_mfma_f32_16x16x32_bf16 v[112:115], v[14:17], v[124:127], v[2:5]
	v_mfma_f32_16x16x32_bf16 v[2:5], v[84:87], v[120:123], v[6:9]
	v_mfma_f32_16x16x32_bf16 v[96:99], v[14:17], v[30:33], v[96:99]
	v_mfma_f32_16x16x32_bf16 v[80:83], v[88:91], v[116:119], v[26:29]
	v_mfma_f32_16x16x32_bf16 v[84:87], v[88:91], v[124:127], v[2:5]
	s_barrier
	ds_read_b128 v[88:91], v139
	ds_read_b128 v[116:119], v139 offset:1024
	ds_read_b128 v[120:123], v139 offset:2048
	ds_read_b128 v[124:127], v139 offset:3072
	s_add_u32 s14, s10, 0x18000
	s_addc_u32 s15, s11, 0
	s_mov_b32 m0, s25
	v_lshl_add_u64 v[26:27], s[14:15], 0, v[70:71]
	ds_read_b128 v[2:5], v79 offset:32768
	ds_read_b128 v[6:9], v79 offset:33792
	ds_read_b128 v[10:13], v79 offset:34816
	ds_read_b128 v[14:17], v79 offset:35840
	ds_read_b128 v[58:61], v79 offset:36864
	ds_read_b128 v[62:65], v79 offset:37888
	ds_read_b128 v[128:131], v79 offset:38912
	ds_read_b128 v[132:135], v79 offset:39936
	global_load_lds_dwordx4 v[26:27], off
	v_lshl_add_u64 v[26:27], s[14:15], 0, v[68:69]
	s_mov_b32 m0, s26
	s_nop 0
	global_load_lds_dwordx4 v[26:27], off
	s_waitcnt vmcnt(8)
	s_waitcnt lgkmcnt(0)
	s_barrier
	v_mfma_f32_16x16x32_bf16 v[26:29], v[88:91], v[2:5], v[50:53]
	v_mfma_f32_16x16x32_bf16 v[2:5], v[120:123], v[2:5], v[18:21]
	v_mfma_f32_16x16x32_bf16 v[30:33], v[124:127], v[6:9], v[2:5]
	v_mfma_f32_16x16x32_bf16 v[2:5], v[88:91], v[10:13], v[22:25]
	v_mfma_f32_16x16x32_bf16 v[18:21], v[116:119], v[14:17], v[2:5]
	v_mfma_f32_16x16x32_bf16 v[2:5], v[120:123], v[10:13], v[92:95]
	v_mfma_f32_16x16x32_bf16 v[22:25], v[124:127], v[14:17], v[2:5]
	v_mfma_f32_16x16x32_bf16 v[2:5], v[88:91], v[58:61], v[100:103]
	v_mfma_f32_16x16x32_bf16 v[10:13], v[116:119], v[62:65], v[2:5]
	v_mfma_f32_16x16x32_bf16 v[2:5], v[120:123], v[58:61], v[34:37]
	v_mfma_f32_16x16x32_bf16 v[26:29], v[116:119], v[6:9], v[26:29]
	v_mfma_f32_16x16x32_bf16 v[14:17], v[124:127], v[62:65], v[2:5]
	v_mfma_f32_16x16x32_bf16 v[2:5], v[88:91], v[128:131], v[38:41]
	v_mfma_f32_16x16x32_bf16 v[6:9], v[120:123], v[128:131], v[42:45]
	v_mfma_f32_16x16x32_bf16 v[2:5], v[116:119], v[132:135], v[2:5]
	v_mfma_f32_16x16x32_bf16 v[6:9], v[124:127], v[132:135], v[6:9]
	s_barrier
	s_mov_b32 m0, s46
	v_lshl_add_u64 v[50:51], v[140:141], 0, s[94:95]
	s_add_u32 s14, s12, 0x18080
	ds_read_b128 v[34:37], v79 offset:49152
	ds_read_b128 v[38:41], v79 offset:50176
	ds_read_b128 v[42:45], v79 offset:51200
	ds_read_b128 v[92:95], v79 offset:52224
	ds_read_b128 v[100:103], v79 offset:53248
	ds_read_b128 v[128:131], v79 offset:54272
	ds_read_b128 v[132:135], v79 offset:55296
	ds_read_b128 v[136:139], v79 offset:56320
	global_load_lds_dwordx4 v[50:51], off
	v_lshl_add_u64 v[50:51], v[142:143], 0, s[94:95]
	s_mov_b32 m0, s37
	s_addc_u32 s15, s13, 0
	global_load_lds_dwordx4 v[50:51], off
	v_lshl_add_u64 v[50:51], s[14:15], 0, v[0:1]
	s_mov_b32 m0, s29
	s_nop 0
	global_load_lds_dwordx4 v[50:51], off
	v_lshl_add_u64 v[50:51], s[14:15], 0, v[66:67]
	s_mov_b32 m0, s30
	s_nop 0
	global_load_lds_dwordx4 v[50:51], off
	v_lshl_add_u64 v[50:51], v[144:145], 0, s[94:95]
	s_mov_b32 m0, s27
	s_nop 0
	global_load_lds_dwordx4 v[50:51], off
	v_lshl_add_u64 v[50:51], v[146:147], 0, s[94:95]
	s_mov_b32 m0, s28
	s_nop 0
	global_load_lds_dwordx4 v[50:51], off
	s_waitcnt vmcnt(8)
	s_waitcnt lgkmcnt(0)
	s_barrier
	v_mfma_f32_16x16x32_bf16 v[50:53], v[88:91], v[34:37], v[96:99]
	v_mfma_f32_16x16x32_bf16 v[34:37], v[120:123], v[34:37], v[46:49]
	v_mfma_f32_16x16x32_bf16 v[62:65], v[124:127], v[38:41], v[34:37]
	v_mfma_f32_16x16x32_bf16 v[34:37], v[88:91], v[42:45], v[54:57]
	v_mfma_f32_16x16x32_bf16 v[58:61], v[116:119], v[38:41], v[50:53]
	v_mfma_f32_16x16x32_bf16 v[50:53], v[116:119], v[92:95], v[34:37]
	v_mfma_f32_16x16x32_bf16 v[34:37], v[120:123], v[42:45], v[104:107]
	v_mfma_f32_16x16x32_bf16 v[54:57], v[124:127], v[92:95], v[34:37]
	v_mfma_f32_16x16x32_bf16 v[34:37], v[88:91], v[100:103], v[108:111]
	v_mfma_f32_16x16x32_bf16 v[42:45], v[116:119], v[128:131], v[34:37]
	v_mfma_f32_16x16x32_bf16 v[34:37], v[120:123], v[100:103], v[80:83]
	v_mfma_f32_16x16x32_bf16 v[46:49], v[124:127], v[128:131], v[34:37]
	v_mfma_f32_16x16x32_bf16 v[34:37], v[88:91], v[132:135], v[112:115]
	v_mfma_f32_16x16x32_bf16 v[38:41], v[120:123], v[132:135], v[84:87]
	v_mfma_f32_16x16x32_bf16 v[34:37], v[116:119], v[136:139], v[34:37]
	v_mfma_f32_16x16x32_bf16 v[38:41], v[124:127], v[136:139], v[38:41]
	s_barrier
	s_andn2_b64 vcc, exec, s[6:7]
	s_cbranch_vccnz .LBB0_319
	s_barrier

; #define PG8_STAGE(bufoff, gbase, voff) do { _Pragma("unroll") for (int _i = 0; _i < 2; ++_i) \
;         __builtin_amdgcn_global_load_lds((const unsigned*)((const char*)(gbase) + (voff)[_i]), (PG8_LAS unsigned*)(lds + (bufoff) + ldsw + _i * 8192), 16, 0, 0); } while (0)
; #define PG8_LDA(dst, b, h) do { _Pragma("unroll") for (int m = 0; m < 4; ++m) _Pragma("unroll") for (int k = 0; k < 2; ++k) dst[m][k] = *(const PG8_LAS bf16x8*)(lds + PG8_SA(b, h) + aoff + m * 2048 + k * 1024); } while (0)
; #define PG8_LDB(dst, b, h) do { _Pragma("unroll") for (int n = 0; n < 2; ++n) _Pragma("unroll") for (int k = 0; k < 2; ++k) dst[n][k] = *(const PG8_LAS bf16x8*)(lds + PG8_SB(b, h) + boff + n * 2048 + k * 1024); } while (0)
; #define PG8_MMA(ai, bj, At, Bt) do { __builtin_amdgcn_s_setprio(1); _Pragma("unroll") for (int m = 0; m < 4; ++m) _Pragma("unroll") for (int n = 0; n < 2; ++n) _Pragma("unroll") for (int k = 0; k < 2; ++k) \
;         acc[ai][bj][m][n] = __builtin_amdgcn_mfma_f32_16x16x32_bf16(Bt[n][k], At[m][k], acc[ai][bj][m][n], 0, 0, 0); __builtin_amdgcn_s_setprio(0); } while (0)
; #define PG8_WAIT_V(n) asm volatile("s_waitcnt vmcnt(" #n ")" ::: "memory")
; #define PG8_WAIT_L(n) asm volatile("s_waitcnt lgkmcnt(" #n ")" ::: "memory")
; #define PG8_BAR __builtin_amdgcn_s_barrier()
; #define PG8_SCHED __builtin_amdgcn_sched_barrier(0)
; template <class Epi, class Sched, bool ALIGN_EPI = false, bool SP2 = false>
; __device__ __forceinline__ void gemm_phase(PG8_LAS unsigned char* lds, const Gemm g, const Sched& S, const Epi& E) {
;     ...
;             PG8_LDB(B0, 0, 0); PG8_LDB(B1, 0, 1); PG8_SCHED; PG8_LDA(At, 0, 0); PG8_STAGE(PG8_SA(1, 1), a1 + hstep, voffA);
;             PG8_WAIT_V(8); PG8_WAIT_L(0); PG8_BAR; PG8_MMA(0, 0, At, B0); PG8_MMA(0, 1, At, B1); PG8_BAR; PG8_SCHED;
;             PG8_LDA(At, 0, 1); PG8_STAGE(PG8_SB(0, 0), b2, voffB); PG8_STAGE(PG8_SB(0, 1), b2 + hstep, voffB); PG8_STAGE(PG8_SA(0, 0), a2, voffA);
;             PG8_WAIT_V(8); PG8_WAIT_L(0); PG8_BAR; PG8_MMA(1, 0, At, B0); PG8_MMA(1, 1, At, B1); PG8_BAR; PG8_SCHED;
.LBB0_391:
	s_add_i32 s38, 0, 0x10000
	s_add_i32 s36, 0, 0x14000
	v_add_u32_e32 v0, s38, v141
	v_add_u32_e32 v10, s36, v141
	ds_read_b128 v[12:15], v0
	ds_read_b128 v[16:19], v0 offset:1024
	ds_read_b128 v[20:23], v0 offset:2048
	ds_read_b128 v[24:27], v0 offset:3072
	ds_read_b128 v[28:31], v10
	ds_read_b128 v[32:35], v10 offset:1024
	ds_read_b128 v[36:39], v10 offset:2048
	ds_read_b128 v[40:43], v10 offset:3072
	s_add_u32 s16, s18, 0x18080
	s_addc_u32 s17, s19, 0
	s_add_i32 s50, s25, 0xc000
	v_lshl_add_u64 v[68:69], s[16:17], 0, v[136:137]
	s_mov_b32 m0, s50
	ds_read_b128 v[2:5], v142
	ds_read_b128 v[6:9], v142 offset:1024
	ds_read_b128 v[44:47], v142 offset:2048
	ds_read_b128 v[48:51], v142 offset:3072
	ds_read_b128 v[52:55], v142 offset:4096
	ds_read_b128 v[56:59], v142 offset:5120
	ds_read_b128 v[60:63], v142 offset:6144
	ds_read_b128 v[64:67], v142 offset:7168
	global_load_lds_dwordx4 v[68:69], off
	v_lshl_add_u64 v[68:69], s[16:17], 0, v[132:133]
	s_add_i32 s16, s25, 0xe000
	s_mov_b32 m0, s16
	s_nop 0
	global_load_lds_dwordx4 v[68:69], off
	s_waitcnt vmcnt(8)
	s_waitcnt lgkmcnt(0)
	s_barrier
	v_mfma_f32_16x16x32_bf16 v[68:71], v[12:15], v[2:5], 0
	v_mfma_f32_16x16x32_bf16 v[72:75], v[20:23], v[2:5], 0
	v_mfma_f32_16x16x32_bf16 v[76:79], v[12:15], v[44:47], 0
	v_mfma_f32_16x16x32_bf16 v[80:83], v[20:23], v[44:47], 0
	v_mfma_f32_16x16x32_bf16 v[84:87], v[12:15], v[52:55], 0
	v_mfma_f32_16x16x32_bf16 v[88:91], v[20:23], v[52:55], 0
	v_mfma_f32_16x16x32_bf16 v[92:95], v[12:15], v[60:63], 0
	v_mfma_f32_16x16x32_bf16 v[96:99], v[20:23], v[60:63], 0
	v_mfma_f32_16x16x32_bf16 v[68:71], v[16:19], v[6:9], v[68:71]
	v_mfma_f32_16x16x32_bf16 v[72:75], v[24:27], v[6:9], v[72:75]
	v_mfma_f32_16x16x32_bf16 v[76:79], v[16:19], v[48:51], v[76:79]
	v_mfma_f32_16x16x32_bf16 v[80:83], v[24:27], v[48:51], v[80:83]
	v_mfma_f32_16x16x32_bf16 v[84:87], v[16:19], v[56:59], v[84:87]
	v_mfma_f32_16x16x32_bf16 v[88:91], v[24:27], v[56:59], v[88:91]
	v_mfma_f32_16x16x32_bf16 v[92:95], v[16:19], v[64:67], v[92:95]
	v_mfma_f32_16x16x32_bf16 v[96:99], v[24:27], v[64:67], v[96:99]
	v_mfma_f32_16x16x32_bf16 v[100:103], v[28:31], v[2:5], 0
	v_mfma_f32_16x16x32_bf16 v[2:5], v[36:39], v[2:5], 0
	v_mfma_f32_16x16x32_bf16 v[104:107], v[40:43], v[6:9], v[2:5]
	v_mfma_f32_16x16x32_bf16 v[2:5], v[28:31], v[44:47], 0
	v_mfma_f32_16x16x32_bf16 v[108:111], v[32:35], v[48:51], v[2:5]
	v_mfma_f32_16x16x32_bf16 v[2:5], v[36:39], v[44:47], 0
	v_mfma_f32_16x16x32_bf16 v[44:47], v[40:43], v[48:51], v[2:5]
	v_mfma_f32_16x16x32_bf16 v[2:5], v[28:31], v[52:55], 0
	v_mfma_f32_16x16x32_bf16 v[48:51], v[32:35], v[56:59], v[2:5]
	v_mfma_f32_16x16x32_bf16 v[2:5], v[36:39], v[52:55], 0
	v_mfma_f32_16x16x32_bf16 v[52:55], v[40:43], v[56:59], v[2:5]
	v_mfma_f32_16x16x32_bf16 v[2:5], v[28:31], v[60:63], 0
	v_mfma_f32_16x16x32_bf16 v[56:59], v[32:35], v[64:67], v[2:5]
	v_mfma_f32_16x16x32_bf16 v[2:5], v[36:39], v[60:63], 0
	v_mfma_f32_16x16x32_bf16 v[100:103], v[32:35], v[6:9], v[100:103]
	v_mfma_f32_16x16x32_bf16 v[60:63], v[40:43], v[64:67], v[2:5]
	s_barrier
	s_nop 3
	v_lshl_add_u64 v[2:3], s[20:21], 0, v[134:135]
	s_add_i32 s38, s38, s24
	v_lshl_add_u64 v[4:5], v[2:3], 0, s[90:91]
	s_mov_b32 m0, s38
	s_add_i32 s17, s38, 0x2000
	ds_read_b128 v[64:67], v142 offset:16384
	ds_read_b128 v[112:115], v142 offset:17408
	ds_read_b128 v[116:119], v142 offset:18432
	ds_read_b128 v[120:123], v142 offset:19456
	ds_read_b128 v[124:127], v142 offset:20480
	ds_read_b128 v[146:149], v142 offset:21504
	ds_read_b128 v[150:153], v142 offset:22528
	ds_read_b128 v[154:157], v142 offset:23552
	global_load_lds_dwordx4 v[4:5], off
	v_lshl_add_u64 v[4:5], s[20:21], 0, v[130:131]
	s_add_u32 s52, s20, 0x18100
	v_lshl_add_u64 v[6:7], v[4:5], 0, s[90:91]
	s_mov_b32 m0, s17
	s_addc_u32 s53, s21, 0
	s_add_i32 s36, s36, s24
	global_load_lds_dwordx4 v[6:7], off
	v_lshl_add_u64 v[6:7], s[52:53], 0, v[134:135]
	s_mov_b32 m0, s36
	s_add_i32 s37, s36, 0x2000
	global_load_lds_dwordx4 v[6:7], off
	v_lshl_add_u64 v[6:7], s[52:53], 0, v[130:131]
	s_mov_b32 m0, s37
	s_nop 0
	global_load_lds_dwordx4 v[6:7], off
	v_lshl_add_u64 v[6:7], s[18:19], 0, v[136:137]
	v_lshl_add_u64 v[8:9], v[6:7], 0, s[90:91]
	s_mov_b32 m0, s25
	s_nop 0
	global_load_lds_dwordx4 v[8:9], off
	v_lshl_add_u64 v[8:9], s[18:19], 0, v[132:133]
	v_lshl_add_u64 v[128:129], v[8:9], 0, s[90:91]
	s_mov_b32 m0, s26
	s_nop 0
	global_load_lds_dwordx4 v[128:129], off
	s_waitcnt vmcnt(8)
	s_waitcnt lgkmcnt(0)
	s_barrier
	v_mfma_f32_16x16x32_bf16 v[158:161], v[12:15], v[64:67], 0
	v_mfma_f32_16x16x32_bf16 v[166:169], v[12:15], v[116:119], 0
	v_mfma_f32_16x16x32_bf16 v[174:177], v[12:15], v[124:127], 0
	v_mfma_f32_16x16x32_bf16 v[12:15], v[12:15], v[150:153], 0
	v_mfma_f32_16x16x32_bf16 v[158:161], v[16:19], v[112:115], v[158:161]
	v_mfma_f32_16x16x32_bf16 v[162:165], v[20:23], v[64:67], 0
	v_mfma_f32_16x16x32_bf16 v[166:169], v[16:19], v[120:123], v[166:169]
	v_mfma_f32_16x16x32_bf16 v[170:173], v[20:23], v[116:119], 0
	v_mfma_f32_16x16x32_bf16 v[174:177], v[16:19], v[146:149], v[174:177]
	v_mfma_f32_16x16x32_bf16 v[178:181], v[20:23], v[124:127], 0
	v_mfma_f32_16x16x32_bf16 v[14:17], v[16:19], v[154:157], v[12:15]
	v_mfma_f32_16x16x32_bf16 v[18:21], v[20:23], v[150:153], 0
	v_mfma_f32_16x16x32_bf16 v[18:21], v[24:27], v[154:157], v[18:21]
	v_mfma_f32_16x16x32_bf16 v[162:165], v[24:27], v[112:115], v[162:165]
	v_mfma_f32_16x16x32_bf16 v[170:173], v[24:27], v[120:123], v[170:173]
	v_mfma_f32_16x16x32_bf16 v[178:181], v[24:27], v[146:149], v[178:181]
	v_mfma_f32_16x16x32_bf16 v[22:25], v[28:31], v[64:67], 0
	v_mfma_f32_16x16x32_bf16 v[64:67], v[36:39], v[64:67], 0
	v_mfma_f32_16x16x32_bf16 v[22:25], v[32:35], v[112:115], v[22:25]
	v_mfma_f32_16x16x32_bf16 v[64:67], v[40:43], v[112:115], v[64:67]
	v_mfma_f32_16x16x32_bf16 v[112:115], v[28:31], v[116:119], 0
	v_mfma_f32_16x16x32_bf16 v[116:119], v[36:39], v[116:119], 0
	v_mfma_f32_16x16x32_bf16 v[112:115], v[32:35], v[120:123], v[112:115]
	v_mfma_f32_16x16x32_bf16 v[116:119], v[40:43], v[120:123], v[116:119]
	v_mfma_f32_16x16x32_bf16 v[120:123], v[28:31], v[124:127], 0
	v_mfma_f32_16x16x32_bf16 v[26:29], v[28:31], v[150:153], 0
	v_mfma_f32_16x16x32_bf16 v[120:123], v[32:35], v[146:149], v[120:123]
	v_mfma_f32_16x16x32_bf16 v[124:127], v[36:39], v[124:127], 0
	v_mfma_f32_16x16x32_bf16 v[26:29], v[32:35], v[154:157], v[26:29]
	v_mfma_f32_16x16x32_bf16 v[30:33], v[36:39], v[150:153], 0
	v_mfma_f32_16x16x32_bf16 v[124:127], v[40:43], v[146:149], v[124:127]
	v_mfma_f32_16x16x32_bf16 v[30:33], v[40:43], v[154:157], v[30:33]
	s_barrier
; #define PG8_STAGE(bufoff, gbase, voff) do { _Pragma("unroll") for (int _i = 0; _i < 2; ++_i) \
;         __builtin_amdgcn_global_load_lds((const unsigned*)((const char*)(gbase) + (voff)[_i]), (PG8_LAS unsigned*)(lds + (bufoff) + ldsw + _i * 8192), 16, 0, 0); } while (0)
; #define PG8_LDA(dst, b, h) do { _Pragma("unroll") for (int m = 0; m < 4; ++m) _Pragma("unroll") for (int k = 0; k < 2; ++k) dst[m][k] = *(const PG8_LAS bf16x8*)(lds + PG8_SA(b, h) + aoff + m * 2048 + k * 1024); } while (0)
; #define PG8_LDB(dst, b, h) do { _Pragma("unroll") for (int n = 0; n < 2; ++n) _Pragma("unroll") for (int k = 0; k < 2; ++k) dst[n][k] = *(const PG8_LAS bf16x8*)(lds + PG8_SB(b, h) + boff + n * 2048 + k * 1024); } while (0)
; #define PG8_MMA(ai, bj, At, Bt) do { __builtin_amdgcn_s_setprio(1); _Pragma("unroll") for (int m = 0; m < 4; ++m) _Pragma("unroll") for (int n = 0; n < 2; ++n) _Pragma("unroll") for (int k = 0; k < 2; ++k) \
;         acc[ai][bj][m][n] = __builtin_amdgcn_mfma_f32_16x16x32_bf16(Bt[n][k], At[m][k], acc[ai][bj][m][n], 0, 0, 0); __builtin_amdgcn_s_setprio(0); } while (0)
; #define PG8_WAIT_V(n) asm volatile("s_waitcnt vmcnt(" #n ")" ::: "memory")
; #define PG8_WAIT_L(n) asm volatile("s_waitcnt lgkmcnt(" #n ")" ::: "memory")
; #define PG8_BAR __builtin_amdgcn_s_barrier()
; #define PG8_SCHED __builtin_amdgcn_sched_barrier(0)
; template <class Epi, class Sched, bool ALIGN_EPI = false, bool SP2 = false>
; __device__ __forceinline__ void gemm_phase(PG8_LAS unsigned char* lds, const Gemm g, const Sched& S, const Epi& E) {
;     ...
;             PG8_LDB(B0, 1, 0); PG8_LDB(B1, 1, 1); PG8_SCHED; PG8_LDA(At, 1, 0); PG8_STAGE(PG8_SA(0, 1), a2 + hstep, voffA);
;             PG8_WAIT_V(8); PG8_WAIT_L(0); PG8_BAR; PG8_MMA(0, 0, At, B0); PG8_MMA(0, 1, At, B1); PG8_BAR; PG8_SCHED;
;             PG8_LDA(At, 1, 1); PG8_STAGE(PG8_SB(1, 0), b3, voffB); PG8_STAGE(PG8_SB(1, 1), b3 + hstep, voffB); PG8_STAGE(PG8_SA(1, 0), a3, voffA);
;             PG8_WAIT_V(8); PG8_WAIT_L(0); PG8_BAR; PG8_MMA(1, 0, At, B0); PG8_MMA(1, 1, At, B1); PG8_BAR; PG8_SCHED;
	s_add_i32 s56, 0, 0x18000
	s_add_i32 s46, 0, 0x1c000
	v_add_u32_e32 v11, s56, v141
	v_add_u32_e32 v12, s46, v141
	ds_read_b128 v[34:37], v11
	ds_read_b128 v[38:41], v11 offset:1024
	ds_read_b128 v[146:149], v11 offset:2048
	ds_read_b128 v[150:153], v11 offset:3072
	ds_read_b128 v[154:157], v12
	ds_read_b128 v[182:185], v12 offset:1024
	ds_read_b128 v[186:189], v12 offset:2048
	ds_read_b128 v[190:193], v12 offset:3072
	s_add_u32 s52, s18, 0x18100
	s_addc_u32 s53, s19, 0
	s_mov_b32 m0, s27
	v_lshl_add_u64 v[42:43], s[52:53], 0, v[136:137]
	ds_read_b128 v[194:197], v142 offset:32768
	ds_read_b128 v[198:201], v142 offset:33792
	ds_read_b128 v[202:205], v142 offset:34816
	ds_read_b128 v[206:209], v142 offset:35840
	ds_read_b128 v[220:223], v142 offset:36864
	ds_read_b128 v[224:227], v142 offset:37888
	ds_read_b128 v[228:231], v142 offset:38912
	ds_read_b128 v[232:235], v142 offset:39936
	global_load_lds_dwordx4 v[42:43], off
	v_lshl_add_u64 v[42:43], s[52:53], 0, v[132:133]
	s_mov_b32 m0, s28
	s_nop 0
	global_load_lds_dwordx4 v[42:43], off
	s_waitcnt vmcnt(8)
	s_waitcnt lgkmcnt(0)
	s_barrier
	v_mfma_f32_16x16x32_bf16 v[68:71], v[34:37], v[194:197], v[68:71]
	v_mfma_f32_16x16x32_bf16 v[72:75], v[146:149], v[194:197], v[72:75]
	v_mfma_f32_16x16x32_bf16 v[76:79], v[34:37], v[202:205], v[76:79]
	v_mfma_f32_16x16x32_bf16 v[80:83], v[146:149], v[202:205], v[80:83]
	v_mfma_f32_16x16x32_bf16 v[84:87], v[34:37], v[220:223], v[84:87]
	v_mfma_f32_16x16x32_bf16 v[88:91], v[146:149], v[220:223], v[88:91]
	v_mfma_f32_16x16x32_bf16 v[92:95], v[34:37], v[228:231], v[92:95]
	v_mfma_f32_16x16x32_bf16 v[96:99], v[146:149], v[228:231], v[96:99]
	v_mfma_f32_16x16x32_bf16 v[68:71], v[38:41], v[198:201], v[68:71]
	v_mfma_f32_16x16x32_bf16 v[72:75], v[150:153], v[198:201], v[72:75]
	v_mfma_f32_16x16x32_bf16 v[76:79], v[38:41], v[206:209], v[76:79]
	v_mfma_f32_16x16x32_bf16 v[80:83], v[150:153], v[206:209], v[80:83]
	v_mfma_f32_16x16x32_bf16 v[84:87], v[38:41], v[224:227], v[84:87]
	v_mfma_f32_16x16x32_bf16 v[88:91], v[150:153], v[224:227], v[88:91]
	v_mfma_f32_16x16x32_bf16 v[92:95], v[38:41], v[232:235], v[92:95]
	v_mfma_f32_16x16x32_bf16 v[96:99], v[150:153], v[232:235], v[96:99]
	v_mfma_f32_16x16x32_bf16 v[100:103], v[154:157], v[194:197], v[100:103]
	v_mfma_f32_16x16x32_bf16 v[104:107], v[186:189], v[194:197], v[104:107]
	v_mfma_f32_16x16x32_bf16 v[108:111], v[154:157], v[202:205], v[108:111]
	v_mfma_f32_16x16x32_bf16 v[42:45], v[186:189], v[202:205], v[44:47]
	v_mfma_f32_16x16x32_bf16 v[46:49], v[154:157], v[220:223], v[48:51]
	v_mfma_f32_16x16x32_bf16 v[50:53], v[186:189], v[220:223], v[52:55]
	v_mfma_f32_16x16x32_bf16 v[54:57], v[154:157], v[228:231], v[56:59]
	v_mfma_f32_16x16x32_bf16 v[58:61], v[186:189], v[228:231], v[60:63]
	v_mfma_f32_16x16x32_bf16 v[100:103], v[182:185], v[198:201], v[100:103]
	v_mfma_f32_16x16x32_bf16 v[104:107], v[190:193], v[198:201], v[104:107]
	v_mfma_f32_16x16x32_bf16 v[108:111], v[182:185], v[206:209], v[108:111]
	v_mfma_f32_16x16x32_bf16 v[42:45], v[190:193], v[206:209], v[42:45]
	v_mfma_f32_16x16x32_bf16 v[46:49], v[182:185], v[224:227], v[46:49]
	v_mfma_f32_16x16x32_bf16 v[50:53], v[190:193], v[224:227], v[50:53]
	v_mfma_f32_16x16x32_bf16 v[54:57], v[182:185], v[232:235], v[54:57]
	v_mfma_f32_16x16x32_bf16 v[58:61], v[190:193], v[232:235], v[58:61]
	s_barrier
	s_add_i32 s56, s56, s24
	s_add_i32 s39, s56, 0x2000
	v_lshl_add_u64 v[62:63], v[2:3], 0, s[76:77]
	s_mov_b32 m0, s56
	s_add_u32 s52, s20, 0x18180
	ds_read_b128 v[194:197], v142 offset:49152
	ds_read_b128 v[198:201], v142 offset:50176
	ds_read_b128 v[202:205], v142 offset:51200
	ds_read_b128 v[206:209], v142 offset:52224
	ds_read_b128 v[220:223], v142 offset:53248
	ds_read_b128 v[224:227], v142 offset:54272
	ds_read_b128 v[228:231], v142 offset:55296
	ds_read_b128 v[232:235], v142 offset:56320
	global_load_lds_dwordx4 v[62:63], off
	v_lshl_add_u64 v[62:63], v[4:5], 0, s[76:77]
	s_mov_b32 m0, s39
	s_addc_u32 s53, s21, 0
	s_add_i32 s46, s46, s24
	global_load_lds_dwordx4 v[62:63], off
	v_lshl_add_u64 v[62:63], s[52:53], 0, v[134:135]
	s_mov_b32 m0, s46
	s_add_i32 s55, s46, 0x2000
	global_load_lds_dwordx4 v[62:63], off
	v_lshl_add_u64 v[62:63], s[52:53], 0, v[130:131]
	s_mov_b32 m0, s55
	s_nop 0
	global_load_lds_dwordx4 v[62:63], off
	v_lshl_add_u64 v[62:63], v[6:7], 0, s[76:77]
	s_mov_b32 m0, s30
	s_nop 0
	global_load_lds_dwordx4 v[62:63], off
	v_lshl_add_u64 v[62:63], v[8:9], 0, s[76:77]
	s_mov_b32 m0, s31
	s_nop 0
	global_load_lds_dwordx4 v[62:63], off
	s_waitcnt vmcnt(8)
	s_waitcnt lgkmcnt(0)
	s_barrier
; #define PG8_STAGE(bufoff, gbase, voff) do { _Pragma("unroll") for (int _i = 0; _i < 2; ++_i) \
;         __builtin_amdgcn_global_load_lds((const unsigned*)((const char*)(gbase) + (voff)[_i]), (PG8_LAS unsigned*)(lds + (bufoff) + ldsw + _i * 8192), 16, 0, 0); } while (0)
; #define PG8_LDA(dst, b, h) do { _Pragma("unroll") for (int m = 0; m < 4; ++m) _Pragma("unroll") for (int k = 0; k < 2; ++k) dst[m][k] = *(const PG8_LAS bf16x8*)(lds + PG8_SA(b, h) + aoff + m * 2048 + k * 1024); } while (0)
; #define PG8_LDB(dst, b, h) do { _Pragma("unroll") for (int n = 0; n < 2; ++n) _Pragma("unroll") for (int k = 0; k < 2; ++k) dst[n][k] = *(const PG8_LAS bf16x8*)(lds + PG8_SB(b, h) + boff + n * 2048 + k * 1024); } while (0)
; #define PG8_MMA(ai, bj, At, Bt) do { __builtin_amdgcn_s_setprio(1); _Pragma("unroll") for (int m = 0; m < 4; ++m) _Pragma("unroll") for (int n = 0; n < 2; ++n) _Pragma("unroll") for (int k = 0; k < 2; ++k) \
;         acc[ai][bj][m][n] = __builtin_amdgcn_mfma_f32_16x16x32_bf16(Bt[n][k], At[m][k], acc[ai][bj][m][n], 0, 0, 0); __builtin_amdgcn_s_setprio(0); } while (0)
; #define PG8_WAIT_V(n) asm volatile("s_waitcnt vmcnt(" #n ")" ::: "memory")
; #define PG8_WAIT_L(n) asm volatile("s_waitcnt lgkmcnt(" #n ")" ::: "memory")
; #define PG8_BAR __builtin_amdgcn_s_barrier()
; #define PG8_SCHED __builtin_amdgcn_sched_barrier(0)
; template <class Epi, class Sched, bool ALIGN_EPI = false, bool SP2 = false>
; __device__ __forceinline__ void gemm_phase(PG8_LAS unsigned char* lds, const Gemm g, const Sched& S, const Epi& E) {
;     ...
;             PG8_LDB(B0, 0, 0); PG8_LDB(B1, 0, 1); PG8_SCHED; PG8_LDA(At, 0, 0); PG8_STAGE(PG8_SA(1, 1), a1 + hstep, voffA);
;             PG8_WAIT_V(8); PG8_WAIT_L(0); PG8_BAR; PG8_MMA(0, 0, At, B0); PG8_MMA(0, 1, At, B1); PG8_BAR; PG8_SCHED;
;     ...
;             PG8_WAIT_V(8); PG8_WAIT_L(0); PG8_BAR; PG8_MMA(1, 0, At, B0); PG8_MMA(1, 1, At, B1); PG8_BAR; PG8_SCHED;
	v_mfma_f32_16x16x32_bf16 v[14:17], v[34:37], v[228:231], v[14:17]
	v_mfma_f32_16x16x32_bf16 v[18:21], v[146:149], v[228:231], v[18:21]
	v_mfma_f32_16x16x32_bf16 v[158:161], v[34:37], v[194:197], v[158:161]
	v_mfma_f32_16x16x32_bf16 v[162:165], v[146:149], v[194:197], v[162:165]
	v_mfma_f32_16x16x32_bf16 v[166:169], v[34:37], v[202:205], v[166:169]
	v_mfma_f32_16x16x32_bf16 v[170:173], v[146:149], v[202:205], v[170:173]
	v_mfma_f32_16x16x32_bf16 v[174:177], v[34:37], v[220:223], v[174:177]
	v_mfma_f32_16x16x32_bf16 v[178:181], v[146:149], v[220:223], v[178:181]
	v_mfma_f32_16x16x32_bf16 v[14:17], v[38:41], v[232:235], v[14:17]
	v_mfma_f32_16x16x32_bf16 v[18:21], v[150:153], v[232:235], v[18:21]
	v_mfma_f32_16x16x32_bf16 v[158:161], v[38:41], v[198:201], v[158:161]
	v_mfma_f32_16x16x32_bf16 v[162:165], v[150:153], v[198:201], v[162:165]
	v_mfma_f32_16x16x32_bf16 v[166:169], v[38:41], v[206:209], v[166:169]
	v_mfma_f32_16x16x32_bf16 v[170:173], v[150:153], v[206:209], v[170:173]
	v_mfma_f32_16x16x32_bf16 v[174:177], v[38:41], v[224:227], v[174:177]
	v_mfma_f32_16x16x32_bf16 v[178:181], v[150:153], v[224:227], v[178:181]
	v_mfma_f32_16x16x32_bf16 v[22:25], v[154:157], v[194:197], v[22:25]
	v_mfma_f32_16x16x32_bf16 v[34:37], v[186:189], v[194:197], v[64:67]
	v_mfma_f32_16x16x32_bf16 v[38:41], v[154:157], v[202:205], v[112:115]
	v_mfma_f32_16x16x32_bf16 v[62:65], v[186:189], v[202:205], v[116:119]
	v_mfma_f32_16x16x32_bf16 v[112:115], v[154:157], v[220:223], v[120:123]
	v_mfma_f32_16x16x32_bf16 v[116:119], v[186:189], v[220:223], v[124:127]
	v_mfma_f32_16x16x32_bf16 v[26:29], v[154:157], v[228:231], v[26:29]
	v_mfma_f32_16x16x32_bf16 v[30:33], v[186:189], v[228:231], v[30:33]
	v_mfma_f32_16x16x32_bf16 v[22:25], v[182:185], v[198:201], v[22:25]
	v_mfma_f32_16x16x32_bf16 v[34:37], v[190:193], v[198:201], v[34:37]
	v_mfma_f32_16x16x32_bf16 v[38:41], v[182:185], v[206:209], v[38:41]
	v_mfma_f32_16x16x32_bf16 v[62:65], v[190:193], v[206:209], v[62:65]
	v_mfma_f32_16x16x32_bf16 v[112:115], v[182:185], v[224:227], v[112:115]
	v_mfma_f32_16x16x32_bf16 v[116:119], v[190:193], v[224:227], v[116:119]
	v_mfma_f32_16x16x32_bf16 v[26:29], v[182:185], v[232:235], v[26:29]
	v_mfma_f32_16x16x32_bf16 v[30:33], v[190:193], v[232:235], v[30:33]
	s_barrier
	ds_read_b128 v[120:123], v0
	ds_read_b128 v[124:127], v0 offset:1024
	ds_read_b128 v[146:149], v0 offset:2048
	ds_read_b128 v[150:153], v0 offset:3072
	ds_read_b128 v[154:157], v10
	ds_read_b128 v[182:185], v10 offset:1024
	ds_read_b128 v[186:189], v10 offset:2048
	ds_read_b128 v[190:193], v10 offset:3072
	s_add_u32 s52, s18, 0x18180
	s_addc_u32 s53, s19, 0
	s_mov_b32 m0, s50
	v_lshl_add_u64 v[66:67], s[52:53], 0, v[136:137]
	ds_read_b128 v[194:197], v142
	ds_read_b128 v[198:201], v142 offset:1024
	ds_read_b128 v[202:205], v142 offset:2048
	ds_read_b128 v[206:209], v142 offset:3072
	ds_read_b128 v[220:223], v142 offset:4096
	ds_read_b128 v[224:227], v142 offset:5120
	ds_read_b128 v[228:231], v142 offset:6144
	ds_read_b128 v[232:235], v142 offset:7168
	global_load_lds_dwordx4 v[66:67], off
	v_lshl_add_u64 v[66:67], s[52:53], 0, v[132:133]
	s_mov_b32 m0, s16
	s_nop 0
	global_load_lds_dwordx4 v[66:67], off
	s_waitcnt vmcnt(8)
	s_waitcnt lgkmcnt(0)
	s_barrier
	v_mfma_f32_16x16x32_bf16 v[66:69], v[120:123], v[194:197], v[68:71]
	v_mfma_f32_16x16x32_bf16 v[70:73], v[146:149], v[194:197], v[72:75]
	v_mfma_f32_16x16x32_bf16 v[74:77], v[120:123], v[202:205], v[76:79]
	v_mfma_f32_16x16x32_bf16 v[78:81], v[146:149], v[202:205], v[80:83]
	v_mfma_f32_16x16x32_bf16 v[82:85], v[120:123], v[220:223], v[84:87]
	v_mfma_f32_16x16x32_bf16 v[86:89], v[146:149], v[220:223], v[88:91]
	v_mfma_f32_16x16x32_bf16 v[90:93], v[120:123], v[228:231], v[92:95]
	v_mfma_f32_16x16x32_bf16 v[94:97], v[146:149], v[228:231], v[96:99]
	v_mfma_f32_16x16x32_bf16 v[66:69], v[124:127], v[198:201], v[66:69]
	v_mfma_f32_16x16x32_bf16 v[70:73], v[150:153], v[198:201], v[70:73]
	v_mfma_f32_16x16x32_bf16 v[74:77], v[124:127], v[206:209], v[74:77]
	v_mfma_f32_16x16x32_bf16 v[78:81], v[150:153], v[206:209], v[78:81]
	v_mfma_f32_16x16x32_bf16 v[82:85], v[124:127], v[224:227], v[82:85]
	v_mfma_f32_16x16x32_bf16 v[86:89], v[150:153], v[224:227], v[86:89]
	v_mfma_f32_16x16x32_bf16 v[90:93], v[124:127], v[232:235], v[90:93]
	v_mfma_f32_16x16x32_bf16 v[94:97], v[150:153], v[232:235], v[94:97]
	v_mfma_f32_16x16x32_bf16 v[98:101], v[154:157], v[194:197], v[100:103]
	v_mfma_f32_16x16x32_bf16 v[102:105], v[186:189], v[194:197], v[104:107]
	v_mfma_f32_16x16x32_bf16 v[106:109], v[154:157], v[202:205], v[108:111]
	v_mfma_f32_16x16x32_bf16 v[42:45], v[186:189], v[202:205], v[42:45]
	v_mfma_f32_16x16x32_bf16 v[46:49], v[154:157], v[220:223], v[46:49]
	v_mfma_f32_16x16x32_bf16 v[50:53], v[186:189], v[220:223], v[50:53]
	v_mfma_f32_16x16x32_bf16 v[54:57], v[154:157], v[228:231], v[54:57]
	v_mfma_f32_16x16x32_bf16 v[58:61], v[186:189], v[228:231], v[58:61]
	v_mfma_f32_16x16x32_bf16 v[98:101], v[182:185], v[198:201], v[98:101]
	v_mfma_f32_16x16x32_bf16 v[102:105], v[190:193], v[198:201], v[102:105]
	v_mfma_f32_16x16x32_bf16 v[106:109], v[182:185], v[206:209], v[106:109]
	v_mfma_f32_16x16x32_bf16 v[42:45], v[190:193], v[206:209], v[42:45]
	v_mfma_f32_16x16x32_bf16 v[46:49], v[182:185], v[224:227], v[46:49]
	v_mfma_f32_16x16x32_bf16 v[50:53], v[190:193], v[224:227], v[50:53]
	v_mfma_f32_16x16x32_bf16 v[54:57], v[182:185], v[232:235], v[54:57]
	v_mfma_f32_16x16x32_bf16 v[58:61], v[190:193], v[232:235], v[58:61]
	s_barrier
; #define PG8_STAGE(bufoff, gbase, voff) do { _Pragma("unroll") for (int _i = 0; _i < 2; ++_i) \
;         __builtin_amdgcn_global_load_lds((const unsigned*)((const char*)(gbase) + (voff)[_i]), (PG8_LAS unsigned*)(lds + (bufoff) + ldsw + _i * 8192), 16, 0, 0); } while (0)
; #define PG8_LDA(dst, b, h) do { _Pragma("unroll") for (int m = 0; m < 4; ++m) _Pragma("unroll") for (int k = 0; k < 2; ++k) dst[m][k] = *(const PG8_LAS bf16x8*)(lds + PG8_SA(b, h) + aoff + m * 2048 + k * 1024); } while (0)
; #define PG8_LDB(dst, b, h) do { _Pragma("unroll") for (int n = 0; n < 2; ++n) _Pragma("unroll") for (int k = 0; k < 2; ++k) dst[n][k] = *(const PG8_LAS bf16x8*)(lds + PG8_SB(b, h) + boff + n * 2048 + k * 1024); } while (0)
; #define PG8_MMA(ai, bj, At, Bt) do { __builtin_amdgcn_s_setprio(1); _Pragma("unroll") for (int m = 0; m < 4; ++m) _Pragma("unroll") for (int n = 0; n < 2; ++n) _Pragma("unroll") for (int k = 0; k < 2; ++k) \
;         acc[ai][bj][m][n] = __builtin_amdgcn_mfma_f32_16x16x32_bf16(Bt[n][k], At[m][k], acc[ai][bj][m][n], 0, 0, 0); __builtin_amdgcn_s_setprio(0); } while (0)
; #define PG8_WAIT_V(n) asm volatile("s_waitcnt vmcnt(" #n ")" ::: "memory")
; #define PG8_WAIT_L(n) asm volatile("s_waitcnt lgkmcnt(" #n ")" ::: "memory")
; #define PG8_BAR __builtin_amdgcn_s_barrier()
; #define PG8_SCHED __builtin_amdgcn_sched_barrier(0)
; template <class Epi, class Sched, bool ALIGN_EPI = false, bool SP2 = false>
; __device__ __forceinline__ void gemm_phase(PG8_LAS unsigned char* lds, const Gemm g, const Sched& S, const Epi& E) {
;     ...
;             PG8_LDA(At, 0, 1); PG8_STAGE(PG8_SB(0, 0), b2, voffB); PG8_STAGE(PG8_SB(0, 1), b2 + hstep, voffB); PG8_STAGE(PG8_SA(0, 0), a2, voffA);
;             PG8_WAIT_V(8); PG8_WAIT_L(0); PG8_BAR; PG8_MMA(1, 0, At, B0); PG8_MMA(1, 1, At, B1); PG8_BAR; PG8_SCHED;
;             PG8_LDB(B0, 1, 0); PG8_LDB(B1, 1, 1); PG8_SCHED; PG8_LDA(At, 1, 0); PG8_STAGE(PG8_SA(0, 1), a2 + hstep, voffA);
;             PG8_WAIT_V(8); PG8_WAIT_L(0); PG8_BAR; PG8_MMA(0, 0, At, B0); PG8_MMA(0, 1, At, B1); PG8_BAR; PG8_SCHED;
	s_mov_b32 m0, s38
	v_lshl_add_u64 v[110:111], v[2:3], 0, s[88:89]
	s_add_u32 s52, s20, 0x18200
	ds_read_b128 v[194:197], v142 offset:16384
	ds_read_b128 v[198:201], v142 offset:17408
	ds_read_b128 v[202:205], v142 offset:18432
	ds_read_b128 v[206:209], v142 offset:19456
	ds_read_b128 v[220:223], v142 offset:20480
	ds_read_b128 v[224:227], v142 offset:21504
	ds_read_b128 v[228:231], v142 offset:22528
	ds_read_b128 v[232:235], v142 offset:23552
	global_load_lds_dwordx4 v[110:111], off
	v_lshl_add_u64 v[110:111], v[4:5], 0, s[88:89]
	s_mov_b32 m0, s17
	s_addc_u32 s53, s21, 0
	global_load_lds_dwordx4 v[110:111], off
	v_lshl_add_u64 v[110:111], s[52:53], 0, v[134:135]
	s_mov_b32 m0, s36
	s_nop 0
	global_load_lds_dwordx4 v[110:111], off
	v_lshl_add_u64 v[110:111], s[52:53], 0, v[130:131]
	s_mov_b32 m0, s37
	s_nop 0
	global_load_lds_dwordx4 v[110:111], off
	v_lshl_add_u64 v[110:111], v[6:7], 0, s[88:89]
	s_mov_b32 m0, s25
	s_nop 0
	global_load_lds_dwordx4 v[110:111], off
	v_lshl_add_u64 v[110:111], v[8:9], 0, s[88:89]
	s_mov_b32 m0, s26
	s_nop 0
	global_load_lds_dwordx4 v[110:111], off
	s_waitcnt vmcnt(8)
	s_waitcnt lgkmcnt(0)
	s_barrier
	v_mfma_f32_16x16x32_bf16 v[14:17], v[120:123], v[228:231], v[14:17]
	v_mfma_f32_16x16x32_bf16 v[18:21], v[146:149], v[228:231], v[18:21]
	v_mfma_f32_16x16x32_bf16 v[158:161], v[120:123], v[194:197], v[158:161]
	v_mfma_f32_16x16x32_bf16 v[162:165], v[146:149], v[194:197], v[162:165]
	v_mfma_f32_16x16x32_bf16 v[166:169], v[120:123], v[202:205], v[166:169]
	v_mfma_f32_16x16x32_bf16 v[170:173], v[146:149], v[202:205], v[170:173]
	v_mfma_f32_16x16x32_bf16 v[174:177], v[120:123], v[220:223], v[174:177]
	v_mfma_f32_16x16x32_bf16 v[178:181], v[146:149], v[220:223], v[178:181]
	v_mfma_f32_16x16x32_bf16 v[14:17], v[124:127], v[232:235], v[14:17]
	v_mfma_f32_16x16x32_bf16 v[18:21], v[150:153], v[232:235], v[18:21]
	v_mfma_f32_16x16x32_bf16 v[158:161], v[124:127], v[198:201], v[158:161]
	v_mfma_f32_16x16x32_bf16 v[162:165], v[150:153], v[198:201], v[162:165]
	v_mfma_f32_16x16x32_bf16 v[166:169], v[124:127], v[206:209], v[166:169]
	v_mfma_f32_16x16x32_bf16 v[170:173], v[150:153], v[206:209], v[170:173]
	v_mfma_f32_16x16x32_bf16 v[174:177], v[124:127], v[224:227], v[174:177]
	v_mfma_f32_16x16x32_bf16 v[178:181], v[150:153], v[224:227], v[178:181]
	v_mfma_f32_16x16x32_bf16 v[22:25], v[154:157], v[194:197], v[22:25]
	v_mfma_f32_16x16x32_bf16 v[34:37], v[186:189], v[194:197], v[34:37]
	v_mfma_f32_16x16x32_bf16 v[38:41], v[154:157], v[202:205], v[38:41]
	v_mfma_f32_16x16x32_bf16 v[62:65], v[186:189], v[202:205], v[62:65]
	v_mfma_f32_16x16x32_bf16 v[110:113], v[154:157], v[220:223], v[112:115]
	v_mfma_f32_16x16x32_bf16 v[114:117], v[186:189], v[220:223], v[116:119]
	v_mfma_f32_16x16x32_bf16 v[26:29], v[154:157], v[228:231], v[26:29]
	v_mfma_f32_16x16x32_bf16 v[30:33], v[186:189], v[228:231], v[30:33]
	v_mfma_f32_16x16x32_bf16 v[22:25], v[182:185], v[198:201], v[22:25]
	v_mfma_f32_16x16x32_bf16 v[34:37], v[190:193], v[198:201], v[34:37]
	v_mfma_f32_16x16x32_bf16 v[38:41], v[182:185], v[206:209], v[38:41]
	v_mfma_f32_16x16x32_bf16 v[62:65], v[190:193], v[206:209], v[62:65]
	v_mfma_f32_16x16x32_bf16 v[110:113], v[182:185], v[224:227], v[110:113]
	v_mfma_f32_16x16x32_bf16 v[114:117], v[190:193], v[224:227], v[114:117]
	v_mfma_f32_16x16x32_bf16 v[26:29], v[182:185], v[232:235], v[26:29]
	v_mfma_f32_16x16x32_bf16 v[30:33], v[190:193], v[232:235], v[30:33]
	s_barrier
	ds_read_b128 v[118:121], v11
	ds_read_b128 v[122:125], v11 offset:1024
	ds_read_b128 v[126:129], v11 offset:2048
	ds_read_b128 v[146:149], v11 offset:3072
	ds_read_b128 v[150:153], v12
	ds_read_b128 v[154:157], v12 offset:1024
	ds_read_b128 v[182:185], v12 offset:2048
	ds_read_b128 v[186:189], v12 offset:3072
	s_add_u32 s52, s18, 0x18200
	s_addc_u32 s53, s19, 0
	s_mov_b32 m0, s27
	v_lshl_add_u64 v[210:211], s[52:53], 0, v[136:137]
	ds_read_b128 v[190:193], v142 offset:32768
	ds_read_b128 v[194:197], v142 offset:33792
	ds_read_b128 v[198:201], v142 offset:34816
	ds_read_b128 v[202:205], v142 offset:35840
	ds_read_b128 v[206:209], v142 offset:36864
	ds_read_b128 v[220:223], v142 offset:37888
	ds_read_b128 v[224:227], v142 offset:38912
	ds_read_b128 v[228:231], v142 offset:39936
	global_load_lds_dwordx4 v[210:211], off
	v_lshl_add_u64 v[210:211], s[52:53], 0, v[132:133]
	s_mov_b32 m0, s28
	s_nop 0
	global_load_lds_dwordx4 v[210:211], off
	s_waitcnt vmcnt(8)
	s_waitcnt lgkmcnt(0)
	s_barrier
	v_mfma_f32_16x16x32_bf16 v[66:69], v[118:121], v[190:193], v[66:69]
	v_mfma_f32_16x16x32_bf16 v[70:73], v[126:129], v[190:193], v[70:73]
	v_mfma_f32_16x16x32_bf16 v[74:77], v[118:121], v[198:201], v[74:77]
	v_mfma_f32_16x16x32_bf16 v[78:81], v[126:129], v[198:201], v[78:81]
	v_mfma_f32_16x16x32_bf16 v[82:85], v[118:121], v[206:209], v[82:85]
	v_mfma_f32_16x16x32_bf16 v[86:89], v[126:129], v[206:209], v[86:89]
	v_mfma_f32_16x16x32_bf16 v[90:93], v[118:121], v[224:227], v[90:93]
	v_mfma_f32_16x16x32_bf16 v[94:97], v[126:129], v[224:227], v[94:97]
	v_mfma_f32_16x16x32_bf16 v[66:69], v[122:125], v[194:197], v[66:69]
	v_mfma_f32_16x16x32_bf16 v[70:73], v[146:149], v[194:197], v[70:73]
	v_mfma_f32_16x16x32_bf16 v[74:77], v[122:125], v[202:205], v[74:77]
	v_mfma_f32_16x16x32_bf16 v[78:81], v[146:149], v[202:205], v[78:81]
	v_mfma_f32_16x16x32_bf16 v[82:85], v[122:125], v[220:223], v[82:85]
	v_mfma_f32_16x16x32_bf16 v[86:89], v[146:149], v[220:223], v[86:89]
	v_mfma_f32_16x16x32_bf16 v[90:93], v[122:125], v[228:231], v[90:93]
	v_mfma_f32_16x16x32_bf16 v[94:97], v[146:149], v[228:231], v[94:97]
	v_mfma_f32_16x16x32_bf16 v[98:101], v[150:153], v[190:193], v[98:101]
	v_mfma_f32_16x16x32_bf16 v[102:105], v[182:185], v[190:193], v[102:105]
	v_mfma_f32_16x16x32_bf16 v[106:109], v[150:153], v[198:201], v[106:109]
	v_mfma_f32_16x16x32_bf16 v[42:45], v[182:185], v[198:201], v[42:45]
	v_mfma_f32_16x16x32_bf16 v[46:49], v[150:153], v[206:209], v[46:49]
	v_mfma_f32_16x16x32_bf16 v[50:53], v[182:185], v[206:209], v[50:53]
	v_mfma_f32_16x16x32_bf16 v[54:57], v[150:153], v[224:227], v[54:57]
	v_mfma_f32_16x16x32_bf16 v[58:61], v[182:185], v[224:227], v[58:61]
	v_mfma_f32_16x16x32_bf16 v[98:101], v[154:157], v[194:197], v[98:101]
	v_mfma_f32_16x16x32_bf16 v[102:105], v[186:189], v[194:197], v[102:105]
	v_mfma_f32_16x16x32_bf16 v[106:109], v[154:157], v[202:205], v[106:109]
	v_mfma_f32_16x16x32_bf16 v[42:45], v[186:189], v[202:205], v[42:45]
	v_mfma_f32_16x16x32_bf16 v[46:49], v[154:157], v[220:223], v[46:49]
	v_mfma_f32_16x16x32_bf16 v[50:53], v[186:189], v[220:223], v[50:53]
	v_mfma_f32_16x16x32_bf16 v[54:57], v[154:157], v[228:231], v[54:57]
	v_mfma_f32_16x16x32_bf16 v[58:61], v[186:189], v[228:231], v[58:61]
	s_barrier
; #define PG8_STAGE(bufoff, gbase, voff) do { _Pragma("unroll") for (int _i = 0; _i < 2; ++_i) \
;         __builtin_amdgcn_global_load_lds((const unsigned*)((const char*)(gbase) + (voff)[_i]), (PG8_LAS unsigned*)(lds + (bufoff) + ldsw + _i * 8192), 16, 0, 0); } while (0)
; #define PG8_LDA(dst, b, h) do { _Pragma("unroll") for (int m = 0; m < 4; ++m) _Pragma("unroll") for (int k = 0; k < 2; ++k) dst[m][k] = *(const PG8_LAS bf16x8*)(lds + PG8_SA(b, h) + aoff + m * 2048 + k * 1024); } while (0)
; #define PG8_LDB(dst, b, h) do { _Pragma("unroll") for (int n = 0; n < 2; ++n) _Pragma("unroll") for (int k = 0; k < 2; ++k) dst[n][k] = *(const PG8_LAS bf16x8*)(lds + PG8_SB(b, h) + boff + n * 2048 + k * 1024); } while (0)
; #define PG8_MMA(ai, bj, At, Bt) do { __builtin_amdgcn_s_setprio(1); _Pragma("unroll") for (int m = 0; m < 4; ++m) _Pragma("unroll") for (int n = 0; n < 2; ++n) _Pragma("unroll") for (int k = 0; k < 2; ++k) \
;         acc[ai][bj][m][n] = __builtin_amdgcn_mfma_f32_16x16x32_bf16(Bt[n][k], At[m][k], acc[ai][bj][m][n], 0, 0, 0); __builtin_amdgcn_s_setprio(0); } while (0)
; #define PG8_WAIT_V(n) asm volatile("s_waitcnt vmcnt(" #n ")" ::: "memory")
; template <class Epi, class Sched, bool ALIGN_EPI = false, bool SP2 = false>
; __device__ __forceinline__ void gemm_phase(PG8_LAS unsigned char* lds, const Gemm g, const Sched& S, const Epi& E) {
;     ...
;             PG8_LDB(B0, 0, 0); PG8_LDB(B1, 0, 1); PG8_SCHED; PG8_LDA(At, 0, 0); PG8_STAGE(PG8_SA(1, 1), a1 + hstep, voffA);
;             PG8_WAIT_V(8); PG8_WAIT_L(0); PG8_BAR; PG8_MMA(0, 0, At, B0); PG8_MMA(0, 1, At, B1); PG8_BAR; PG8_SCHED;
;             PG8_LDA(At, 0, 1); PG8_STAGE(PG8_SB(0, 0), b2, voffB); PG8_STAGE(PG8_SB(0, 1), b2 + hstep, voffB); PG8_STAGE(PG8_SA(0, 0), a2, voffA);
;             PG8_WAIT_V(8); PG8_WAIT_L(0); PG8_BAR; PG8_MMA(1, 0, At, B0); PG8_MMA(1, 1, At, B1); PG8_BAR; PG8_SCHED;
;             PG8_LDB(B0, 1, 0); PG8_LDB(B1, 1, 1); PG8_SCHED; PG8_LDA(At, 1, 0); PG8_STAGE(PG8_SA(0, 1), a2 + hstep, voffA);
;             PG8_WAIT_V(8); PG8_WAIT_L(0); PG8_BAR; PG8_MMA(0, 0, At, B0); PG8_MMA(0, 1, At, B1); PG8_BAR; PG8_SCHED;
;             PG8_LDA(At, 1, 1); PG8_STAGE(PG8_SB(1, 0), b3, voffB); PG8_STAGE(PG8_SB(1, 1), b3 + hstep, voffB); PG8_STAGE(PG8_SA(1, 0), a3, voffA);
;             PG8_WAIT_V(8); PG8_WAIT_L(0); PG8_BAR; PG8_MMA(1, 0, At, B0); PG8_MMA(1, 1, At, B1); PG8_BAR; PG8_SCHED;
	s_mov_b32 m0, s56
	v_lshl_add_u64 v[2:3], v[2:3], 0, s[78:79]
	s_add_u32 s20, s20, 0x18280
	ds_read_b128 v[190:193], v142 offset:49152
	ds_read_b128 v[194:197], v142 offset:50176
	ds_read_b128 v[198:201], v142 offset:51200
	ds_read_b128 v[202:205], v142 offset:52224
	ds_read_b128 v[206:209], v142 offset:53248
	ds_read_b128 v[220:223], v142 offset:54272
	ds_read_b128 v[224:227], v142 offset:55296
	ds_read_b128 v[228:231], v142 offset:56320
	global_load_lds_dwordx4 v[2:3], off
	v_lshl_add_u64 v[2:3], v[4:5], 0, s[78:79]
	s_mov_b32 m0, s39
	s_addc_u32 s21, s21, 0
	global_load_lds_dwordx4 v[2:3], off
	v_lshl_add_u64 v[2:3], s[20:21], 0, v[134:135]
	s_mov_b32 m0, s46
	s_nop 0
	global_load_lds_dwordx4 v[2:3], off
	v_lshl_add_u64 v[2:3], s[20:21], 0, v[130:131]
	s_mov_b32 m0, s55
	s_nop 0
	global_load_lds_dwordx4 v[2:3], off
	v_lshl_add_u64 v[2:3], v[6:7], 0, s[78:79]
	s_mov_b32 m0, s30
	s_nop 0
	global_load_lds_dwordx4 v[2:3], off
	v_lshl_add_u64 v[2:3], v[8:9], 0, s[78:79]
	s_mov_b32 m0, s31
	s_nop 0
	global_load_lds_dwordx4 v[2:3], off
	s_waitcnt vmcnt(8)
	s_waitcnt lgkmcnt(0)
	s_barrier
	v_mfma_f32_16x16x32_bf16 v[2:5], v[118:121], v[190:193], v[158:161]
	v_mfma_f32_16x16x32_bf16 v[6:9], v[126:129], v[190:193], v[162:165]
	v_mfma_f32_16x16x32_bf16 v[14:17], v[118:121], v[224:227], v[14:17]
	v_mfma_f32_16x16x32_bf16 v[18:21], v[126:129], v[224:227], v[18:21]
	v_mfma_f32_16x16x32_bf16 v[2:5], v[122:125], v[194:197], v[2:5]
	v_mfma_f32_16x16x32_bf16 v[6:9], v[146:149], v[194:197], v[6:9]
	v_mfma_f32_16x16x32_bf16 v[158:161], v[118:121], v[198:201], v[166:169]
	v_mfma_f32_16x16x32_bf16 v[162:165], v[126:129], v[198:201], v[170:173]
	v_mfma_f32_16x16x32_bf16 v[166:169], v[118:121], v[206:209], v[174:177]
	v_mfma_f32_16x16x32_bf16 v[170:173], v[126:129], v[206:209], v[178:181]
	v_mfma_f32_16x16x32_bf16 v[14:17], v[122:125], v[228:231], v[14:17]
	v_mfma_f32_16x16x32_bf16 v[18:21], v[146:149], v[228:231], v[18:21]
	v_mfma_f32_16x16x32_bf16 v[158:161], v[122:125], v[202:205], v[158:161]
	v_mfma_f32_16x16x32_bf16 v[162:165], v[146:149], v[202:205], v[162:165]
	v_mfma_f32_16x16x32_bf16 v[166:169], v[122:125], v[220:223], v[166:169]
	v_mfma_f32_16x16x32_bf16 v[170:173], v[146:149], v[220:223], v[170:173]
	v_mfma_f32_16x16x32_bf16 v[22:25], v[150:153], v[190:193], v[22:25]
	v_mfma_f32_16x16x32_bf16 v[34:37], v[182:185], v[190:193], v[34:37]
	v_mfma_f32_16x16x32_bf16 v[38:41], v[150:153], v[198:201], v[38:41]
	v_mfma_f32_16x16x32_bf16 v[62:65], v[182:185], v[198:201], v[62:65]
	v_mfma_f32_16x16x32_bf16 v[110:113], v[150:153], v[206:209], v[110:113]
	v_mfma_f32_16x16x32_bf16 v[114:117], v[182:185], v[206:209], v[114:117]
	v_mfma_f32_16x16x32_bf16 v[26:29], v[150:153], v[224:227], v[26:29]
	v_mfma_f32_16x16x32_bf16 v[30:33], v[182:185], v[224:227], v[30:33]
	v_mfma_f32_16x16x32_bf16 v[22:25], v[154:157], v[194:197], v[22:25]
	v_mfma_f32_16x16x32_bf16 v[34:37], v[186:189], v[194:197], v[34:37]
	v_mfma_f32_16x16x32_bf16 v[38:41], v[154:157], v[202:205], v[38:41]
	v_mfma_f32_16x16x32_bf16 v[62:65], v[186:189], v[202:205], v[62:65]
	v_mfma_f32_16x16x32_bf16 v[110:113], v[154:157], v[220:223], v[110:113]
	v_mfma_f32_16x16x32_bf16 v[114:117], v[186:189], v[220:223], v[114:117]
	v_mfma_f32_16x16x32_bf16 v[26:29], v[154:157], v[228:231], v[26:29]
	v_mfma_f32_16x16x32_bf16 v[30:33], v[186:189], v[228:231], v[30:33]
	s_barrier
	ds_read_b128 v[118:121], v0
	ds_read_b128 v[122:125], v0 offset:1024
	ds_read_b128 v[126:129], v0 offset:2048
	ds_read_b128 v[146:149], v0 offset:3072
	ds_read_b128 v[150:153], v10
	ds_read_b128 v[154:157], v10 offset:1024
	ds_read_b128 v[174:177], v10 offset:2048
	ds_read_b128 v[178:181], v10 offset:3072
	s_add_u32 s18, s18, 0x18280
	s_addc_u32 s19, s19, 0
	s_mov_b32 m0, s50
	v_lshl_add_u64 v[210:211], s[18:19], 0, v[136:137]
	ds_read_b128 v[182:185], v142
	ds_read_b128 v[186:189], v142 offset:1024
	ds_read_b128 v[190:193], v142 offset:2048
	ds_read_b128 v[194:197], v142 offset:3072
	ds_read_b128 v[198:201], v142 offset:4096
	ds_read_b128 v[202:205], v142 offset:5120
	ds_read_b128 v[206:209], v142 offset:6144
	ds_read_b128 v[220:223], v142 offset:7168
	global_load_lds_dwordx4 v[210:211], off
	v_lshl_add_u64 v[210:211], s[18:19], 0, v[132:133]
	s_mov_b32 m0, s16
	s_nop 0
	global_load_lds_dwordx4 v[210:211], off
	s_waitcnt vmcnt(8)
	s_waitcnt lgkmcnt(0)
	s_barrier
	v_mfma_f32_16x16x32_bf16 v[66:69], v[118:121], v[182:185], v[66:69]
	v_mfma_f32_16x16x32_bf16 v[70:73], v[126:129], v[182:185], v[70:73]
	v_mfma_f32_16x16x32_bf16 v[74:77], v[118:121], v[190:193], v[74:77]
	v_mfma_f32_16x16x32_bf16 v[78:81], v[126:129], v[190:193], v[78:81]
	v_mfma_f32_16x16x32_bf16 v[82:85], v[118:121], v[198:201], v[82:85]
	v_mfma_f32_16x16x32_bf16 v[86:89], v[126:129], v[198:201], v[86:89]
	v_mfma_f32_16x16x32_bf16 v[90:93], v[118:121], v[206:209], v[90:93]
	v_mfma_f32_16x16x32_bf16 v[66:69], v[122:125], v[186:189], v[66:69]
	v_mfma_f32_16x16x32_bf16 v[70:73], v[146:149], v[186:189], v[70:73]
	v_mfma_f32_16x16x32_bf16 v[74:77], v[122:125], v[194:197], v[74:77]
	v_mfma_f32_16x16x32_bf16 v[78:81], v[146:149], v[194:197], v[78:81]
	v_mfma_f32_16x16x32_bf16 v[82:85], v[122:125], v[202:205], v[82:85]
	v_mfma_f32_16x16x32_bf16 v[86:89], v[146:149], v[202:205], v[86:89]
	v_mfma_f32_16x16x32_bf16 v[224:227], v[122:125], v[220:223], v[90:93]
	v_mfma_f32_16x16x32_bf16 v[90:93], v[126:129], v[206:209], v[94:97]
	v_mfma_f32_16x16x32_bf16 v[228:231], v[146:149], v[220:223], v[90:93]
	v_mfma_f32_16x16x32_bf16 v[90:93], v[150:153], v[182:185], v[98:101]
	v_mfma_f32_16x16x32_bf16 v[98:101], v[154:157], v[186:189], v[90:93]
	v_mfma_f32_16x16x32_bf16 v[90:93], v[174:177], v[182:185], v[102:105]
	v_mfma_f32_16x16x32_bf16 v[42:45], v[174:177], v[190:193], v[42:45]
	v_mfma_f32_16x16x32_bf16 v[46:49], v[150:153], v[198:201], v[46:49]
	v_mfma_f32_16x16x32_bf16 v[50:53], v[174:177], v[198:201], v[50:53]
	v_mfma_f32_16x16x32_bf16 v[54:57], v[150:153], v[206:209], v[54:57]
	v_mfma_f32_16x16x32_bf16 v[58:61], v[174:177], v[206:209], v[58:61]
	v_mfma_f32_16x16x32_bf16 v[102:105], v[178:181], v[186:189], v[90:93]
	v_mfma_f32_16x16x32_bf16 v[90:93], v[150:153], v[190:193], v[106:109]
	v_mfma_f32_16x16x32_bf16 v[42:45], v[178:181], v[194:197], v[42:45]
	v_mfma_f32_16x16x32_bf16 v[46:49], v[154:157], v[202:205], v[46:49]
	v_mfma_f32_16x16x32_bf16 v[50:53], v[178:181], v[202:205], v[50:53]
	v_mfma_f32_16x16x32_bf16 v[54:57], v[154:157], v[220:223], v[54:57]
	v_mfma_f32_16x16x32_bf16 v[58:61], v[178:181], v[220:223], v[58:61]
	v_mfma_f32_16x16x32_bf16 v[182:185], v[154:157], v[194:197], v[90:93]
	s_barrier
; #define PG8_STAGE(bufoff, gbase, voff) do { _Pragma("unroll") for (int _i = 0; _i < 2; ++_i) \
;         __builtin_amdgcn_global_load_lds((const unsigned*)((const char*)(gbase) + (voff)[_i]), (PG8_LAS unsigned*)(lds + (bufoff) + ldsw + _i * 8192), 16, 0, 0); } while (0)
; #define PG8_LDA(dst, b, h) do { _Pragma("unroll") for (int m = 0; m < 4; ++m) _Pragma("unroll") for (int k = 0; k < 2; ++k) dst[m][k] = *(const PG8_LAS bf16x8*)(lds + PG8_SA(b, h) + aoff + m * 2048 + k * 1024); } while (0)
; #define PG8_LDB(dst, b, h) do { _Pragma("unroll") for (int n = 0; n < 2; ++n) _Pragma("unroll") for (int k = 0; k < 2; ++k) dst[n][k] = *(const PG8_LAS bf16x8*)(lds + PG8_SB(b, h) + boff + n * 2048 + k * 1024); } while (0)
; #define PG8_MMA(ai, bj, At, Bt) do { __builtin_amdgcn_s_setprio(1); _Pragma("unroll") for (int m = 0; m < 4; ++m) _Pragma("unroll") for (int n = 0; n < 2; ++n) _Pragma("unroll") for (int k = 0; k < 2; ++k) \
;         acc[ai][bj][m][n] = __builtin_amdgcn_mfma_f32_16x16x32_bf16(Bt[n][k], At[m][k], acc[ai][bj][m][n], 0, 0, 0); __builtin_amdgcn_s_setprio(0); } while (0)
; #define PG8_WAIT_V(n) asm volatile("s_waitcnt vmcnt(" #n ")" ::: "memory")
; #define PG8_WAIT_L(n) asm volatile("s_waitcnt lgkmcnt(" #n ")" ::: "memory")
; #define PG8_BAR __builtin_amdgcn_s_barrier()
; #define PG8_SCHED __builtin_amdgcn_sched_barrier(0)
; template <class Epi, class Sched, bool ALIGN_EPI = false, bool SP2 = false>
; __device__ __forceinline__ void gemm_phase(PG8_LAS unsigned char* lds, const Gemm g, const Sched& S, const Epi& E) {
;     ...
;             PG8_LDA(At, 0, 1); PG8_STAGE(PG8_SB(0, 0), b2, voffB); PG8_STAGE(PG8_SB(0, 1), b2 + hstep, voffB); PG8_STAGE(PG8_SA(0, 0), a2, voffA);
;             PG8_WAIT_V(8); PG8_WAIT_L(0); PG8_BAR; PG8_MMA(1, 0, At, B0); PG8_MMA(1, 1, At, B1); PG8_BAR; PG8_SCHED;
;             PG8_LDB(B0, 1, 0); PG8_LDB(B1, 1, 1); PG8_SCHED; PG8_LDA(At, 1, 0); PG8_STAGE(PG8_SA(0, 1), a2 + hstep, voffA);
;             PG8_WAIT_V(8); PG8_WAIT_L(0); PG8_BAR; PG8_MMA(0, 0, At, B0); PG8_MMA(0, 1, At, B1); PG8_BAR; PG8_SCHED;
	s_mov_b32 m0, s38
	v_lshl_add_u64 v[236:237], s[14:15], 0, v[134:135]
	s_add_u32 s16, s14, 0x18000
	ds_read_b128 v[90:93], v142 offset:16384
	ds_read_b128 v[94:97], v142 offset:17408
	ds_read_b128 v[106:109], v142 offset:18432
	ds_read_b128 v[186:189], v142 offset:19456
	ds_read_b128 v[190:193], v142 offset:20480
	ds_read_b128 v[194:197], v142 offset:21504
	ds_read_b128 v[198:201], v142 offset:22528
	ds_read_b128 v[202:205], v142 offset:23552
	global_load_lds_dwordx4 v[236:237], off
	v_lshl_add_u64 v[252:253], s[14:15], 0, v[130:131]
	s_mov_b32 m0, s17
	s_addc_u32 s17, s15, 0
	global_load_lds_dwordx4 v[252:253], off
	v_lshl_add_u64 v[206:207], s[16:17], 0, v[134:135]
	s_mov_b32 m0, s36
	v_lshl_add_u64 v[218:219], s[12:13], 0, v[136:137]
	global_load_lds_dwordx4 v[206:207], off
	v_lshl_add_u64 v[206:207], s[16:17], 0, v[130:131]
	s_mov_b32 m0, s37
	v_lshl_add_u64 v[238:239], s[12:13], 0, v[132:133]
	global_load_lds_dwordx4 v[206:207], off
	s_mov_b32 m0, s25
	s_nop 0
	global_load_lds_dwordx4 v[218:219], off
	s_mov_b32 m0, s26
	s_nop 0
	global_load_lds_dwordx4 v[238:239], off
	s_waitcnt vmcnt(8)
	s_waitcnt lgkmcnt(0)
	s_barrier
	v_mfma_f32_16x16x32_bf16 v[2:5], v[118:121], v[90:93], v[2:5]
	v_mfma_f32_16x16x32_bf16 v[6:9], v[126:129], v[90:93], v[6:9]
	v_mfma_f32_16x16x32_bf16 v[14:17], v[118:121], v[198:201], v[14:17]
	v_mfma_f32_16x16x32_bf16 v[18:21], v[126:129], v[198:201], v[18:21]
	v_mfma_f32_16x16x32_bf16 v[2:5], v[122:125], v[94:97], v[2:5]
	v_mfma_f32_16x16x32_bf16 v[6:9], v[146:149], v[94:97], v[6:9]
	v_mfma_f32_16x16x32_bf16 v[158:161], v[118:121], v[106:109], v[158:161]
	v_mfma_f32_16x16x32_bf16 v[162:165], v[126:129], v[106:109], v[162:165]
	v_mfma_f32_16x16x32_bf16 v[166:169], v[118:121], v[190:193], v[166:169]
	v_mfma_f32_16x16x32_bf16 v[170:173], v[126:129], v[190:193], v[170:173]
	v_mfma_f32_16x16x32_bf16 v[14:17], v[122:125], v[202:205], v[14:17]
	v_mfma_f32_16x16x32_bf16 v[18:21], v[146:149], v[202:205], v[18:21]
	v_mfma_f32_16x16x32_bf16 v[158:161], v[122:125], v[186:189], v[158:161]
	v_mfma_f32_16x16x32_bf16 v[162:165], v[146:149], v[186:189], v[162:165]
	v_mfma_f32_16x16x32_bf16 v[166:169], v[122:125], v[194:197], v[166:169]
	v_mfma_f32_16x16x32_bf16 v[170:173], v[146:149], v[194:197], v[170:173]
	v_mfma_f32_16x16x32_bf16 v[62:65], v[174:177], v[106:109], v[62:65]
	v_mfma_f32_16x16x32_bf16 v[22:25], v[150:153], v[90:93], v[22:25]
	v_mfma_f32_16x16x32_bf16 v[34:37], v[174:177], v[90:93], v[34:37]
	v_mfma_f32_16x16x32_bf16 v[38:41], v[150:153], v[106:109], v[38:41]
	v_mfma_f32_16x16x32_bf16 v[146:149], v[178:181], v[186:189], v[62:65]
	v_mfma_f32_16x16x32_bf16 v[62:65], v[150:153], v[190:193], v[110:113]
	v_mfma_f32_16x16x32_bf16 v[26:29], v[150:153], v[198:201], v[26:29]
	v_mfma_f32_16x16x32_bf16 v[22:25], v[154:157], v[94:97], v[22:25]
	v_mfma_f32_16x16x32_bf16 v[34:37], v[178:181], v[94:97], v[34:37]
	v_mfma_f32_16x16x32_bf16 v[38:41], v[154:157], v[186:189], v[38:41]
	v_mfma_f32_16x16x32_bf16 v[186:189], v[154:157], v[194:197], v[62:65]
	v_mfma_f32_16x16x32_bf16 v[62:65], v[174:177], v[190:193], v[114:117]
	v_mfma_f32_16x16x32_bf16 v[150:153], v[154:157], v[202:205], v[26:29]
	v_mfma_f32_16x16x32_bf16 v[26:29], v[174:177], v[198:201], v[30:33]
	v_mfma_f32_16x16x32_bf16 v[190:193], v[178:181], v[194:197], v[62:65]
	v_mfma_f32_16x16x32_bf16 v[154:157], v[178:181], v[202:205], v[26:29]
	s_barrier
	ds_read_b128 v[174:177], v11
	ds_read_b128 v[178:181], v11 offset:1024
	ds_read_b128 v[194:197], v11 offset:2048
	ds_read_b128 v[198:201], v11 offset:3072
	ds_read_b128 v[202:205], v12
	ds_read_b128 v[206:209], v12 offset:1024
	ds_read_b128 v[220:223], v12 offset:2048
	ds_read_b128 v[232:235], v12 offset:3072
	s_add_u32 s16, s12, 0x18000
	s_addc_u32 s17, s13, 0
	s_mov_b32 m0, s27
	v_lshl_add_u64 v[90:91], s[16:17], 0, v[136:137]
	ds_read_b128 v[10:13], v142 offset:32768
	ds_read_b128 v[26:29], v142 offset:33792
	ds_read_b128 v[30:33], v142 offset:34816
	ds_read_b128 v[62:65], v142 offset:35840
	ds_read_b128 v[244:247], v142 offset:36864
	ds_read_b128 v[248:251], v142 offset:37888
	ds_read_b128 v[210:213], v142 offset:38912
	ds_read_b128 v[214:217], v142 offset:39936
	global_load_lds_dwordx4 v[90:91], off
	v_lshl_add_u64 v[90:91], s[16:17], 0, v[132:133]
	s_mov_b32 m0, s28
	s_nop 0
	global_load_lds_dwordx4 v[90:91], off
	s_waitcnt vmcnt(8)
	s_waitcnt lgkmcnt(0)
	s_barrier
; #define PG8_STAGE(bufoff, gbase, voff) do { _Pragma("unroll") for (int _i = 0; _i < 2; ++_i) \
;         __builtin_amdgcn_global_load_lds((const unsigned*)((const char*)(gbase) + (voff)[_i]), (PG8_LAS unsigned*)(lds + (bufoff) + ldsw + _i * 8192), 16, 0, 0); } while (0)
; #define PG8_LDA(dst, b, h) do { _Pragma("unroll") for (int m = 0; m < 4; ++m) _Pragma("unroll") for (int k = 0; k < 2; ++k) dst[m][k] = *(const PG8_LAS bf16x8*)(lds + PG8_SA(b, h) + aoff + m * 2048 + k * 1024); } while (0)
; #define PG8_MMA(ai, bj, At, Bt) do { __builtin_amdgcn_s_setprio(1); _Pragma("unroll") for (int m = 0; m < 4; ++m) _Pragma("unroll") for (int n = 0; n < 2; ++n) _Pragma("unroll") for (int k = 0; k < 2; ++k) \
;         acc[ai][bj][m][n] = __builtin_amdgcn_mfma_f32_16x16x32_bf16(Bt[n][k], At[m][k], acc[ai][bj][m][n], 0, 0, 0); __builtin_amdgcn_s_setprio(0); } while (0)
; #define PG8_WAIT_V(n) asm volatile("s_waitcnt vmcnt(" #n ")" ::: "memory")
; #define PG8_WAIT_L(n) asm volatile("s_waitcnt lgkmcnt(" #n ")" ::: "memory")
; #define PG8_BAR __builtin_amdgcn_s_barrier()
; #define PG8_SCHED __builtin_amdgcn_sched_barrier(0)
; template <class Epi, class Sched, bool ALIGN_EPI = false, bool SP2 = false>
; __device__ __forceinline__ void gemm_phase(PG8_LAS unsigned char* lds, const Gemm g, const Sched& S, const Epi& E) {
;     ...
;             PG8_WAIT_V(8); PG8_WAIT_L(0); PG8_BAR; PG8_MMA(0, 0, At, B0); PG8_MMA(0, 1, At, B1); PG8_BAR; PG8_SCHED;
;             PG8_LDA(At, 1, 1); PG8_STAGE(PG8_SB(1, 0), b3, voffB); PG8_STAGE(PG8_SB(1, 1), b3 + hstep, voffB); PG8_STAGE(PG8_SA(1, 0), a3, voffA);
;             PG8_WAIT_V(8); PG8_WAIT_L(0); PG8_BAR; PG8_MMA(1, 0, At, B0); PG8_MMA(1, 1, At, B1); PG8_BAR; PG8_SCHED;
;     ...
;         if constexpr (ALIGN_EPI) { if (wr == 0) PG8_BAR; }
	v_mfma_f32_16x16x32_bf16 v[66:69], v[174:177], v[10:13], v[66:69]
	v_mfma_f32_16x16x32_bf16 v[126:129], v[178:181], v[26:29], v[66:69]
	v_mfma_f32_16x16x32_bf16 v[66:69], v[194:197], v[10:13], v[70:73]
	v_mfma_f32_16x16x32_bf16 v[122:125], v[198:201], v[26:29], v[66:69]
	v_mfma_f32_16x16x32_bf16 v[66:69], v[174:177], v[30:33], v[74:77]
	v_mfma_f32_16x16x32_bf16 v[110:113], v[178:181], v[62:65], v[66:69]
	v_mfma_f32_16x16x32_bf16 v[66:69], v[194:197], v[30:33], v[78:81]
	v_mfma_f32_16x16x32_bf16 v[106:109], v[198:201], v[62:65], v[66:69]
	v_mfma_f32_16x16x32_bf16 v[66:69], v[174:177], v[244:247], v[82:85]
	v_mfma_f32_16x16x32_bf16 v[94:97], v[178:181], v[248:251], v[66:69]
	v_mfma_f32_16x16x32_bf16 v[66:69], v[194:197], v[244:247], v[86:89]
	v_mfma_f32_16x16x32_bf16 v[90:93], v[198:201], v[248:251], v[66:69]
	v_mfma_f32_16x16x32_bf16 v[66:69], v[174:177], v[210:213], v[224:227]
	v_mfma_f32_16x16x32_bf16 v[78:81], v[178:181], v[214:217], v[66:69]
	v_mfma_f32_16x16x32_bf16 v[66:69], v[194:197], v[210:213], v[228:231]
	v_mfma_f32_16x16x32_bf16 v[74:77], v[198:201], v[214:217], v[66:69]
	v_mfma_f32_16x16x32_bf16 v[66:69], v[202:205], v[10:13], v[98:101]
	v_mfma_f32_16x16x32_bf16 v[10:13], v[220:223], v[10:13], v[102:105]
	v_mfma_f32_16x16x32_bf16 v[114:117], v[232:235], v[26:29], v[10:13]
	v_mfma_f32_16x16x32_bf16 v[10:13], v[202:205], v[30:33], v[182:185]
	v_mfma_f32_16x16x32_bf16 v[102:105], v[206:209], v[62:65], v[10:13]
	v_mfma_f32_16x16x32_bf16 v[10:13], v[220:223], v[30:33], v[42:45]
	v_mfma_f32_16x16x32_bf16 v[98:101], v[232:235], v[62:65], v[10:13]
	v_mfma_f32_16x16x32_bf16 v[10:13], v[202:205], v[244:247], v[46:49]
	v_mfma_f32_16x16x32_bf16 v[86:89], v[206:209], v[248:251], v[10:13]
	v_mfma_f32_16x16x32_bf16 v[10:13], v[220:223], v[244:247], v[50:53]
	v_mfma_f32_16x16x32_bf16 v[82:85], v[232:235], v[248:251], v[10:13]
	v_mfma_f32_16x16x32_bf16 v[10:13], v[202:205], v[210:213], v[54:57]
	v_mfma_f32_16x16x32_bf16 v[70:73], v[206:209], v[214:217], v[10:13]
	v_mfma_f32_16x16x32_bf16 v[10:13], v[220:223], v[210:213], v[58:61]
	v_mfma_f32_16x16x32_bf16 v[118:121], v[206:209], v[26:29], v[66:69]
	v_mfma_f32_16x16x32_bf16 v[66:69], v[232:235], v[214:217], v[10:13]
	s_barrier
	s_mov_b32 m0, s56
	s_nop 2
	v_lshl_add_u64 v[10:11], v[236:237], 0, s[94:95]
	s_add_u32 s16, s14, 0x18080
	ds_read_b128 v[50:53], v142 offset:49152
	ds_read_b128 v[182:185], v142 offset:50176
	ds_read_b128 v[210:213], v142 offset:51200
	ds_read_b128 v[214:217], v142 offset:52224
	ds_read_b128 v[224:227], v142 offset:53248
	ds_read_b128 v[228:231], v142 offset:54272
	ds_read_b128 v[244:247], v142 offset:55296
	ds_read_b128 v[248:251], v142 offset:56320
	global_load_lds_dwordx4 v[10:11], off
	v_lshl_add_u64 v[10:11], v[252:253], 0, s[94:95]
	s_mov_b32 m0, s39
	s_addc_u32 s17, s15, 0
	global_load_lds_dwordx4 v[10:11], off
	v_lshl_add_u64 v[10:11], s[16:17], 0, v[134:135]
	s_mov_b32 m0, s46
	s_nop 0
	global_load_lds_dwordx4 v[10:11], off
	v_lshl_add_u64 v[10:11], s[16:17], 0, v[130:131]
	s_mov_b32 m0, s55
	s_nop 0
	global_load_lds_dwordx4 v[10:11], off
	v_lshl_add_u64 v[10:11], v[218:219], 0, s[94:95]
	s_mov_b32 m0, s30
	s_nop 0
	global_load_lds_dwordx4 v[10:11], off
	v_lshl_add_u64 v[10:11], v[238:239], 0, s[94:95]
	s_mov_b32 m0, s31
	s_nop 0
	global_load_lds_dwordx4 v[10:11], off
	s_waitcnt vmcnt(8)
	s_waitcnt lgkmcnt(0)
	s_barrier
	v_mfma_f32_16x16x32_bf16 v[2:5], v[174:177], v[50:53], v[2:5]
	v_mfma_f32_16x16x32_bf16 v[62:65], v[178:181], v[182:185], v[2:5]
	v_mfma_f32_16x16x32_bf16 v[2:5], v[194:197], v[50:53], v[6:9]
	v_mfma_f32_16x16x32_bf16 v[58:61], v[198:201], v[182:185], v[2:5]
	v_mfma_f32_16x16x32_bf16 v[2:5], v[174:177], v[210:213], v[158:161]
	v_mfma_f32_16x16x32_bf16 v[46:49], v[178:181], v[214:217], v[2:5]
	v_mfma_f32_16x16x32_bf16 v[2:5], v[194:197], v[210:213], v[162:165]
	v_mfma_f32_16x16x32_bf16 v[42:45], v[198:201], v[214:217], v[2:5]
	v_mfma_f32_16x16x32_bf16 v[2:5], v[174:177], v[224:227], v[166:169]
	v_mfma_f32_16x16x32_bf16 v[30:33], v[178:181], v[228:231], v[2:5]
	v_mfma_f32_16x16x32_bf16 v[2:5], v[194:197], v[224:227], v[170:173]
	v_mfma_f32_16x16x32_bf16 v[26:29], v[198:201], v[228:231], v[2:5]
	v_mfma_f32_16x16x32_bf16 v[2:5], v[174:177], v[244:247], v[14:17]
	v_mfma_f32_16x16x32_bf16 v[14:17], v[178:181], v[248:251], v[2:5]
	v_mfma_f32_16x16x32_bf16 v[2:5], v[194:197], v[244:247], v[18:21]
	v_mfma_f32_16x16x32_bf16 v[10:13], v[198:201], v[248:251], v[2:5]
	v_mfma_f32_16x16x32_bf16 v[2:5], v[202:205], v[50:53], v[22:25]
	v_mfma_f32_16x16x32_bf16 v[54:57], v[206:209], v[182:185], v[2:5]
	v_mfma_f32_16x16x32_bf16 v[2:5], v[220:223], v[50:53], v[34:37]
	v_mfma_f32_16x16x32_bf16 v[50:53], v[232:235], v[182:185], v[2:5]
	v_mfma_f32_16x16x32_bf16 v[2:5], v[202:205], v[210:213], v[38:41]
	v_mfma_f32_16x16x32_bf16 v[38:41], v[206:209], v[214:217], v[2:5]
	v_mfma_f32_16x16x32_bf16 v[2:5], v[220:223], v[210:213], v[146:149]
	v_mfma_f32_16x16x32_bf16 v[34:37], v[232:235], v[214:217], v[2:5]
	v_mfma_f32_16x16x32_bf16 v[2:5], v[202:205], v[224:227], v[186:189]
	v_mfma_f32_16x16x32_bf16 v[22:25], v[206:209], v[228:231], v[2:5]
	v_mfma_f32_16x16x32_bf16 v[2:5], v[220:223], v[224:227], v[190:193]
	v_mfma_f32_16x16x32_bf16 v[18:21], v[232:235], v[228:231], v[2:5]
	v_mfma_f32_16x16x32_bf16 v[2:5], v[202:205], v[244:247], v[150:153]
	v_mfma_f32_16x16x32_bf16 v[6:9], v[206:209], v[248:251], v[2:5]
	v_mfma_f32_16x16x32_bf16 v[2:5], v[220:223], v[244:247], v[154:157]
	v_mfma_f32_16x16x32_bf16 v[2:5], v[232:235], v[248:251], v[2:5]
	s_barrier
	s_andn2_b64 vcc, exec, s[8:9]
	s_cbranch_vccnz .LBB0_393
	s_barrier

; #define PG8_STAGE(bufoff, gbase, voff) do { _Pragma("unroll") for (int _i = 0; _i < 2; ++_i) \
;         __builtin_amdgcn_global_load_lds((const unsigned*)((const char*)(gbase) + (voff)[_i]), (PG8_LAS unsigned*)(lds + (bufoff) + ldsw + _i * 8192), 16, 0, 0); } while (0)
; #define PG8_LDA(dst, b, h) do { _Pragma("unroll") for (int m = 0; m < 4; ++m) _Pragma("unroll") for (int k = 0; k < 2; ++k) dst[m][k] = *(const PG8_LAS bf16x8*)(lds + PG8_SA(b, h) + aoff + m * 2048 + k * 1024); } while (0)
; #define PG8_LDB(dst, b, h) do { _Pragma("unroll") for (int n = 0; n < 2; ++n) _Pragma("unroll") for (int k = 0; k < 2; ++k) dst[n][k] = *(const PG8_LAS bf16x8*)(lds + PG8_SB(b, h) + boff + n * 2048 + k * 1024); } while (0)
; #define PG8_MMA(ai, bj, At, Bt) do { __builtin_amdgcn_s_setprio(1); _Pragma("unroll") for (int m = 0; m < 4; ++m) _Pragma("unroll") for (int n = 0; n < 2; ++n) _Pragma("unroll") for (int k = 0; k < 2; ++k) \
;         acc[ai][bj][m][n] = __builtin_amdgcn_mfma_f32_16x16x32_bf16(Bt[n][k], At[m][k], acc[ai][bj][m][n], 0, 0, 0); __builtin_amdgcn_s_setprio(0); } while (0)
; #define PG8_WAIT_V(n) asm volatile("s_waitcnt vmcnt(" #n ")" ::: "memory")
; template <class Epi, class Sched, bool ALIGN_EPI = false, bool SP2 = false>
; __device__ __forceinline__ void gemm_phase(PG8_LAS unsigned char* lds, const Gemm g, const Sched& S, const Epi& E) {
;     ...
;         const char* nA = has_next ? (const char*)g.A + (size_t)nxt.pm * tstep : cA; const char* nB = has_next ? (const char*)g.Bt + (size_t)nxt.pn * tstep : cB;
;         for (int t = 0; t < nt; t += 2) {
;             const bool last = (t == nt - 2);
;             const char* a1 = cA + (size_t)(t + 1) * kstep;
;             const char* a2 = last ? nA : cA + (size_t)(t + 2) * kstep; const char* b2 = last ? nB : cB + (size_t)(t + 2) * kstep;
;             const char* a3 = a2 + kstep; const char* b3 = b2 + kstep;
;             if (last && has_next) S.a_ready(nxt);
;             if constexpr (SP2) {
;             PG8_LDB(B0, 0, 0); PG8_LDB(B1, 0, 1); PG8_SCHED; PG8_LDA(At, 0, 0); PG8_STAGE(PG8_SA(1, 1), a1 + hstep, voffA);
;             PG8_WAIT_V(8); PG8_WAIT_L(0); PG8_BAR; PG8_MMA(0, 0, At, B0); PG8_MMA(0, 1, At, B1); PG8_BAR; PG8_SCHED;
;             PG8_LDA(At, 0, 1); PG8_STAGE(PG8_SB(0, 0), b2, voffB); PG8_STAGE(PG8_SB(0, 1), b2 + hstep, voffB); PG8_STAGE(PG8_SA(0, 0), a2, voffA);
.Lboff_skip_F:
.LBB0_547:
	s_add_u32 s16, s22, 0xfffe0080
	s_addc_u32 s17, s23, -1
	s_add_i32 s52, 0, 0x10000
	s_cmp_eq_u32 s50, 4
	s_cselect_b32 s25, s15, s17
	s_cselect_b32 s24, s55, s16
	v_add_u32_e32 v0, s52, v244
	s_cselect_b32 s17, s13, s60
	s_cselect_b32 s16, s56, s57
	s_add_i32 s61, 0, 0x14000
	ds_read_b128 v[74:77], v0
	ds_read_b128 v[82:85], v0 offset:1024
	ds_read_b128 v[90:93], v0 offset:2048
	ds_read_b128 v[94:97], v0 offset:3072
	v_add_u32_e32 v0, s61, v244
	ds_read_b128 v[98:101], v0
	ds_read_b128 v[110:113], v0 offset:1024
	ds_read_b128 v[114:117], v0 offset:2048
	ds_read_b128 v[130:133], v0 offset:3072
	v_lshl_add_u64 v[194:195], s[22:23], 0, v[220:221]
	s_add_i32 m0, s31, 0xc000
	ds_read_b128 v[138:141], v245
	ds_read_b128 v[150:153], v245 offset:1024
	ds_read_b128 v[162:165], v245 offset:2048
	ds_read_b128 v[174:177], v245 offset:3072
	ds_read_b128 v[178:181], v245 offset:4096
	ds_read_b128 v[182:185], v245 offset:5120
	ds_read_b128 v[186:189], v245 offset:6144
	ds_read_b128 v[190:193], v245 offset:7168
	global_load_lds_dwordx4 v[194:195], off
	v_lshl_add_u64 v[194:195], s[22:23], 0, v[222:223]
	s_add_i32 m0, s31, 0xe000
	s_nop 0
	global_load_lds_dwordx4 v[194:195], off
	s_waitcnt vmcnt(8)
	s_waitcnt lgkmcnt(0)
	s_barrier
	v_mfma_f32_16x16x32_bf16 v[170:173], v[74:77], v[138:141], v[170:173]
	v_mfma_f32_16x16x32_bf16 v[166:169], v[90:93], v[138:141], v[166:169]
	v_mfma_f32_16x16x32_bf16 v[146:149], v[74:77], v[162:165], v[146:149]
	v_mfma_f32_16x16x32_bf16 v[142:145], v[90:93], v[162:165], v[142:145]
	v_mfma_f32_16x16x32_bf16 v[122:125], v[74:77], v[178:181], v[122:125]
	v_mfma_f32_16x16x32_bf16 v[118:121], v[90:93], v[178:181], v[118:121]
	v_mfma_f32_16x16x32_bf16 v[86:89], v[74:77], v[186:189], v[86:89]
	v_mfma_f32_16x16x32_bf16 v[78:81], v[90:93], v[186:189], v[78:81]
	v_mfma_f32_16x16x32_bf16 v[170:173], v[82:85], v[150:153], v[170:173]
	v_mfma_f32_16x16x32_bf16 v[166:169], v[94:97], v[150:153], v[166:169]
	v_mfma_f32_16x16x32_bf16 v[146:149], v[82:85], v[174:177], v[146:149]
	v_mfma_f32_16x16x32_bf16 v[142:145], v[94:97], v[174:177], v[142:145]
	v_mfma_f32_16x16x32_bf16 v[122:125], v[82:85], v[182:185], v[122:125]
	v_mfma_f32_16x16x32_bf16 v[118:121], v[94:97], v[182:185], v[118:121]
	v_mfma_f32_16x16x32_bf16 v[86:89], v[82:85], v[190:193], v[86:89]
	v_mfma_f32_16x16x32_bf16 v[78:81], v[94:97], v[190:193], v[78:81]
	v_mfma_f32_16x16x32_bf16 v[158:161], v[98:101], v[138:141], v[158:161]
	v_mfma_f32_16x16x32_bf16 v[134:137], v[98:101], v[162:165], v[134:137]
	v_mfma_f32_16x16x32_bf16 v[126:129], v[114:117], v[162:165], v[126:129]
	v_mfma_f32_16x16x32_bf16 v[106:109], v[98:101], v[178:181], v[106:109]
	v_mfma_f32_16x16x32_bf16 v[102:105], v[114:117], v[178:181], v[102:105]
	v_mfma_f32_16x16x32_bf16 v[70:73], v[98:101], v[186:189], v[70:73]
	v_mfma_f32_16x16x32_bf16 v[66:69], v[114:117], v[186:189], v[66:69]
	v_mfma_f32_16x16x32_bf16 v[158:161], v[110:113], v[150:153], v[158:161]
	v_mfma_f32_16x16x32_bf16 v[138:141], v[114:117], v[138:141], v[154:157]
	v_mfma_f32_16x16x32_bf16 v[134:137], v[110:113], v[174:177], v[134:137]
	v_mfma_f32_16x16x32_bf16 v[126:129], v[130:133], v[174:177], v[126:129]
	v_mfma_f32_16x16x32_bf16 v[106:109], v[110:113], v[182:185], v[106:109]
	v_mfma_f32_16x16x32_bf16 v[102:105], v[130:133], v[182:185], v[102:105]
	v_mfma_f32_16x16x32_bf16 v[70:73], v[110:113], v[190:193], v[70:73]
	v_mfma_f32_16x16x32_bf16 v[66:69], v[130:133], v[190:193], v[66:69]
	v_mfma_f32_16x16x32_bf16 v[138:141], v[130:133], v[150:153], v[138:141]
	s_barrier
	s_add_i32 s52, s52, s30
	v_lshl_add_u64 v[194:195], s[16:17], 0, v[206:207]
	s_mov_b32 m0, s52
	ds_read_b128 v[150:153], v245 offset:16384
	ds_read_b128 v[154:157], v245 offset:17408
	ds_read_b128 v[162:165], v245 offset:18432
	ds_read_b128 v[174:177], v245 offset:19456
	ds_read_b128 v[178:181], v245 offset:20480
	ds_read_b128 v[182:185], v245 offset:21504
	ds_read_b128 v[186:189], v245 offset:22528
	ds_read_b128 v[190:193], v245 offset:23552
	global_load_lds_dwordx4 v[194:195], off
	s_add_i32 m0, s52, 0x2000
	s_add_u32 s52, s16, 0x20000
	v_lshl_add_u64 v[196:197], s[16:17], 0, v[202:203]
	s_addc_u32 s53, s17, 0
	s_add_i32 s61, s61, s30
	global_load_lds_dwordx4 v[196:197], off
	v_lshl_add_u64 v[198:199], s[52:53], 0, v[206:207]
	s_mov_b32 m0, s61
	v_lshl_add_u64 v[200:201], s[24:25], 0, v[204:205]
	global_load_lds_dwordx4 v[198:199], off
	v_lshl_add_u64 v[198:199], s[52:53], 0, v[202:203]
	s_add_i32 m0, s61, 0x2000
	s_nop 0
	global_load_lds_dwordx4 v[198:199], off
	v_lshl_add_u64 v[198:199], s[24:25], 0, v[208:209]
	s_mov_b32 m0, s31
	s_nop 0
	global_load_lds_dwordx4 v[198:199], off
	s_mov_b32 m0, s34
	s_nop 0
	global_load_lds_dwordx4 v[200:201], off
	s_waitcnt vmcnt(8)
	s_waitcnt lgkmcnt(0)
	s_barrier
; #define PG8_STAGE(bufoff, gbase, voff) do { _Pragma("unroll") for (int _i = 0; _i < 2; ++_i) \
;         __builtin_amdgcn_global_load_lds((const unsigned*)((const char*)(gbase) + (voff)[_i]), (PG8_LAS unsigned*)(lds + (bufoff) + ldsw + _i * 8192), 16, 0, 0); } while (0)
; #define PG8_LDA(dst, b, h) do { _Pragma("unroll") for (int m = 0; m < 4; ++m) _Pragma("unroll") for (int k = 0; k < 2; ++k) dst[m][k] = *(const PG8_LAS bf16x8*)(lds + PG8_SA(b, h) + aoff + m * 2048 + k * 1024); } while (0)
; #define PG8_LDB(dst, b, h) do { _Pragma("unroll") for (int n = 0; n < 2; ++n) _Pragma("unroll") for (int k = 0; k < 2; ++k) dst[n][k] = *(const PG8_LAS bf16x8*)(lds + PG8_SB(b, h) + boff + n * 2048 + k * 1024); } while (0)
; #define PG8_MMA(ai, bj, At, Bt) do { __builtin_amdgcn_s_setprio(1); _Pragma("unroll") for (int m = 0; m < 4; ++m) _Pragma("unroll") for (int n = 0; n < 2; ++n) _Pragma("unroll") for (int k = 0; k < 2; ++k) \
;         acc[ai][bj][m][n] = __builtin_amdgcn_mfma_f32_16x16x32_bf16(Bt[n][k], At[m][k], acc[ai][bj][m][n], 0, 0, 0); __builtin_amdgcn_s_setprio(0); } while (0)
; #define PG8_WAIT_V(n) asm volatile("s_waitcnt vmcnt(" #n ")" ::: "memory")
; #define PG8_WAIT_L(n) asm volatile("s_waitcnt lgkmcnt(" #n ")" ::: "memory")
; #define PG8_BAR __builtin_amdgcn_s_barrier()
; #define PG8_SCHED __builtin_amdgcn_sched_barrier(0)
; template <class Epi, class Sched, bool ALIGN_EPI = false, bool SP2 = false>
; __device__ __forceinline__ void gemm_phase(PG8_LAS unsigned char* lds, const Gemm g, const Sched& S, const Epi& E) {
;     ...
;             PG8_WAIT_V(8); PG8_WAIT_L(0); PG8_BAR; PG8_MMA(1, 0, At, B0); PG8_MMA(1, 1, At, B1); PG8_BAR; PG8_SCHED;
;             PG8_LDB(B0, 1, 0); PG8_LDB(B1, 1, 1); PG8_SCHED; PG8_LDA(At, 1, 0); PG8_STAGE(PG8_SA(0, 1), a2 + hstep, voffA);
;             PG8_WAIT_V(8); PG8_WAIT_L(0); PG8_BAR; PG8_MMA(0, 0, At, B0); PG8_MMA(0, 1, At, B1); PG8_BAR; PG8_SCHED;
	v_mfma_f32_16x16x32_bf16 v[62:65], v[74:77], v[150:153], v[62:65]
	v_mfma_f32_16x16x32_bf16 v[58:61], v[90:93], v[150:153], v[58:61]
	v_mfma_f32_16x16x32_bf16 v[46:49], v[74:77], v[162:165], v[46:49]
	v_mfma_f32_16x16x32_bf16 v[42:45], v[90:93], v[162:165], v[42:45]
	v_mfma_f32_16x16x32_bf16 v[30:33], v[74:77], v[178:181], v[30:33]
	v_mfma_f32_16x16x32_bf16 v[26:29], v[90:93], v[178:181], v[26:29]
	v_mfma_f32_16x16x32_bf16 v[14:17], v[74:77], v[186:189], v[14:17]
	v_mfma_f32_16x16x32_bf16 v[10:13], v[90:93], v[186:189], v[10:13]
	v_mfma_f32_16x16x32_bf16 v[62:65], v[82:85], v[154:157], v[62:65]
	v_mfma_f32_16x16x32_bf16 v[58:61], v[94:97], v[154:157], v[58:61]
	v_mfma_f32_16x16x32_bf16 v[46:49], v[82:85], v[174:177], v[46:49]
	v_mfma_f32_16x16x32_bf16 v[42:45], v[94:97], v[174:177], v[42:45]
	v_mfma_f32_16x16x32_bf16 v[30:33], v[82:85], v[182:185], v[30:33]
	v_mfma_f32_16x16x32_bf16 v[26:29], v[94:97], v[182:185], v[26:29]
	v_mfma_f32_16x16x32_bf16 v[14:17], v[82:85], v[190:193], v[14:17]
	v_mfma_f32_16x16x32_bf16 v[10:13], v[94:97], v[190:193], v[10:13]
	v_mfma_f32_16x16x32_bf16 v[54:57], v[98:101], v[150:153], v[54:57]
	v_mfma_f32_16x16x32_bf16 v[50:53], v[114:117], v[150:153], v[50:53]
	v_mfma_f32_16x16x32_bf16 v[38:41], v[98:101], v[162:165], v[38:41]
	v_mfma_f32_16x16x32_bf16 v[34:37], v[114:117], v[162:165], v[34:37]
	v_mfma_f32_16x16x32_bf16 v[22:25], v[98:101], v[178:181], v[22:25]
	v_mfma_f32_16x16x32_bf16 v[18:21], v[114:117], v[178:181], v[18:21]
	v_mfma_f32_16x16x32_bf16 v[6:9], v[98:101], v[186:189], v[6:9]
	v_mfma_f32_16x16x32_bf16 v[2:5], v[114:117], v[186:189], v[2:5]
	v_mfma_f32_16x16x32_bf16 v[54:57], v[110:113], v[154:157], v[54:57]
	v_mfma_f32_16x16x32_bf16 v[50:53], v[130:133], v[154:157], v[50:53]
	v_mfma_f32_16x16x32_bf16 v[38:41], v[110:113], v[174:177], v[38:41]
	v_mfma_f32_16x16x32_bf16 v[34:37], v[130:133], v[174:177], v[34:37]
	v_mfma_f32_16x16x32_bf16 v[22:25], v[110:113], v[182:185], v[22:25]
	v_mfma_f32_16x16x32_bf16 v[18:21], v[130:133], v[182:185], v[18:21]
	v_mfma_f32_16x16x32_bf16 v[6:9], v[110:113], v[190:193], v[6:9]
	v_mfma_f32_16x16x32_bf16 v[2:5], v[130:133], v[190:193], v[2:5]
	s_barrier
	s_add_i32 s52, 0, 0x18000
	v_add_u32_e32 v0, s52, v244
	s_add_i32 s53, 0, 0x1c000
	ds_read_b128 v[74:77], v0
	ds_read_b128 v[82:85], v0 offset:1024
	ds_read_b128 v[90:93], v0 offset:2048
	ds_read_b128 v[94:97], v0 offset:3072
	v_add_u32_e32 v0, s53, v244
	ds_read_b128 v[98:101], v0
	ds_read_b128 v[110:113], v0 offset:1024
	ds_read_b128 v[114:117], v0 offset:2048
	ds_read_b128 v[130:133], v0 offset:3072
	s_add_u32 s24, s24, 0x20000
	s_addc_u32 s25, s25, 0
	s_mov_b32 m0, s35
	v_lshl_add_u64 v[212:213], s[24:25], 0, v[208:209]
	ds_read_b128 v[150:153], v245 offset:32768
	ds_read_b128 v[154:157], v245 offset:33792
	ds_read_b128 v[162:165], v245 offset:34816
	ds_read_b128 v[174:177], v245 offset:35840
	ds_read_b128 v[178:181], v245 offset:36864
	ds_read_b128 v[182:185], v245 offset:37888
	ds_read_b128 v[186:189], v245 offset:38912
	ds_read_b128 v[190:193], v245 offset:39936
	global_load_lds_dwordx4 v[212:213], off
	v_lshl_add_u64 v[212:213], s[24:25], 0, v[204:205]
	s_mov_b32 m0, s36
	s_nop 0
	global_load_lds_dwordx4 v[212:213], off
	s_waitcnt vmcnt(8)
	s_waitcnt lgkmcnt(0)
	s_barrier
	v_mfma_f32_16x16x32_bf16 v[170:173], v[74:77], v[150:153], v[170:173]
	v_mfma_f32_16x16x32_bf16 v[166:169], v[90:93], v[150:153], v[166:169]
	v_mfma_f32_16x16x32_bf16 v[146:149], v[74:77], v[162:165], v[146:149]
	v_mfma_f32_16x16x32_bf16 v[142:145], v[90:93], v[162:165], v[142:145]
	v_mfma_f32_16x16x32_bf16 v[122:125], v[74:77], v[178:181], v[122:125]
	v_mfma_f32_16x16x32_bf16 v[118:121], v[90:93], v[178:181], v[118:121]
	v_mfma_f32_16x16x32_bf16 v[86:89], v[74:77], v[186:189], v[86:89]
	v_mfma_f32_16x16x32_bf16 v[78:81], v[90:93], v[186:189], v[78:81]
	v_mfma_f32_16x16x32_bf16 v[170:173], v[82:85], v[154:157], v[170:173]
	v_mfma_f32_16x16x32_bf16 v[166:169], v[94:97], v[154:157], v[166:169]
	v_mfma_f32_16x16x32_bf16 v[146:149], v[82:85], v[174:177], v[146:149]
	v_mfma_f32_16x16x32_bf16 v[142:145], v[94:97], v[174:177], v[142:145]
	v_mfma_f32_16x16x32_bf16 v[122:125], v[82:85], v[182:185], v[122:125]
	v_mfma_f32_16x16x32_bf16 v[118:121], v[94:97], v[182:185], v[118:121]
	v_mfma_f32_16x16x32_bf16 v[86:89], v[82:85], v[190:193], v[86:89]
	v_mfma_f32_16x16x32_bf16 v[78:81], v[94:97], v[190:193], v[78:81]
	v_mfma_f32_16x16x32_bf16 v[158:161], v[98:101], v[150:153], v[158:161]
	v_mfma_f32_16x16x32_bf16 v[138:141], v[114:117], v[150:153], v[138:141]
	v_mfma_f32_16x16x32_bf16 v[134:137], v[98:101], v[162:165], v[134:137]
	v_mfma_f32_16x16x32_bf16 v[126:129], v[114:117], v[162:165], v[126:129]
	v_mfma_f32_16x16x32_bf16 v[106:109], v[98:101], v[178:181], v[106:109]
	v_mfma_f32_16x16x32_bf16 v[102:105], v[114:117], v[178:181], v[102:105]
	v_mfma_f32_16x16x32_bf16 v[70:73], v[98:101], v[186:189], v[70:73]
	v_mfma_f32_16x16x32_bf16 v[66:69], v[114:117], v[186:189], v[66:69]
	v_mfma_f32_16x16x32_bf16 v[158:161], v[110:113], v[154:157], v[158:161]
	v_mfma_f32_16x16x32_bf16 v[154:157], v[130:133], v[154:157], v[138:141]
	v_mfma_f32_16x16x32_bf16 v[134:137], v[110:113], v[174:177], v[134:137]
	v_mfma_f32_16x16x32_bf16 v[126:129], v[130:133], v[174:177], v[126:129]
	v_mfma_f32_16x16x32_bf16 v[106:109], v[110:113], v[182:185], v[106:109]
	v_mfma_f32_16x16x32_bf16 v[102:105], v[130:133], v[182:185], v[102:105]
	v_mfma_f32_16x16x32_bf16 v[70:73], v[110:113], v[190:193], v[70:73]
	v_mfma_f32_16x16x32_bf16 v[66:69], v[130:133], v[190:193], v[66:69]
	s_barrier
; #define PG8_STAGE(bufoff, gbase, voff) do { _Pragma("unroll") for (int _i = 0; _i < 2; ++_i) \
;         __builtin_amdgcn_global_load_lds((const unsigned*)((const char*)(gbase) + (voff)[_i]), (PG8_LAS unsigned*)(lds + (bufoff) + ldsw + _i * 8192), 16, 0, 0); } while (0)
; #define PG8_LDA(dst, b, h) do { _Pragma("unroll") for (int m = 0; m < 4; ++m) _Pragma("unroll") for (int k = 0; k < 2; ++k) dst[m][k] = *(const PG8_LAS bf16x8*)(lds + PG8_SA(b, h) + aoff + m * 2048 + k * 1024); } while (0)
; #define PG8_MMA(ai, bj, At, Bt) do { __builtin_amdgcn_s_setprio(1); _Pragma("unroll") for (int m = 0; m < 4; ++m) _Pragma("unroll") for (int n = 0; n < 2; ++n) _Pragma("unroll") for (int k = 0; k < 2; ++k) \
;         acc[ai][bj][m][n] = __builtin_amdgcn_mfma_f32_16x16x32_bf16(Bt[n][k], At[m][k], acc[ai][bj][m][n], 0, 0, 0); __builtin_amdgcn_s_setprio(0); } while (0)
; #define PG8_WAIT_V(n) asm volatile("s_waitcnt vmcnt(" #n ")" ::: "memory")
; #define PG8_WAIT_L(n) asm volatile("s_waitcnt lgkmcnt(" #n ")" ::: "memory")
; #define PG8_BAR __builtin_amdgcn_s_barrier()
; #define PG8_SCHED __builtin_amdgcn_sched_barrier(0)
; template <class Epi, class Sched, bool ALIGN_EPI = false, bool SP2 = false>
; __device__ __forceinline__ void gemm_phase(PG8_LAS unsigned char* lds, const Gemm g, const Sched& S, const Epi& E) {
;     ...
;         for (int t = 0; t < nt; t += 2) {
;     ...
;             PG8_LDA(At, 1, 1); PG8_STAGE(PG8_SB(1, 0), b3, voffB); PG8_STAGE(PG8_SB(1, 1), b3 + hstep, voffB); PG8_STAGE(PG8_SA(1, 0), a3, voffA);
;             PG8_WAIT_V(8); PG8_WAIT_L(0); PG8_BAR; PG8_MMA(1, 0, At, B0); PG8_MMA(1, 1, At, B1); PG8_BAR; PG8_SCHED;
	s_add_i32 s24, s52, s30
	v_lshl_add_u64 v[194:195], v[194:195], 0, s[94:95]
	s_mov_b32 m0, s24
	ds_read_b128 v[138:141], v245 offset:49152
	ds_read_b128 v[150:153], v245 offset:50176
	ds_read_b128 v[162:165], v245 offset:51200
	ds_read_b128 v[174:177], v245 offset:52224
	ds_read_b128 v[178:181], v245 offset:53248
	ds_read_b128 v[182:185], v245 offset:54272
	ds_read_b128 v[186:189], v245 offset:55296
	ds_read_b128 v[190:193], v245 offset:56320
	global_load_lds_dwordx4 v[194:195], off
	s_add_i32 m0, s24, 0x2000
	s_add_u32 s16, s16, 0x20080
	v_lshl_add_u64 v[194:195], v[196:197], 0, s[94:95]
	s_addc_u32 s17, s17, 0
	s_add_i32 s24, s53, s30
	global_load_lds_dwordx4 v[194:195], off
	v_lshl_add_u64 v[194:195], s[16:17], 0, v[206:207]
	s_mov_b32 m0, s24
	s_nop 0
	global_load_lds_dwordx4 v[194:195], off
	v_lshl_add_u64 v[194:195], s[16:17], 0, v[202:203]
	s_add_i32 m0, s24, 0x2000
	s_nop 0
	global_load_lds_dwordx4 v[194:195], off
	v_lshl_add_u64 v[194:195], v[198:199], 0, s[94:95]
	s_mov_b32 m0, s37
	s_nop 0
	global_load_lds_dwordx4 v[194:195], off
	v_lshl_add_u64 v[194:195], v[200:201], 0, s[94:95]
	s_mov_b32 m0, s38
	s_nop 0
	global_load_lds_dwordx4 v[194:195], off
	s_waitcnt vmcnt(8)
	s_waitcnt lgkmcnt(0)
	s_barrier
	v_mfma_f32_16x16x32_bf16 v[62:65], v[74:77], v[138:141], v[62:65]
	v_mfma_f32_16x16x32_bf16 v[58:61], v[90:93], v[138:141], v[58:61]
	v_mfma_f32_16x16x32_bf16 v[46:49], v[74:77], v[162:165], v[46:49]
	v_mfma_f32_16x16x32_bf16 v[42:45], v[90:93], v[162:165], v[42:45]
	v_mfma_f32_16x16x32_bf16 v[30:33], v[74:77], v[178:181], v[30:33]
	v_mfma_f32_16x16x32_bf16 v[26:29], v[90:93], v[178:181], v[26:29]
	v_mfma_f32_16x16x32_bf16 v[14:17], v[74:77], v[186:189], v[14:17]
	v_mfma_f32_16x16x32_bf16 v[10:13], v[90:93], v[186:189], v[10:13]
	v_mfma_f32_16x16x32_bf16 v[62:65], v[82:85], v[150:153], v[62:65]
	v_mfma_f32_16x16x32_bf16 v[58:61], v[94:97], v[150:153], v[58:61]
	v_mfma_f32_16x16x32_bf16 v[46:49], v[82:85], v[174:177], v[46:49]
	v_mfma_f32_16x16x32_bf16 v[42:45], v[94:97], v[174:177], v[42:45]
	v_mfma_f32_16x16x32_bf16 v[30:33], v[82:85], v[182:185], v[30:33]
	v_mfma_f32_16x16x32_bf16 v[26:29], v[94:97], v[182:185], v[26:29]
	v_mfma_f32_16x16x32_bf16 v[14:17], v[82:85], v[190:193], v[14:17]
	v_mfma_f32_16x16x32_bf16 v[10:13], v[94:97], v[190:193], v[10:13]
	v_mfma_f32_16x16x32_bf16 v[54:57], v[98:101], v[138:141], v[54:57]
	v_mfma_f32_16x16x32_bf16 v[50:53], v[114:117], v[138:141], v[50:53]
	v_mfma_f32_16x16x32_bf16 v[38:41], v[98:101], v[162:165], v[38:41]
	v_mfma_f32_16x16x32_bf16 v[34:37], v[114:117], v[162:165], v[34:37]
	v_mfma_f32_16x16x32_bf16 v[22:25], v[98:101], v[178:181], v[22:25]
	v_mfma_f32_16x16x32_bf16 v[18:21], v[114:117], v[178:181], v[18:21]
	v_mfma_f32_16x16x32_bf16 v[6:9], v[98:101], v[186:189], v[6:9]
	v_mfma_f32_16x16x32_bf16 v[2:5], v[114:117], v[186:189], v[2:5]
	v_mfma_f32_16x16x32_bf16 v[54:57], v[110:113], v[150:153], v[54:57]
	v_mfma_f32_16x16x32_bf16 v[50:53], v[130:133], v[150:153], v[50:53]
	v_mfma_f32_16x16x32_bf16 v[38:41], v[110:113], v[174:177], v[38:41]
	v_mfma_f32_16x16x32_bf16 v[34:37], v[130:133], v[174:177], v[34:37]
	v_mfma_f32_16x16x32_bf16 v[22:25], v[110:113], v[182:185], v[22:25]
	v_mfma_f32_16x16x32_bf16 v[18:21], v[130:133], v[182:185], v[18:21]
	v_mfma_f32_16x16x32_bf16 v[6:9], v[110:113], v[190:193], v[6:9]
	v_mfma_f32_16x16x32_bf16 v[2:5], v[130:133], v[190:193], v[2:5]
	s_barrier
	s_add_i32 s50, s50, 2
	s_add_u32 s22, s22, 0x100
	s_addc_u32 s23, s23, 0
	s_add_u32 s57, s57, 0x100
	s_addc_u32 s60, s60, 0
	s_cmp_gt_u32 s50, 5
	s_cbranch_scc0 .LBB0_547
	s_and_b64 vcc, exec, s[10:11]
	s_cbranch_vccz .LBB0_550
	s_barrier

; #define PG8_STAGE(bufoff, gbase, voff) do { _Pragma("unroll") for (int _i = 0; _i < 2; ++_i) \
;         __builtin_amdgcn_global_load_lds((const unsigned*)((const char*)(gbase) + (voff)[_i]), (PG8_LAS unsigned*)(lds + (bufoff) + ldsw + _i * 8192), 16, 0, 0); } while (0)
; #define PG8_LDA(dst, b, h) do { _Pragma("unroll") for (int m = 0; m < 4; ++m) _Pragma("unroll") for (int k = 0; k < 2; ++k) dst[m][k] = *(const PG8_LAS bf16x8*)(lds + PG8_SA(b, h) + aoff + m * 2048 + k * 1024); } while (0)
; #define PG8_LDB(dst, b, h) do { _Pragma("unroll") for (int n = 0; n < 2; ++n) _Pragma("unroll") for (int k = 0; k < 2; ++k) dst[n][k] = *(const PG8_LAS bf16x8*)(lds + PG8_SB(b, h) + boff + n * 2048 + k * 1024); } while (0)
; #define PG8_MMA(ai, bj, At, Bt) do { __builtin_amdgcn_s_setprio(1); _Pragma("unroll") for (int m = 0; m < 4; ++m) _Pragma("unroll") for (int n = 0; n < 2; ++n) _Pragma("unroll") for (int k = 0; k < 2; ++k) \
;         acc[ai][bj][m][n] = __builtin_amdgcn_mfma_f32_16x16x32_bf16(Bt[n][k], At[m][k], acc[ai][bj][m][n], 0, 0, 0); __builtin_amdgcn_s_setprio(0); } while (0)
; #define PG8_WAIT_V(n) asm volatile("s_waitcnt vmcnt(" #n ")" ::: "memory")
; #define PG8_WAIT_L(n) asm volatile("s_waitcnt lgkmcnt(" #n ")" ::: "memory")
; #define PG8_BAR __builtin_amdgcn_s_barrier()
; #define PG8_SCHED __builtin_amdgcn_sched_barrier(0)
; template <class Epi, class Sched, bool ALIGN_EPI = false, bool SP2 = false>
; __device__ __forceinline__ void gemm_phase(PG8_LAS unsigned char* lds, const Gemm g, const Sched& S, const Epi& E) {
;     ...
;             const bool last = (t == nt - 2);
;             const char* a1 = cA + (size_t)(t + 1) * kstep;
;             const char* a2 = last ? nA : cA + (size_t)(t + 2) * kstep; const char* b2 = last ? nB : cB + (size_t)(t + 2) * kstep;
;             const char* a3 = a2 + kstep; const char* b3 = b2 + kstep;
;             if (last && has_next) S.a_ready(nxt);
;             if constexpr (SP2) {
;             PG8_LDB(B0, 0, 0); PG8_LDB(B1, 0, 1); PG8_SCHED; PG8_LDA(At, 0, 0); PG8_STAGE(PG8_SA(1, 1), a1 + hstep, voffA);
;             PG8_WAIT_V(8); PG8_WAIT_L(0); PG8_BAR; PG8_MMA(0, 0, At, B0); PG8_MMA(0, 1, At, B1); PG8_BAR; PG8_SCHED;
;             PG8_LDA(At, 0, 1); PG8_STAGE(PG8_SB(0, 0), b2, voffB); PG8_STAGE(PG8_SB(0, 1), b2 + hstep, voffB); PG8_STAGE(PG8_SA(0, 0), a2, voffA);
.Lboff_skip_G:
.LBB0_567:
	s_add_u32 s16, s20, 0xfffe0080
	s_addc_u32 s17, s21, -1
	s_add_i32 s52, 0, 0x10000
	s_cmp_eq_u32 s50, 4
	s_cselect_b32 s23, s13, s17
	s_cselect_b32 s22, s55, s16
	s_cselect_b32 s17, s11, s60
	s_cselect_b32 s16, s56, s57
	s_add_i32 s61, 0, 0x14000
	v_add_u32_e32 v142, s52, v171
	v_add_u32_e32 v173, s61, v171
	ds_read_b128 v[130:133], v142
	ds_read_b128 v[134:137], v142 offset:1024
	ds_read_b128 v[138:141], v142 offset:2048
	ds_read_b128 v[142:145], v142 offset:3072
	ds_read_b128 v[146:149], v173
	ds_read_b128 v[162:165], v173 offset:1024
	ds_read_b128 v[166:169], v173 offset:2048
	ds_read_b128 v[174:177], v173 offset:3072
	v_lshl_add_u64 v[210:211], s[20:21], 0, v[158:159]
	s_add_i32 m0, s29, 0xc000
	ds_read_b128 v[178:181], v172
	ds_read_b128 v[182:185], v172 offset:1024
	ds_read_b128 v[186:189], v172 offset:2048
	ds_read_b128 v[190:193], v172 offset:3072
	ds_read_b128 v[194:197], v172 offset:4096
	ds_read_b128 v[198:201], v172 offset:5120
	ds_read_b128 v[202:205], v172 offset:6144
	ds_read_b128 v[206:209], v172 offset:7168
	global_load_lds_dwordx4 v[210:211], off
	v_lshl_add_u64 v[210:211], s[20:21], 0, v[160:161]
	s_add_i32 m0, s29, 0xe000
	s_nop 0
	global_load_lds_dwordx4 v[210:211], off
	s_waitcnt vmcnt(8)
	s_waitcnt lgkmcnt(0)
	s_barrier
	v_mfma_f32_16x16x32_bf16 v[126:129], v[130:133], v[178:181], v[126:129]
	v_mfma_f32_16x16x32_bf16 v[122:125], v[138:141], v[178:181], v[122:125]
	v_mfma_f32_16x16x32_bf16 v[118:121], v[130:133], v[186:189], v[118:121]
	v_mfma_f32_16x16x32_bf16 v[110:113], v[138:141], v[186:189], v[110:113]
	v_mfma_f32_16x16x32_bf16 v[98:101], v[130:133], v[194:197], v[98:101]
	v_mfma_f32_16x16x32_bf16 v[90:93], v[138:141], v[194:197], v[90:93]
	v_mfma_f32_16x16x32_bf16 v[82:85], v[130:133], v[202:205], v[82:85]
	v_mfma_f32_16x16x32_bf16 v[74:77], v[138:141], v[202:205], v[74:77]
	v_mfma_f32_16x16x32_bf16 v[126:129], v[134:137], v[182:185], v[126:129]
	v_mfma_f32_16x16x32_bf16 v[122:125], v[142:145], v[182:185], v[122:125]
	v_mfma_f32_16x16x32_bf16 v[118:121], v[134:137], v[190:193], v[118:121]
	v_mfma_f32_16x16x32_bf16 v[110:113], v[142:145], v[190:193], v[110:113]
	v_mfma_f32_16x16x32_bf16 v[98:101], v[134:137], v[198:201], v[98:101]
	v_mfma_f32_16x16x32_bf16 v[90:93], v[142:145], v[198:201], v[90:93]
	v_mfma_f32_16x16x32_bf16 v[82:85], v[134:137], v[206:209], v[82:85]
	v_mfma_f32_16x16x32_bf16 v[74:77], v[142:145], v[206:209], v[74:77]
	v_mfma_f32_16x16x32_bf16 v[114:117], v[146:149], v[178:181], v[114:117]
	v_mfma_f32_16x16x32_bf16 v[106:109], v[166:169], v[178:181], v[106:109]
	v_mfma_f32_16x16x32_bf16 v[102:105], v[146:149], v[186:189], v[102:105]
	v_mfma_f32_16x16x32_bf16 v[94:97], v[166:169], v[186:189], v[94:97]
	v_mfma_f32_16x16x32_bf16 v[86:89], v[146:149], v[194:197], v[86:89]
	v_mfma_f32_16x16x32_bf16 v[78:81], v[166:169], v[194:197], v[78:81]
	v_mfma_f32_16x16x32_bf16 v[70:73], v[146:149], v[202:205], v[70:73]
	v_mfma_f32_16x16x32_bf16 v[66:69], v[166:169], v[202:205], v[66:69]
	v_mfma_f32_16x16x32_bf16 v[114:117], v[162:165], v[182:185], v[114:117]
	v_mfma_f32_16x16x32_bf16 v[106:109], v[174:177], v[182:185], v[106:109]
	v_mfma_f32_16x16x32_bf16 v[102:105], v[162:165], v[190:193], v[102:105]
	v_mfma_f32_16x16x32_bf16 v[94:97], v[174:177], v[190:193], v[94:97]
	v_mfma_f32_16x16x32_bf16 v[86:89], v[162:165], v[198:201], v[86:89]
	v_mfma_f32_16x16x32_bf16 v[78:81], v[174:177], v[198:201], v[78:81]
	v_mfma_f32_16x16x32_bf16 v[70:73], v[162:165], v[206:209], v[70:73]
	v_mfma_f32_16x16x32_bf16 v[66:69], v[174:177], v[206:209], v[66:69]
	s_barrier
	s_add_i32 s52, s52, s28
	v_lshl_add_u64 v[210:211], s[16:17], 0, v[154:155]
	s_mov_b32 m0, s52
	ds_read_b128 v[178:181], v172 offset:16384
	ds_read_b128 v[182:185], v172 offset:17408
	ds_read_b128 v[186:189], v172 offset:18432
	ds_read_b128 v[190:193], v172 offset:19456
	ds_read_b128 v[194:197], v172 offset:20480
	ds_read_b128 v[198:201], v172 offset:21504
	ds_read_b128 v[202:205], v172 offset:22528
	ds_read_b128 v[206:209], v172 offset:23552
	global_load_lds_dwordx4 v[210:211], off
	s_add_i32 m0, s52, 0x2000
	s_add_u32 s52, s16, 0x20000
	v_lshl_add_u64 v[212:213], s[16:17], 0, v[150:151]
	s_addc_u32 s53, s17, 0
	s_add_i32 s61, s61, s28
	global_load_lds_dwordx4 v[212:213], off
	v_lshl_add_u64 v[214:215], s[52:53], 0, v[154:155]
	s_mov_b32 m0, s61
	v_lshl_add_u64 v[216:217], s[22:23], 0, v[152:153]
	global_load_lds_dwordx4 v[214:215], off
	v_lshl_add_u64 v[214:215], s[52:53], 0, v[150:151]
	s_add_i32 m0, s61, 0x2000
	s_nop 0
	global_load_lds_dwordx4 v[214:215], off
	v_lshl_add_u64 v[214:215], s[22:23], 0, v[156:157]
	s_mov_b32 m0, s29
	s_nop 0
	global_load_lds_dwordx4 v[214:215], off
	s_mov_b32 m0, s30
	s_nop 0
	global_load_lds_dwordx4 v[216:217], off
	s_waitcnt vmcnt(8)
	s_waitcnt lgkmcnt(0)
	s_barrier
; #define PG8_STAGE(bufoff, gbase, voff) do { _Pragma("unroll") for (int _i = 0; _i < 2; ++_i) \
;         __builtin_amdgcn_global_load_lds((const unsigned*)((const char*)(gbase) + (voff)[_i]), (PG8_LAS unsigned*)(lds + (bufoff) + ldsw + _i * 8192), 16, 0, 0); } while (0)
; #define PG8_LDA(dst, b, h) do { _Pragma("unroll") for (int m = 0; m < 4; ++m) _Pragma("unroll") for (int k = 0; k < 2; ++k) dst[m][k] = *(const PG8_LAS bf16x8*)(lds + PG8_SA(b, h) + aoff + m * 2048 + k * 1024); } while (0)
; #define PG8_LDB(dst, b, h) do { _Pragma("unroll") for (int n = 0; n < 2; ++n) _Pragma("unroll") for (int k = 0; k < 2; ++k) dst[n][k] = *(const PG8_LAS bf16x8*)(lds + PG8_SB(b, h) + boff + n * 2048 + k * 1024); } while (0)
; #define PG8_MMA(ai, bj, At, Bt) do { __builtin_amdgcn_s_setprio(1); _Pragma("unroll") for (int m = 0; m < 4; ++m) _Pragma("unroll") for (int n = 0; n < 2; ++n) _Pragma("unroll") for (int k = 0; k < 2; ++k) \
;         acc[ai][bj][m][n] = __builtin_amdgcn_mfma_f32_16x16x32_bf16(Bt[n][k], At[m][k], acc[ai][bj][m][n], 0, 0, 0); __builtin_amdgcn_s_setprio(0); } while (0)
; #define PG8_WAIT_V(n) asm volatile("s_waitcnt vmcnt(" #n ")" ::: "memory")
; #define PG8_WAIT_L(n) asm volatile("s_waitcnt lgkmcnt(" #n ")" ::: "memory")
; #define PG8_BAR __builtin_amdgcn_s_barrier()
; #define PG8_SCHED __builtin_amdgcn_sched_barrier(0)
; template <class Epi, class Sched, bool ALIGN_EPI = false, bool SP2 = false>
; __device__ __forceinline__ void gemm_phase(PG8_LAS unsigned char* lds, const Gemm g, const Sched& S, const Epi& E) {
;     ...
;             PG8_WAIT_V(8); PG8_WAIT_L(0); PG8_BAR; PG8_MMA(1, 0, At, B0); PG8_MMA(1, 1, At, B1); PG8_BAR; PG8_SCHED;
;             PG8_LDB(B0, 1, 0); PG8_LDB(B1, 1, 1); PG8_SCHED; PG8_LDA(At, 1, 0); PG8_STAGE(PG8_SA(0, 1), a2 + hstep, voffA);
;             PG8_WAIT_V(8); PG8_WAIT_L(0); PG8_BAR; PG8_MMA(0, 0, At, B0); PG8_MMA(0, 1, At, B1); PG8_BAR; PG8_SCHED;
	v_mfma_f32_16x16x32_bf16 v[62:65], v[130:133], v[178:181], v[62:65]
	v_mfma_f32_16x16x32_bf16 v[58:61], v[138:141], v[178:181], v[58:61]
	v_mfma_f32_16x16x32_bf16 v[50:53], v[130:133], v[186:189], v[50:53]
	v_mfma_f32_16x16x32_bf16 v[42:45], v[138:141], v[186:189], v[42:45]
	v_mfma_f32_16x16x32_bf16 v[34:37], v[130:133], v[194:197], v[34:37]
	v_mfma_f32_16x16x32_bf16 v[26:29], v[138:141], v[194:197], v[26:29]
	v_mfma_f32_16x16x32_bf16 v[18:21], v[130:133], v[202:205], v[18:21]
	v_mfma_f32_16x16x32_bf16 v[10:13], v[138:141], v[202:205], v[10:13]
	v_mfma_f32_16x16x32_bf16 v[62:65], v[134:137], v[182:185], v[62:65]
	v_mfma_f32_16x16x32_bf16 v[58:61], v[142:145], v[182:185], v[58:61]
	v_mfma_f32_16x16x32_bf16 v[50:53], v[134:137], v[190:193], v[50:53]
	v_mfma_f32_16x16x32_bf16 v[42:45], v[142:145], v[190:193], v[42:45]
	v_mfma_f32_16x16x32_bf16 v[34:37], v[134:137], v[198:201], v[34:37]
	v_mfma_f32_16x16x32_bf16 v[26:29], v[142:145], v[198:201], v[26:29]
	v_mfma_f32_16x16x32_bf16 v[18:21], v[134:137], v[206:209], v[18:21]
	v_mfma_f32_16x16x32_bf16 v[10:13], v[142:145], v[206:209], v[10:13]
	v_mfma_f32_16x16x32_bf16 v[54:57], v[146:149], v[178:181], v[54:57]
	v_mfma_f32_16x16x32_bf16 v[46:49], v[166:169], v[178:181], v[46:49]
	v_mfma_f32_16x16x32_bf16 v[38:41], v[146:149], v[186:189], v[38:41]
	v_mfma_f32_16x16x32_bf16 v[30:33], v[166:169], v[186:189], v[30:33]
	v_mfma_f32_16x16x32_bf16 v[22:25], v[146:149], v[194:197], v[22:25]
	v_mfma_f32_16x16x32_bf16 v[14:17], v[166:169], v[194:197], v[14:17]
	v_mfma_f32_16x16x32_bf16 v[6:9], v[146:149], v[202:205], v[6:9]
	v_mfma_f32_16x16x32_bf16 v[2:5], v[166:169], v[202:205], v[2:5]
	v_mfma_f32_16x16x32_bf16 v[54:57], v[162:165], v[182:185], v[54:57]
	v_mfma_f32_16x16x32_bf16 v[46:49], v[174:177], v[182:185], v[46:49]
	v_mfma_f32_16x16x32_bf16 v[38:41], v[162:165], v[190:193], v[38:41]
	v_mfma_f32_16x16x32_bf16 v[30:33], v[174:177], v[190:193], v[30:33]
	v_mfma_f32_16x16x32_bf16 v[22:25], v[162:165], v[198:201], v[22:25]
	v_mfma_f32_16x16x32_bf16 v[14:17], v[174:177], v[198:201], v[14:17]
	v_mfma_f32_16x16x32_bf16 v[6:9], v[162:165], v[206:209], v[6:9]
	v_mfma_f32_16x16x32_bf16 v[2:5], v[174:177], v[206:209], v[2:5]
	s_barrier
	s_add_i32 s52, 0, 0x18000
	s_add_i32 s53, 0, 0x1c000
	v_add_u32_e32 v142, s52, v171
	v_add_u32_e32 v173, s53, v171
	ds_read_b128 v[130:133], v142
	ds_read_b128 v[134:137], v142 offset:1024
	ds_read_b128 v[138:141], v142 offset:2048
	ds_read_b128 v[142:145], v142 offset:3072
	ds_read_b128 v[146:149], v173
	ds_read_b128 v[162:165], v173 offset:1024
	ds_read_b128 v[166:169], v173 offset:2048
	ds_read_b128 v[174:177], v173 offset:3072
	s_add_u32 s22, s22, 0x20000
	s_addc_u32 s23, s23, 0
	s_mov_b32 m0, s31
	v_lshl_add_u64 v[218:219], s[22:23], 0, v[156:157]
	ds_read_b128 v[178:181], v172 offset:32768
	ds_read_b128 v[182:185], v172 offset:33792
	ds_read_b128 v[186:189], v172 offset:34816
	ds_read_b128 v[190:193], v172 offset:35840
	ds_read_b128 v[194:197], v172 offset:36864
	ds_read_b128 v[198:201], v172 offset:37888
	ds_read_b128 v[202:205], v172 offset:38912
	ds_read_b128 v[206:209], v172 offset:39936
	global_load_lds_dwordx4 v[218:219], off
	v_lshl_add_u64 v[218:219], s[22:23], 0, v[152:153]
	s_mov_b32 m0, s34
	s_nop 0
	global_load_lds_dwordx4 v[218:219], off
	s_waitcnt vmcnt(8)
	s_waitcnt lgkmcnt(0)
	s_barrier
	v_mfma_f32_16x16x32_bf16 v[126:129], v[130:133], v[178:181], v[126:129]
	v_mfma_f32_16x16x32_bf16 v[122:125], v[138:141], v[178:181], v[122:125]
	v_mfma_f32_16x16x32_bf16 v[118:121], v[130:133], v[186:189], v[118:121]
	v_mfma_f32_16x16x32_bf16 v[110:113], v[138:141], v[186:189], v[110:113]
	v_mfma_f32_16x16x32_bf16 v[98:101], v[130:133], v[194:197], v[98:101]
	v_mfma_f32_16x16x32_bf16 v[90:93], v[138:141], v[194:197], v[90:93]
	v_mfma_f32_16x16x32_bf16 v[82:85], v[130:133], v[202:205], v[82:85]
	v_mfma_f32_16x16x32_bf16 v[74:77], v[138:141], v[202:205], v[74:77]
	v_mfma_f32_16x16x32_bf16 v[126:129], v[134:137], v[182:185], v[126:129]
	v_mfma_f32_16x16x32_bf16 v[122:125], v[142:145], v[182:185], v[122:125]
	v_mfma_f32_16x16x32_bf16 v[118:121], v[134:137], v[190:193], v[118:121]
	v_mfma_f32_16x16x32_bf16 v[110:113], v[142:145], v[190:193], v[110:113]
	v_mfma_f32_16x16x32_bf16 v[98:101], v[134:137], v[198:201], v[98:101]
	v_mfma_f32_16x16x32_bf16 v[90:93], v[142:145], v[198:201], v[90:93]
	v_mfma_f32_16x16x32_bf16 v[82:85], v[134:137], v[206:209], v[82:85]
	v_mfma_f32_16x16x32_bf16 v[74:77], v[142:145], v[206:209], v[74:77]
	v_mfma_f32_16x16x32_bf16 v[114:117], v[146:149], v[178:181], v[114:117]
	v_mfma_f32_16x16x32_bf16 v[106:109], v[166:169], v[178:181], v[106:109]
	v_mfma_f32_16x16x32_bf16 v[102:105], v[146:149], v[186:189], v[102:105]
	v_mfma_f32_16x16x32_bf16 v[94:97], v[166:169], v[186:189], v[94:97]
	v_mfma_f32_16x16x32_bf16 v[86:89], v[146:149], v[194:197], v[86:89]
	v_mfma_f32_16x16x32_bf16 v[78:81], v[166:169], v[194:197], v[78:81]
	v_mfma_f32_16x16x32_bf16 v[70:73], v[146:149], v[202:205], v[70:73]
	v_mfma_f32_16x16x32_bf16 v[66:69], v[166:169], v[202:205], v[66:69]
	v_mfma_f32_16x16x32_bf16 v[114:117], v[162:165], v[182:185], v[114:117]
	v_mfma_f32_16x16x32_bf16 v[106:109], v[174:177], v[182:185], v[106:109]
	v_mfma_f32_16x16x32_bf16 v[102:105], v[162:165], v[190:193], v[102:105]
	v_mfma_f32_16x16x32_bf16 v[94:97], v[174:177], v[190:193], v[94:97]
	v_mfma_f32_16x16x32_bf16 v[86:89], v[162:165], v[198:201], v[86:89]
	v_mfma_f32_16x16x32_bf16 v[78:81], v[174:177], v[198:201], v[78:81]
	v_mfma_f32_16x16x32_bf16 v[70:73], v[162:165], v[206:209], v[70:73]
	v_mfma_f32_16x16x32_bf16 v[66:69], v[174:177], v[206:209], v[66:69]
	s_barrier
; #define PG8_STAGE(bufoff, gbase, voff) do { _Pragma("unroll") for (int _i = 0; _i < 2; ++_i) \
;         __builtin_amdgcn_global_load_lds((const unsigned*)((const char*)(gbase) + (voff)[_i]), (PG8_LAS unsigned*)(lds + (bufoff) + ldsw + _i * 8192), 16, 0, 0); } while (0)
; #define PG8_LDA(dst, b, h) do { _Pragma("unroll") for (int m = 0; m < 4; ++m) _Pragma("unroll") for (int k = 0; k < 2; ++k) dst[m][k] = *(const PG8_LAS bf16x8*)(lds + PG8_SA(b, h) + aoff + m * 2048 + k * 1024); } while (0)
; #define PG8_MMA(ai, bj, At, Bt) do { __builtin_amdgcn_s_setprio(1); _Pragma("unroll") for (int m = 0; m < 4; ++m) _Pragma("unroll") for (int n = 0; n < 2; ++n) _Pragma("unroll") for (int k = 0; k < 2; ++k) \
;         acc[ai][bj][m][n] = __builtin_amdgcn_mfma_f32_16x16x32_bf16(Bt[n][k], At[m][k], acc[ai][bj][m][n], 0, 0, 0); __builtin_amdgcn_s_setprio(0); } while (0)
; #define PG8_WAIT_V(n) asm volatile("s_waitcnt vmcnt(" #n ")" ::: "memory")
; #define PG8_WAIT_L(n) asm volatile("s_waitcnt lgkmcnt(" #n ")" ::: "memory")
; #define PG8_BAR __builtin_amdgcn_s_barrier()
; #define PG8_SCHED __builtin_amdgcn_sched_barrier(0)
; template <class Epi, class Sched, bool ALIGN_EPI = false, bool SP2 = false>
; __device__ __forceinline__ void gemm_phase(PG8_LAS unsigned char* lds, const Gemm g, const Sched& S, const Epi& E) {
;     ...
;         for (int t = 0; t < nt; t += 2) {
;     ...
;             PG8_LDA(At, 1, 1); PG8_STAGE(PG8_SB(1, 0), b3, voffB); PG8_STAGE(PG8_SB(1, 1), b3 + hstep, voffB); PG8_STAGE(PG8_SA(1, 0), a3, voffA);
;             PG8_WAIT_V(8); PG8_WAIT_L(0); PG8_BAR; PG8_MMA(1, 0, At, B0); PG8_MMA(1, 1, At, B1); PG8_BAR; PG8_SCHED;
	s_add_i32 s22, s52, s28
	v_lshl_add_u64 v[210:211], v[210:211], 0, s[94:95]
	s_mov_b32 m0, s22
	ds_read_b128 v[178:181], v172 offset:49152
	ds_read_b128 v[182:185], v172 offset:50176
	ds_read_b128 v[186:189], v172 offset:51200
	ds_read_b128 v[190:193], v172 offset:52224
	ds_read_b128 v[194:197], v172 offset:53248
	ds_read_b128 v[198:201], v172 offset:54272
	ds_read_b128 v[202:205], v172 offset:55296
	ds_read_b128 v[206:209], v172 offset:56320
	global_load_lds_dwordx4 v[210:211], off
	s_add_i32 m0, s22, 0x2000
	s_add_u32 s16, s16, 0x20080
	v_lshl_add_u64 v[210:211], v[212:213], 0, s[94:95]
	s_addc_u32 s17, s17, 0
	s_add_i32 s22, s53, s28
	global_load_lds_dwordx4 v[210:211], off
	v_lshl_add_u64 v[210:211], s[16:17], 0, v[154:155]
	s_mov_b32 m0, s22
	s_nop 0
	global_load_lds_dwordx4 v[210:211], off
	v_lshl_add_u64 v[210:211], s[16:17], 0, v[150:151]
	s_add_i32 m0, s22, 0x2000
	s_nop 0
	global_load_lds_dwordx4 v[210:211], off
	v_lshl_add_u64 v[210:211], v[214:215], 0, s[94:95]
	s_mov_b32 m0, s33
	s_nop 0
	global_load_lds_dwordx4 v[210:211], off
	v_lshl_add_u64 v[210:211], v[216:217], 0, s[94:95]
	s_mov_b32 m0, s37
	s_nop 0
	global_load_lds_dwordx4 v[210:211], off
	s_waitcnt vmcnt(8)
	s_waitcnt lgkmcnt(0)
	s_barrier
	v_mfma_f32_16x16x32_bf16 v[62:65], v[130:133], v[178:181], v[62:65]
	v_mfma_f32_16x16x32_bf16 v[58:61], v[138:141], v[178:181], v[58:61]
	v_mfma_f32_16x16x32_bf16 v[50:53], v[130:133], v[186:189], v[50:53]
	v_mfma_f32_16x16x32_bf16 v[42:45], v[138:141], v[186:189], v[42:45]
	v_mfma_f32_16x16x32_bf16 v[34:37], v[130:133], v[194:197], v[34:37]
	v_mfma_f32_16x16x32_bf16 v[26:29], v[138:141], v[194:197], v[26:29]
	v_mfma_f32_16x16x32_bf16 v[18:21], v[130:133], v[202:205], v[18:21]
	v_mfma_f32_16x16x32_bf16 v[10:13], v[138:141], v[202:205], v[10:13]
	v_mfma_f32_16x16x32_bf16 v[62:65], v[134:137], v[182:185], v[62:65]
	v_mfma_f32_16x16x32_bf16 v[58:61], v[142:145], v[182:185], v[58:61]
	v_mfma_f32_16x16x32_bf16 v[50:53], v[134:137], v[190:193], v[50:53]
	v_mfma_f32_16x16x32_bf16 v[42:45], v[142:145], v[190:193], v[42:45]
	v_mfma_f32_16x16x32_bf16 v[34:37], v[134:137], v[198:201], v[34:37]
	v_mfma_f32_16x16x32_bf16 v[26:29], v[142:145], v[198:201], v[26:29]
	v_mfma_f32_16x16x32_bf16 v[18:21], v[134:137], v[206:209], v[18:21]
	v_mfma_f32_16x16x32_bf16 v[10:13], v[142:145], v[206:209], v[10:13]
	v_mfma_f32_16x16x32_bf16 v[54:57], v[146:149], v[178:181], v[54:57]
	v_mfma_f32_16x16x32_bf16 v[46:49], v[166:169], v[178:181], v[46:49]
	v_mfma_f32_16x16x32_bf16 v[38:41], v[146:149], v[186:189], v[38:41]
	v_mfma_f32_16x16x32_bf16 v[30:33], v[166:169], v[186:189], v[30:33]
	v_mfma_f32_16x16x32_bf16 v[22:25], v[146:149], v[194:197], v[22:25]
	v_mfma_f32_16x16x32_bf16 v[14:17], v[166:169], v[194:197], v[14:17]
	v_mfma_f32_16x16x32_bf16 v[6:9], v[146:149], v[202:205], v[6:9]
	v_mfma_f32_16x16x32_bf16 v[2:5], v[166:169], v[202:205], v[2:5]
	v_mfma_f32_16x16x32_bf16 v[54:57], v[162:165], v[182:185], v[54:57]
	v_mfma_f32_16x16x32_bf16 v[46:49], v[174:177], v[182:185], v[46:49]
	v_mfma_f32_16x16x32_bf16 v[38:41], v[162:165], v[190:193], v[38:41]
	v_mfma_f32_16x16x32_bf16 v[30:33], v[174:177], v[190:193], v[30:33]
	v_mfma_f32_16x16x32_bf16 v[22:25], v[162:165], v[198:201], v[22:25]
	v_mfma_f32_16x16x32_bf16 v[14:17], v[174:177], v[198:201], v[14:17]
	v_mfma_f32_16x16x32_bf16 v[6:9], v[162:165], v[206:209], v[6:9]
	v_mfma_f32_16x16x32_bf16 v[2:5], v[174:177], v[206:209], v[2:5]
	s_barrier
	s_add_i32 s50, s50, 2
	s_add_u32 s20, s20, 0x100
	s_addc_u32 s21, s21, 0
	s_add_u32 s57, s57, 0x100
	s_addc_u32 s60, s60, 0
	s_cmp_gt_u32 s50, 5
	s_cbranch_scc0 .LBB0_567
	s_and_b64 vcc, exec, s[8:9]
	s_cbranch_vccz .LBB0_570
	s_barrier

; #define PG8_STAGE(bufoff, gbase, voff) do { _Pragma("unroll") for (int _i = 0; _i < 2; ++_i) \
;         __builtin_amdgcn_global_load_lds((const unsigned*)((const char*)(gbase) + (voff)[_i]), (PG8_LAS unsigned*)(lds + (bufoff) + ldsw + _i * 8192), 16, 0, 0); } while (0)
; #define PG8_LDA(dst, b, h) do { _Pragma("unroll") for (int m = 0; m < 4; ++m) _Pragma("unroll") for (int k = 0; k < 2; ++k) dst[m][k] = *(const PG8_LAS bf16x8*)(lds + PG8_SA(b, h) + aoff + m * 2048 + k * 1024); } while (0)
; #define PG8_LDB(dst, b, h) do { _Pragma("unroll") for (int n = 0; n < 2; ++n) _Pragma("unroll") for (int k = 0; k < 2; ++k) dst[n][k] = *(const PG8_LAS bf16x8*)(lds + PG8_SB(b, h) + boff + n * 2048 + k * 1024); } while (0)
; #define PG8_MMA(ai, bj, At, Bt) do { __builtin_amdgcn_s_setprio(1); _Pragma("unroll") for (int m = 0; m < 4; ++m) _Pragma("unroll") for (int n = 0; n < 2; ++n) _Pragma("unroll") for (int k = 0; k < 2; ++k) \
;         acc[ai][bj][m][n] = __builtin_amdgcn_mfma_f32_16x16x32_bf16(Bt[n][k], At[m][k], acc[ai][bj][m][n], 0, 0, 0); __builtin_amdgcn_s_setprio(0); } while (0)
; #define PG8_WAIT_V(n) asm volatile("s_waitcnt vmcnt(" #n ")" ::: "memory")
; #define PG8_WAIT_L(n) asm volatile("s_waitcnt lgkmcnt(" #n ")" ::: "memory")
; #define PG8_BAR __builtin_amdgcn_s_barrier()
; #define PG8_SCHED __builtin_amdgcn_sched_barrier(0)
; template <class Epi, class Sched, bool ALIGN_EPI = false, bool SP2 = false>
; __device__ __forceinline__ void gemm_phase(PG8_LAS unsigned char* lds, const Gemm g, const Sched& S, const Epi& E) {
;     ...
;             const bool last = (t == nt - 2);
;             const char* a1 = cA + (size_t)(t + 1) * kstep;
;             const char* a2 = last ? nA : cA + (size_t)(t + 2) * kstep; const char* b2 = last ? nB : cB + (size_t)(t + 2) * kstep;
;             const char* a3 = a2 + kstep; const char* b3 = b2 + kstep;
;             if (last && has_next) S.a_ready(nxt);
;             if constexpr (SP2) {
;             PG8_LDB(B0, 0, 0); PG8_LDB(B1, 0, 1); PG8_SCHED; PG8_LDA(At, 0, 0); PG8_STAGE(PG8_SA(1, 1), a1 + hstep, voffA);
;             PG8_WAIT_V(8); PG8_WAIT_L(0); PG8_BAR; PG8_MMA(0, 0, At, B0); PG8_MMA(0, 1, At, B1); PG8_BAR; PG8_SCHED;
;             PG8_LDA(At, 0, 1); PG8_STAGE(PG8_SB(0, 0), b2, voffB); PG8_STAGE(PG8_SB(0, 1), b2 + hstep, voffB); PG8_STAGE(PG8_SA(0, 0), a2, voffA);
.Lboff_skip_H:
.LBB0_632:
	s_add_u32 s16, s22, 0xfffe0080
	s_addc_u32 s17, s23, -1
	s_add_i32 s52, 0, 0x10000
	s_cmp_eq_u32 s50, 4
	s_cselect_b32 s25, s15, s17
	s_cselect_b32 s24, s55, s16
	v_add_u32_e32 v0, s52, v205
	s_cselect_b32 s17, s13, s60
	s_cselect_b32 s16, s56, s57
	s_add_i32 s61, 0, 0x14000
	ds_read_b128 v[130:133], v0
	ds_read_b128 v[134:137], v0 offset:1024
	ds_read_b128 v[138:141], v0 offset:2048
	ds_read_b128 v[142:145], v0 offset:3072
	v_add_u32_e32 v0, s61, v205
	ds_read_b128 v[146:149], v0
	ds_read_b128 v[150:153], v0 offset:1024
	ds_read_b128 v[154:157], v0 offset:2048
	ds_read_b128 v[158:161], v0 offset:3072
	v_lshl_add_u64 v[210:211], s[22:23], 0, v[206:207]
	s_add_i32 m0, s31, 0xc000
	ds_read_b128 v[162:165], v226
	ds_read_b128 v[166:169], v226 offset:1024
	ds_read_b128 v[170:173], v226 offset:2048
	ds_read_b128 v[174:177], v226 offset:3072
	ds_read_b128 v[178:181], v226 offset:4096
	ds_read_b128 v[182:185], v226 offset:5120
	ds_read_b128 v[186:189], v226 offset:6144
	ds_read_b128 v[190:193], v226 offset:7168
	global_load_lds_dwordx4 v[210:211], off
	v_lshl_add_u64 v[210:211], s[22:23], 0, v[208:209]
	s_add_i32 m0, s31, 0xe000
	s_nop 0
	global_load_lds_dwordx4 v[210:211], off
	s_waitcnt vmcnt(8)
	s_waitcnt lgkmcnt(0)
	s_barrier
	v_mfma_f32_16x16x32_bf16 v[126:129], v[130:133], v[162:165], v[126:129]
	v_mfma_f32_16x16x32_bf16 v[122:125], v[138:141], v[162:165], v[122:125]
	v_mfma_f32_16x16x32_bf16 v[110:113], v[130:133], v[170:173], v[110:113]
	v_mfma_f32_16x16x32_bf16 v[106:109], v[138:141], v[170:173], v[106:109]
	v_mfma_f32_16x16x32_bf16 v[94:97], v[130:133], v[178:181], v[94:97]
	v_mfma_f32_16x16x32_bf16 v[90:93], v[138:141], v[178:181], v[90:93]
	v_mfma_f32_16x16x32_bf16 v[78:81], v[130:133], v[186:189], v[78:81]
	v_mfma_f32_16x16x32_bf16 v[74:77], v[138:141], v[186:189], v[74:77]
	v_mfma_f32_16x16x32_bf16 v[126:129], v[134:137], v[166:169], v[126:129]
	v_mfma_f32_16x16x32_bf16 v[122:125], v[142:145], v[166:169], v[122:125]
	v_mfma_f32_16x16x32_bf16 v[110:113], v[134:137], v[174:177], v[110:113]
	v_mfma_f32_16x16x32_bf16 v[106:109], v[142:145], v[174:177], v[106:109]
	v_mfma_f32_16x16x32_bf16 v[94:97], v[134:137], v[182:185], v[94:97]
	v_mfma_f32_16x16x32_bf16 v[90:93], v[142:145], v[182:185], v[90:93]
	v_mfma_f32_16x16x32_bf16 v[78:81], v[134:137], v[190:193], v[78:81]
	v_mfma_f32_16x16x32_bf16 v[74:77], v[142:145], v[190:193], v[74:77]
	v_mfma_f32_16x16x32_bf16 v[118:121], v[146:149], v[162:165], v[118:121]
	v_mfma_f32_16x16x32_bf16 v[114:117], v[154:157], v[162:165], v[114:117]
	v_mfma_f32_16x16x32_bf16 v[102:105], v[146:149], v[170:173], v[102:105]
	v_mfma_f32_16x16x32_bf16 v[98:101], v[154:157], v[170:173], v[98:101]
	v_mfma_f32_16x16x32_bf16 v[86:89], v[146:149], v[178:181], v[86:89]
	v_mfma_f32_16x16x32_bf16 v[82:85], v[154:157], v[178:181], v[82:85]
	v_mfma_f32_16x16x32_bf16 v[70:73], v[146:149], v[186:189], v[70:73]
	v_mfma_f32_16x16x32_bf16 v[66:69], v[154:157], v[186:189], v[66:69]
	v_mfma_f32_16x16x32_bf16 v[118:121], v[150:153], v[166:169], v[118:121]
	v_mfma_f32_16x16x32_bf16 v[114:117], v[158:161], v[166:169], v[114:117]
	v_mfma_f32_16x16x32_bf16 v[102:105], v[150:153], v[174:177], v[102:105]
	v_mfma_f32_16x16x32_bf16 v[98:101], v[158:161], v[174:177], v[98:101]
	v_mfma_f32_16x16x32_bf16 v[86:89], v[150:153], v[182:185], v[86:89]
	v_mfma_f32_16x16x32_bf16 v[82:85], v[158:161], v[182:185], v[82:85]
	v_mfma_f32_16x16x32_bf16 v[70:73], v[150:153], v[190:193], v[70:73]
	v_mfma_f32_16x16x32_bf16 v[66:69], v[158:161], v[190:193], v[66:69]
	s_barrier
	s_add_i32 s52, s52, s30
	v_lshl_add_u64 v[210:211], s[16:17], 0, v[198:199]
	s_mov_b32 m0, s52
	ds_read_b128 v[162:165], v226 offset:16384
	ds_read_b128 v[166:169], v226 offset:17408
	ds_read_b128 v[170:173], v226 offset:18432
	ds_read_b128 v[174:177], v226 offset:19456
	ds_read_b128 v[178:181], v226 offset:20480
	ds_read_b128 v[182:185], v226 offset:21504
	ds_read_b128 v[186:189], v226 offset:22528
	ds_read_b128 v[190:193], v226 offset:23552
	global_load_lds_dwordx4 v[210:211], off
	s_add_i32 m0, s52, 0x2000
	s_add_u32 s52, s16, 0x20000
	v_lshl_add_u64 v[212:213], s[16:17], 0, v[194:195]
	s_addc_u32 s53, s17, 0
	s_add_i32 s61, s61, s30
	global_load_lds_dwordx4 v[212:213], off
	v_lshl_add_u64 v[214:215], s[52:53], 0, v[198:199]
	s_mov_b32 m0, s61
	v_lshl_add_u64 v[216:217], s[24:25], 0, v[196:197]
	global_load_lds_dwordx4 v[214:215], off
	v_lshl_add_u64 v[214:215], s[52:53], 0, v[194:195]
	s_add_i32 m0, s61, 0x2000
	s_nop 0
	global_load_lds_dwordx4 v[214:215], off
	v_lshl_add_u64 v[214:215], s[24:25], 0, v[200:201]
	s_mov_b32 m0, s31
	s_nop 0
	global_load_lds_dwordx4 v[214:215], off
	s_mov_b32 m0, s34
	s_nop 0
	global_load_lds_dwordx4 v[216:217], off
	s_waitcnt vmcnt(8)
	s_waitcnt lgkmcnt(0)
	s_barrier
; #define PG8_STAGE(bufoff, gbase, voff) do { _Pragma("unroll") for (int _i = 0; _i < 2; ++_i) \
;         __builtin_amdgcn_global_load_lds((const unsigned*)((const char*)(gbase) + (voff)[_i]), (PG8_LAS unsigned*)(lds + (bufoff) + ldsw + _i * 8192), 16, 0, 0); } while (0)
; #define PG8_LDA(dst, b, h) do { _Pragma("unroll") for (int m = 0; m < 4; ++m) _Pragma("unroll") for (int k = 0; k < 2; ++k) dst[m][k] = *(const PG8_LAS bf16x8*)(lds + PG8_SA(b, h) + aoff + m * 2048 + k * 1024); } while (0)
; #define PG8_LDB(dst, b, h) do { _Pragma("unroll") for (int n = 0; n < 2; ++n) _Pragma("unroll") for (int k = 0; k < 2; ++k) dst[n][k] = *(const PG8_LAS bf16x8*)(lds + PG8_SB(b, h) + boff + n * 2048 + k * 1024); } while (0)
; #define PG8_MMA(ai, bj, At, Bt) do { __builtin_amdgcn_s_setprio(1); _Pragma("unroll") for (int m = 0; m < 4; ++m) _Pragma("unroll") for (int n = 0; n < 2; ++n) _Pragma("unroll") for (int k = 0; k < 2; ++k) \
;         acc[ai][bj][m][n] = __builtin_amdgcn_mfma_f32_16x16x32_bf16(Bt[n][k], At[m][k], acc[ai][bj][m][n], 0, 0, 0); __builtin_amdgcn_s_setprio(0); } while (0)
; #define PG8_WAIT_V(n) asm volatile("s_waitcnt vmcnt(" #n ")" ::: "memory")
; #define PG8_WAIT_L(n) asm volatile("s_waitcnt lgkmcnt(" #n ")" ::: "memory")
; #define PG8_BAR __builtin_amdgcn_s_barrier()
; #define PG8_SCHED __builtin_amdgcn_sched_barrier(0)
; template <class Epi, class Sched, bool ALIGN_EPI = false, bool SP2 = false>
; __device__ __forceinline__ void gemm_phase(PG8_LAS unsigned char* lds, const Gemm g, const Sched& S, const Epi& E) {
;     ...
;             PG8_WAIT_V(8); PG8_WAIT_L(0); PG8_BAR; PG8_MMA(1, 0, At, B0); PG8_MMA(1, 1, At, B1); PG8_BAR; PG8_SCHED;
;             PG8_LDB(B0, 1, 0); PG8_LDB(B1, 1, 1); PG8_SCHED; PG8_LDA(At, 1, 0); PG8_STAGE(PG8_SA(0, 1), a2 + hstep, voffA);
;             PG8_WAIT_V(8); PG8_WAIT_L(0); PG8_BAR; PG8_MMA(0, 0, At, B0); PG8_MMA(0, 1, At, B1); PG8_BAR; PG8_SCHED;
	v_mfma_f32_16x16x32_bf16 v[62:65], v[130:133], v[162:165], v[62:65]
	v_mfma_f32_16x16x32_bf16 v[58:61], v[138:141], v[162:165], v[58:61]
	v_mfma_f32_16x16x32_bf16 v[46:49], v[130:133], v[170:173], v[46:49]
	v_mfma_f32_16x16x32_bf16 v[42:45], v[138:141], v[170:173], v[42:45]
	v_mfma_f32_16x16x32_bf16 v[30:33], v[130:133], v[178:181], v[30:33]
	v_mfma_f32_16x16x32_bf16 v[26:29], v[138:141], v[178:181], v[26:29]
	v_mfma_f32_16x16x32_bf16 v[14:17], v[130:133], v[186:189], v[14:17]
	v_mfma_f32_16x16x32_bf16 v[10:13], v[138:141], v[186:189], v[10:13]
	v_mfma_f32_16x16x32_bf16 v[62:65], v[134:137], v[166:169], v[62:65]
	v_mfma_f32_16x16x32_bf16 v[58:61], v[142:145], v[166:169], v[58:61]
	v_mfma_f32_16x16x32_bf16 v[46:49], v[134:137], v[174:177], v[46:49]
	v_mfma_f32_16x16x32_bf16 v[42:45], v[142:145], v[174:177], v[42:45]
	v_mfma_f32_16x16x32_bf16 v[30:33], v[134:137], v[182:185], v[30:33]
	v_mfma_f32_16x16x32_bf16 v[26:29], v[142:145], v[182:185], v[26:29]
	v_mfma_f32_16x16x32_bf16 v[14:17], v[134:137], v[190:193], v[14:17]
	v_mfma_f32_16x16x32_bf16 v[10:13], v[142:145], v[190:193], v[10:13]
	v_mfma_f32_16x16x32_bf16 v[54:57], v[146:149], v[162:165], v[54:57]
	v_mfma_f32_16x16x32_bf16 v[50:53], v[154:157], v[162:165], v[50:53]
	v_mfma_f32_16x16x32_bf16 v[38:41], v[146:149], v[170:173], v[38:41]
	v_mfma_f32_16x16x32_bf16 v[34:37], v[154:157], v[170:173], v[34:37]
	v_mfma_f32_16x16x32_bf16 v[22:25], v[146:149], v[178:181], v[22:25]
	v_mfma_f32_16x16x32_bf16 v[18:21], v[154:157], v[178:181], v[18:21]
	v_mfma_f32_16x16x32_bf16 v[6:9], v[146:149], v[186:189], v[6:9]
	v_mfma_f32_16x16x32_bf16 v[2:5], v[154:157], v[186:189], v[2:5]
	v_mfma_f32_16x16x32_bf16 v[54:57], v[150:153], v[166:169], v[54:57]
	v_mfma_f32_16x16x32_bf16 v[50:53], v[158:161], v[166:169], v[50:53]
	v_mfma_f32_16x16x32_bf16 v[38:41], v[150:153], v[174:177], v[38:41]
	v_mfma_f32_16x16x32_bf16 v[34:37], v[158:161], v[174:177], v[34:37]
	v_mfma_f32_16x16x32_bf16 v[22:25], v[150:153], v[182:185], v[22:25]
	v_mfma_f32_16x16x32_bf16 v[18:21], v[158:161], v[182:185], v[18:21]
	v_mfma_f32_16x16x32_bf16 v[6:9], v[150:153], v[190:193], v[6:9]
	v_mfma_f32_16x16x32_bf16 v[2:5], v[158:161], v[190:193], v[2:5]
	s_barrier
	s_add_i32 s52, 0, 0x18000
	v_add_u32_e32 v0, s52, v205
	s_add_i32 s53, 0, 0x1c000
	ds_read_b128 v[130:133], v0
	ds_read_b128 v[134:137], v0 offset:1024
	ds_read_b128 v[138:141], v0 offset:2048
	ds_read_b128 v[142:145], v0 offset:3072
	v_add_u32_e32 v0, s53, v205
	ds_read_b128 v[146:149], v0
	ds_read_b128 v[150:153], v0 offset:1024
	ds_read_b128 v[154:157], v0 offset:2048
	ds_read_b128 v[158:161], v0 offset:3072
	s_add_u32 s24, s24, 0x20000
	s_addc_u32 s25, s25, 0
	s_mov_b32 m0, s35
	v_lshl_add_u64 v[218:219], s[24:25], 0, v[200:201]
	ds_read_b128 v[162:165], v226 offset:32768
	ds_read_b128 v[166:169], v226 offset:33792
	ds_read_b128 v[170:173], v226 offset:34816
	ds_read_b128 v[174:177], v226 offset:35840
	ds_read_b128 v[178:181], v226 offset:36864
	ds_read_b128 v[182:185], v226 offset:37888
	ds_read_b128 v[186:189], v226 offset:38912
	ds_read_b128 v[190:193], v226 offset:39936
	global_load_lds_dwordx4 v[218:219], off
	v_lshl_add_u64 v[218:219], s[24:25], 0, v[196:197]
	s_mov_b32 m0, s36
	s_nop 0
	global_load_lds_dwordx4 v[218:219], off
	s_waitcnt vmcnt(8)
	s_waitcnt lgkmcnt(0)
	s_barrier
	v_mfma_f32_16x16x32_bf16 v[126:129], v[130:133], v[162:165], v[126:129]
	v_mfma_f32_16x16x32_bf16 v[122:125], v[138:141], v[162:165], v[122:125]
	v_mfma_f32_16x16x32_bf16 v[110:113], v[130:133], v[170:173], v[110:113]
	v_mfma_f32_16x16x32_bf16 v[106:109], v[138:141], v[170:173], v[106:109]
	v_mfma_f32_16x16x32_bf16 v[94:97], v[130:133], v[178:181], v[94:97]
	v_mfma_f32_16x16x32_bf16 v[90:93], v[138:141], v[178:181], v[90:93]
	v_mfma_f32_16x16x32_bf16 v[78:81], v[130:133], v[186:189], v[78:81]
	v_mfma_f32_16x16x32_bf16 v[74:77], v[138:141], v[186:189], v[74:77]
	v_mfma_f32_16x16x32_bf16 v[126:129], v[134:137], v[166:169], v[126:129]
	v_mfma_f32_16x16x32_bf16 v[122:125], v[142:145], v[166:169], v[122:125]
	v_mfma_f32_16x16x32_bf16 v[110:113], v[134:137], v[174:177], v[110:113]
	v_mfma_f32_16x16x32_bf16 v[106:109], v[142:145], v[174:177], v[106:109]
	v_mfma_f32_16x16x32_bf16 v[94:97], v[134:137], v[182:185], v[94:97]
	v_mfma_f32_16x16x32_bf16 v[90:93], v[142:145], v[182:185], v[90:93]
	v_mfma_f32_16x16x32_bf16 v[78:81], v[134:137], v[190:193], v[78:81]
	v_mfma_f32_16x16x32_bf16 v[74:77], v[142:145], v[190:193], v[74:77]
	v_mfma_f32_16x16x32_bf16 v[118:121], v[146:149], v[162:165], v[118:121]
	v_mfma_f32_16x16x32_bf16 v[114:117], v[154:157], v[162:165], v[114:117]
	v_mfma_f32_16x16x32_bf16 v[102:105], v[146:149], v[170:173], v[102:105]
	v_mfma_f32_16x16x32_bf16 v[98:101], v[154:157], v[170:173], v[98:101]
	v_mfma_f32_16x16x32_bf16 v[86:89], v[146:149], v[178:181], v[86:89]
	v_mfma_f32_16x16x32_bf16 v[82:85], v[154:157], v[178:181], v[82:85]
	v_mfma_f32_16x16x32_bf16 v[70:73], v[146:149], v[186:189], v[70:73]
	v_mfma_f32_16x16x32_bf16 v[66:69], v[154:157], v[186:189], v[66:69]
	v_mfma_f32_16x16x32_bf16 v[118:121], v[150:153], v[166:169], v[118:121]
	v_mfma_f32_16x16x32_bf16 v[114:117], v[158:161], v[166:169], v[114:117]
	v_mfma_f32_16x16x32_bf16 v[102:105], v[150:153], v[174:177], v[102:105]
	v_mfma_f32_16x16x32_bf16 v[98:101], v[158:161], v[174:177], v[98:101]
	v_mfma_f32_16x16x32_bf16 v[86:89], v[150:153], v[182:185], v[86:89]
	v_mfma_f32_16x16x32_bf16 v[82:85], v[158:161], v[182:185], v[82:85]
	v_mfma_f32_16x16x32_bf16 v[70:73], v[150:153], v[190:193], v[70:73]
	v_mfma_f32_16x16x32_bf16 v[66:69], v[158:161], v[190:193], v[66:69]
	s_barrier
; #define PG8_STAGE(bufoff, gbase, voff) do { _Pragma("unroll") for (int _i = 0; _i < 2; ++_i) \
;         __builtin_amdgcn_global_load_lds((const unsigned*)((const char*)(gbase) + (voff)[_i]), (PG8_LAS unsigned*)(lds + (bufoff) + ldsw + _i * 8192), 16, 0, 0); } while (0)
; #define PG8_LDA(dst, b, h) do { _Pragma("unroll") for (int m = 0; m < 4; ++m) _Pragma("unroll") for (int k = 0; k < 2; ++k) dst[m][k] = *(const PG8_LAS bf16x8*)(lds + PG8_SA(b, h) + aoff + m * 2048 + k * 1024); } while (0)
; #define PG8_MMA(ai, bj, At, Bt) do { __builtin_amdgcn_s_setprio(1); _Pragma("unroll") for (int m = 0; m < 4; ++m) _Pragma("unroll") for (int n = 0; n < 2; ++n) _Pragma("unroll") for (int k = 0; k < 2; ++k) \
;         acc[ai][bj][m][n] = __builtin_amdgcn_mfma_f32_16x16x32_bf16(Bt[n][k], At[m][k], acc[ai][bj][m][n], 0, 0, 0); __builtin_amdgcn_s_setprio(0); } while (0)
; #define PG8_WAIT_V(n) asm volatile("s_waitcnt vmcnt(" #n ")" ::: "memory")
; #define PG8_WAIT_L(n) asm volatile("s_waitcnt lgkmcnt(" #n ")" ::: "memory")
; #define PG8_BAR __builtin_amdgcn_s_barrier()
; #define PG8_SCHED __builtin_amdgcn_sched_barrier(0)
; template <class Epi, class Sched, bool ALIGN_EPI = false, bool SP2 = false>
; __device__ __forceinline__ void gemm_phase(PG8_LAS unsigned char* lds, const Gemm g, const Sched& S, const Epi& E) {
;     ...
;         for (int t = 0; t < nt; t += 2) {
;     ...
;             PG8_LDA(At, 1, 1); PG8_STAGE(PG8_SB(1, 0), b3, voffB); PG8_STAGE(PG8_SB(1, 1), b3 + hstep, voffB); PG8_STAGE(PG8_SA(1, 0), a3, voffA);
;             PG8_WAIT_V(8); PG8_WAIT_L(0); PG8_BAR; PG8_MMA(1, 0, At, B0); PG8_MMA(1, 1, At, B1); PG8_BAR; PG8_SCHED;
	s_add_i32 s24, s52, s30
	v_lshl_add_u64 v[210:211], v[210:211], 0, s[94:95]
	s_mov_b32 m0, s24
	ds_read_b128 v[162:165], v226 offset:49152
	ds_read_b128 v[166:169], v226 offset:50176
	ds_read_b128 v[170:173], v226 offset:51200
	ds_read_b128 v[174:177], v226 offset:52224
	ds_read_b128 v[178:181], v226 offset:53248
	ds_read_b128 v[182:185], v226 offset:54272
	ds_read_b128 v[186:189], v226 offset:55296
	ds_read_b128 v[190:193], v226 offset:56320
	global_load_lds_dwordx4 v[210:211], off
	s_add_i32 m0, s24, 0x2000
	s_add_u32 s16, s16, 0x20080
	v_lshl_add_u64 v[210:211], v[212:213], 0, s[94:95]
	s_addc_u32 s17, s17, 0
	s_add_i32 s24, s53, s30
	global_load_lds_dwordx4 v[210:211], off
	v_lshl_add_u64 v[210:211], s[16:17], 0, v[198:199]
	s_mov_b32 m0, s24
	s_nop 0
	global_load_lds_dwordx4 v[210:211], off
	v_lshl_add_u64 v[210:211], s[16:17], 0, v[194:195]
	s_add_i32 m0, s24, 0x2000
	s_nop 0
	global_load_lds_dwordx4 v[210:211], off
	v_lshl_add_u64 v[210:211], v[214:215], 0, s[94:95]
	s_mov_b32 m0, s37
	s_nop 0
	global_load_lds_dwordx4 v[210:211], off
	v_lshl_add_u64 v[210:211], v[216:217], 0, s[94:95]
	s_mov_b32 m0, s38
	s_nop 0
	global_load_lds_dwordx4 v[210:211], off
	s_waitcnt vmcnt(8)
	s_waitcnt lgkmcnt(0)
	s_barrier
	v_mfma_f32_16x16x32_bf16 v[62:65], v[130:133], v[162:165], v[62:65]
	v_mfma_f32_16x16x32_bf16 v[58:61], v[138:141], v[162:165], v[58:61]
	v_mfma_f32_16x16x32_bf16 v[46:49], v[130:133], v[170:173], v[46:49]
	v_mfma_f32_16x16x32_bf16 v[42:45], v[138:141], v[170:173], v[42:45]
	v_mfma_f32_16x16x32_bf16 v[30:33], v[130:133], v[178:181], v[30:33]
	v_mfma_f32_16x16x32_bf16 v[26:29], v[138:141], v[178:181], v[26:29]
	v_mfma_f32_16x16x32_bf16 v[14:17], v[130:133], v[186:189], v[14:17]
	v_mfma_f32_16x16x32_bf16 v[10:13], v[138:141], v[186:189], v[10:13]
	v_mfma_f32_16x16x32_bf16 v[62:65], v[134:137], v[166:169], v[62:65]
	v_mfma_f32_16x16x32_bf16 v[58:61], v[142:145], v[166:169], v[58:61]
	v_mfma_f32_16x16x32_bf16 v[46:49], v[134:137], v[174:177], v[46:49]
	v_mfma_f32_16x16x32_bf16 v[42:45], v[142:145], v[174:177], v[42:45]
	v_mfma_f32_16x16x32_bf16 v[30:33], v[134:137], v[182:185], v[30:33]
	v_mfma_f32_16x16x32_bf16 v[26:29], v[142:145], v[182:185], v[26:29]
	v_mfma_f32_16x16x32_bf16 v[14:17], v[134:137], v[190:193], v[14:17]
	v_mfma_f32_16x16x32_bf16 v[10:13], v[142:145], v[190:193], v[10:13]
	v_mfma_f32_16x16x32_bf16 v[54:57], v[146:149], v[162:165], v[54:57]
	v_mfma_f32_16x16x32_bf16 v[50:53], v[154:157], v[162:165], v[50:53]
	v_mfma_f32_16x16x32_bf16 v[38:41], v[146:149], v[170:173], v[38:41]
	v_mfma_f32_16x16x32_bf16 v[34:37], v[154:157], v[170:173], v[34:37]
	v_mfma_f32_16x16x32_bf16 v[22:25], v[146:149], v[178:181], v[22:25]
	v_mfma_f32_16x16x32_bf16 v[18:21], v[154:157], v[178:181], v[18:21]
	v_mfma_f32_16x16x32_bf16 v[6:9], v[146:149], v[186:189], v[6:9]
	v_mfma_f32_16x16x32_bf16 v[2:5], v[154:157], v[186:189], v[2:5]
	v_mfma_f32_16x16x32_bf16 v[54:57], v[150:153], v[166:169], v[54:57]
	v_mfma_f32_16x16x32_bf16 v[50:53], v[158:161], v[166:169], v[50:53]
	v_mfma_f32_16x16x32_bf16 v[38:41], v[150:153], v[174:177], v[38:41]
	v_mfma_f32_16x16x32_bf16 v[34:37], v[158:161], v[174:177], v[34:37]
	v_mfma_f32_16x16x32_bf16 v[22:25], v[150:153], v[182:185], v[22:25]
	v_mfma_f32_16x16x32_bf16 v[18:21], v[158:161], v[182:185], v[18:21]
	v_mfma_f32_16x16x32_bf16 v[6:9], v[150:153], v[190:193], v[6:9]
	v_mfma_f32_16x16x32_bf16 v[2:5], v[158:161], v[190:193], v[2:5]
	s_barrier
	s_add_i32 s50, s50, 2
	s_add_u32 s22, s22, 0x100
	s_addc_u32 s23, s23, 0
	s_add_u32 s57, s57, 0x100
	s_addc_u32 s60, s60, 0
	s_cmp_gt_u32 s50, 5
	s_cbranch_scc0 .LBB0_632
	s_and_b64 vcc, exec, s[10:11]
	s_cbranch_vccz .LBB0_635
	s_barrier

; #define PG8_STAGE(bufoff, gbase, voff) do { _Pragma("unroll") for (int _i = 0; _i < 2; ++_i) \
;         __builtin_amdgcn_global_load_lds((const unsigned*)((const char*)(gbase) + (voff)[_i]), (PG8_LAS unsigned*)(lds + (bufoff) + ldsw + _i * 8192), 16, 0, 0); } while (0)
; #define PG8_LDA(dst, b, h) do { _Pragma("unroll") for (int m = 0; m < 4; ++m) _Pragma("unroll") for (int k = 0; k < 2; ++k) dst[m][k] = *(const PG8_LAS bf16x8*)(lds + PG8_SA(b, h) + aoff + m * 2048 + k * 1024); } while (0)
; #define PG8_LDB(dst, b, h) do { _Pragma("unroll") for (int n = 0; n < 2; ++n) _Pragma("unroll") for (int k = 0; k < 2; ++k) dst[n][k] = *(const PG8_LAS bf16x8*)(lds + PG8_SB(b, h) + boff + n * 2048 + k * 1024); } while (0)
; #define PG8_MMA(ai, bj, At, Bt) do { __builtin_amdgcn_s_setprio(1); _Pragma("unroll") for (int m = 0; m < 4; ++m) _Pragma("unroll") for (int n = 0; n < 2; ++n) _Pragma("unroll") for (int k = 0; k < 2; ++k) \
;         acc[ai][bj][m][n] = __builtin_amdgcn_mfma_f32_16x16x32_bf16(Bt[n][k], At[m][k], acc[ai][bj][m][n], 0, 0, 0); __builtin_amdgcn_s_setprio(0); } while (0)
; #define PG8_WAIT_V(n) asm volatile("s_waitcnt vmcnt(" #n ")" ::: "memory")
; #define PG8_WAIT_L(n) asm volatile("s_waitcnt lgkmcnt(" #n ")" ::: "memory")
; #define PG8_BAR __builtin_amdgcn_s_barrier()
; #define PG8_SCHED __builtin_amdgcn_sched_barrier(0)
; template <class Epi, class Sched, bool ALIGN_EPI = false, bool SP2 = false>
; __device__ __forceinline__ void gemm_phase(PG8_LAS unsigned char* lds, const Gemm g, const Sched& S, const Epi& E) {
;     ...
;             const bool last = (t == nt - 2);
;             const char* a1 = cA + (size_t)(t + 1) * kstep;
;             const char* a2 = last ? nA : cA + (size_t)(t + 2) * kstep; const char* b2 = last ? nB : cB + (size_t)(t + 2) * kstep;
;             const char* a3 = a2 + kstep; const char* b3 = b2 + kstep;
;             if (last && has_next) S.a_ready(nxt);
;             if constexpr (SP2) {
;             PG8_LDB(B0, 0, 0); PG8_LDB(B1, 0, 1); PG8_SCHED; PG8_LDA(At, 0, 0); PG8_STAGE(PG8_SA(1, 1), a1 + hstep, voffA);
;             PG8_WAIT_V(8); PG8_WAIT_L(0); PG8_BAR; PG8_MMA(0, 0, At, B0); PG8_MMA(0, 1, At, B1); PG8_BAR; PG8_SCHED;
;             PG8_LDA(At, 0, 1); PG8_STAGE(PG8_SB(0, 0), b2, voffB); PG8_STAGE(PG8_SB(0, 1), b2 + hstep, voffB); PG8_STAGE(PG8_SA(0, 0), a2, voffA);
.Lboff_skip_I:
.LBB0_697:
	s_add_u32 s16, s20, 0xfffc0080
	s_addc_u32 s17, s21, -1
	s_add_i32 s52, 0, 0x10000
	s_cmp_eq_u32 s50, 12
	s_cselect_b32 s23, s13, s17
	s_cselect_b32 s22, s39, s16
	s_cselect_b32 s17, s11, s56
	s_cselect_b32 s16, s46, s55
	s_add_i32 s57, 0, 0x14000
	v_add_u32_e32 v142, s52, v231
	v_add_u32_e32 v158, s57, v231
	ds_read_b128 v[130:133], v142
	ds_read_b128 v[134:137], v142 offset:1024
	ds_read_b128 v[138:141], v142 offset:2048
	ds_read_b128 v[142:145], v142 offset:3072
	ds_read_b128 v[146:149], v158
	ds_read_b128 v[150:153], v158 offset:1024
	ds_read_b128 v[154:157], v158 offset:2048
	ds_read_b128 v[158:161], v158 offset:3072
	v_lshl_add_u64 v[206:207], s[20:21], 0, v[202:203]
	s_add_i32 m0, s29, 0xc000
	ds_read_b128 v[162:165], v232
	ds_read_b128 v[166:169], v232 offset:1024
	ds_read_b128 v[170:173], v232 offset:2048
	ds_read_b128 v[174:177], v232 offset:3072
	ds_read_b128 v[178:181], v232 offset:4096
	ds_read_b128 v[182:185], v232 offset:5120
	ds_read_b128 v[186:189], v232 offset:6144
	ds_read_b128 v[190:193], v232 offset:7168
	global_load_lds_dwordx4 v[206:207], off
	v_lshl_add_u64 v[206:207], s[20:21], 0, v[204:205]
	s_add_i32 m0, s29, 0xe000
	s_nop 0
	global_load_lds_dwordx4 v[206:207], off
	s_waitcnt vmcnt(8)
	s_waitcnt lgkmcnt(0)
	s_barrier
	v_mfma_f32_16x16x32_bf16 v[126:129], v[130:133], v[162:165], v[126:129]
	v_mfma_f32_16x16x32_bf16 v[122:125], v[138:141], v[162:165], v[122:125]
	v_mfma_f32_16x16x32_bf16 v[114:117], v[130:133], v[170:173], v[114:117]
	v_mfma_f32_16x16x32_bf16 v[106:109], v[138:141], v[170:173], v[106:109]
	v_mfma_f32_16x16x32_bf16 v[98:101], v[130:133], v[178:181], v[98:101]
	v_mfma_f32_16x16x32_bf16 v[90:93], v[138:141], v[178:181], v[90:93]
	v_mfma_f32_16x16x32_bf16 v[82:85], v[130:133], v[186:189], v[82:85]
	v_mfma_f32_16x16x32_bf16 v[74:77], v[138:141], v[186:189], v[74:77]
	v_mfma_f32_16x16x32_bf16 v[126:129], v[134:137], v[166:169], v[126:129]
	v_mfma_f32_16x16x32_bf16 v[122:125], v[142:145], v[166:169], v[122:125]
	v_mfma_f32_16x16x32_bf16 v[114:117], v[134:137], v[174:177], v[114:117]
	v_mfma_f32_16x16x32_bf16 v[106:109], v[142:145], v[174:177], v[106:109]
	v_mfma_f32_16x16x32_bf16 v[98:101], v[134:137], v[182:185], v[98:101]
	v_mfma_f32_16x16x32_bf16 v[90:93], v[142:145], v[182:185], v[90:93]
	v_mfma_f32_16x16x32_bf16 v[82:85], v[134:137], v[190:193], v[82:85]
	v_mfma_f32_16x16x32_bf16 v[74:77], v[142:145], v[190:193], v[74:77]
	v_mfma_f32_16x16x32_bf16 v[118:121], v[146:149], v[162:165], v[118:121]
	v_mfma_f32_16x16x32_bf16 v[110:113], v[154:157], v[162:165], v[110:113]
	v_mfma_f32_16x16x32_bf16 v[102:105], v[146:149], v[170:173], v[102:105]
	v_mfma_f32_16x16x32_bf16 v[94:97], v[154:157], v[170:173], v[94:97]
	v_mfma_f32_16x16x32_bf16 v[86:89], v[146:149], v[178:181], v[86:89]
	v_mfma_f32_16x16x32_bf16 v[78:81], v[154:157], v[178:181], v[78:81]
	v_mfma_f32_16x16x32_bf16 v[70:73], v[146:149], v[186:189], v[70:73]
	v_mfma_f32_16x16x32_bf16 v[66:69], v[154:157], v[186:189], v[66:69]
	v_mfma_f32_16x16x32_bf16 v[118:121], v[150:153], v[166:169], v[118:121]
	v_mfma_f32_16x16x32_bf16 v[110:113], v[158:161], v[166:169], v[110:113]
	v_mfma_f32_16x16x32_bf16 v[102:105], v[150:153], v[174:177], v[102:105]
	v_mfma_f32_16x16x32_bf16 v[94:97], v[158:161], v[174:177], v[94:97]
	v_mfma_f32_16x16x32_bf16 v[86:89], v[150:153], v[182:185], v[86:89]
	v_mfma_f32_16x16x32_bf16 v[78:81], v[158:161], v[182:185], v[78:81]
	v_mfma_f32_16x16x32_bf16 v[70:73], v[150:153], v[190:193], v[70:73]
	v_mfma_f32_16x16x32_bf16 v[66:69], v[158:161], v[190:193], v[66:69]
	s_barrier
	s_add_i32 s52, s52, s28
	v_lshl_add_u64 v[206:207], s[16:17], 0, v[198:199]
	s_mov_b32 m0, s52
	ds_read_b128 v[162:165], v232 offset:16384
	ds_read_b128 v[166:169], v232 offset:17408
	ds_read_b128 v[170:173], v232 offset:18432
	ds_read_b128 v[174:177], v232 offset:19456
	ds_read_b128 v[178:181], v232 offset:20480
	ds_read_b128 v[182:185], v232 offset:21504
	ds_read_b128 v[186:189], v232 offset:22528
	ds_read_b128 v[190:193], v232 offset:23552
	global_load_lds_dwordx4 v[206:207], off
	s_add_i32 m0, s52, 0x2000
	s_add_u32 s52, s16, 0x40000
	v_lshl_add_u64 v[208:209], s[16:17], 0, v[194:195]
	s_addc_u32 s53, s17, 0
	s_add_i32 s57, s57, s28
	global_load_lds_dwordx4 v[208:209], off
	v_lshl_add_u64 v[210:211], s[52:53], 0, v[198:199]
	s_mov_b32 m0, s57
	v_lshl_add_u64 v[212:213], s[22:23], 0, v[196:197]
	global_load_lds_dwordx4 v[210:211], off
	v_lshl_add_u64 v[210:211], s[52:53], 0, v[194:195]
	s_add_i32 m0, s57, 0x2000
	s_nop 0
	global_load_lds_dwordx4 v[210:211], off
	v_lshl_add_u64 v[210:211], s[22:23], 0, v[200:201]
	s_mov_b32 m0, s29
	s_nop 0
	global_load_lds_dwordx4 v[210:211], off
	s_mov_b32 m0, s30
	s_nop 0
	global_load_lds_dwordx4 v[212:213], off
	s_waitcnt vmcnt(8)
	s_waitcnt lgkmcnt(0)
	s_barrier
; #define PG8_STAGE(bufoff, gbase, voff) do { _Pragma("unroll") for (int _i = 0; _i < 2; ++_i) \
;         __builtin_amdgcn_global_load_lds((const unsigned*)((const char*)(gbase) + (voff)[_i]), (PG8_LAS unsigned*)(lds + (bufoff) + ldsw + _i * 8192), 16, 0, 0); } while (0)
; #define PG8_LDA(dst, b, h) do { _Pragma("unroll") for (int m = 0; m < 4; ++m) _Pragma("unroll") for (int k = 0; k < 2; ++k) dst[m][k] = *(const PG8_LAS bf16x8*)(lds + PG8_SA(b, h) + aoff + m * 2048 + k * 1024); } while (0)
; #define PG8_LDB(dst, b, h) do { _Pragma("unroll") for (int n = 0; n < 2; ++n) _Pragma("unroll") for (int k = 0; k < 2; ++k) dst[n][k] = *(const PG8_LAS bf16x8*)(lds + PG8_SB(b, h) + boff + n * 2048 + k * 1024); } while (0)
; #define PG8_MMA(ai, bj, At, Bt) do { __builtin_amdgcn_s_setprio(1); _Pragma("unroll") for (int m = 0; m < 4; ++m) _Pragma("unroll") for (int n = 0; n < 2; ++n) _Pragma("unroll") for (int k = 0; k < 2; ++k) \
;         acc[ai][bj][m][n] = __builtin_amdgcn_mfma_f32_16x16x32_bf16(Bt[n][k], At[m][k], acc[ai][bj][m][n], 0, 0, 0); __builtin_amdgcn_s_setprio(0); } while (0)
; #define PG8_WAIT_V(n) asm volatile("s_waitcnt vmcnt(" #n ")" ::: "memory")
; #define PG8_WAIT_L(n) asm volatile("s_waitcnt lgkmcnt(" #n ")" ::: "memory")
; #define PG8_BAR __builtin_amdgcn_s_barrier()
; #define PG8_SCHED __builtin_amdgcn_sched_barrier(0)
; template <class Epi, class Sched, bool ALIGN_EPI = false, bool SP2 = false>
; __device__ __forceinline__ void gemm_phase(PG8_LAS unsigned char* lds, const Gemm g, const Sched& S, const Epi& E) {
;     ...
;             PG8_WAIT_V(8); PG8_WAIT_L(0); PG8_BAR; PG8_MMA(1, 0, At, B0); PG8_MMA(1, 1, At, B1); PG8_BAR; PG8_SCHED;
;             PG8_LDB(B0, 1, 0); PG8_LDB(B1, 1, 1); PG8_SCHED; PG8_LDA(At, 1, 0); PG8_STAGE(PG8_SA(0, 1), a2 + hstep, voffA);
;             PG8_WAIT_V(8); PG8_WAIT_L(0); PG8_BAR; PG8_MMA(0, 0, At, B0); PG8_MMA(0, 1, At, B1); PG8_BAR; PG8_SCHED;
	v_mfma_f32_16x16x32_bf16 v[62:65], v[130:133], v[162:165], v[62:65]
	v_mfma_f32_16x16x32_bf16 v[58:61], v[138:141], v[162:165], v[58:61]
	v_mfma_f32_16x16x32_bf16 v[50:53], v[130:133], v[170:173], v[50:53]
	v_mfma_f32_16x16x32_bf16 v[42:45], v[138:141], v[170:173], v[42:45]
	v_mfma_f32_16x16x32_bf16 v[34:37], v[130:133], v[178:181], v[34:37]
	v_mfma_f32_16x16x32_bf16 v[26:29], v[138:141], v[178:181], v[26:29]
	v_mfma_f32_16x16x32_bf16 v[18:21], v[130:133], v[186:189], v[18:21]
	v_mfma_f32_16x16x32_bf16 v[10:13], v[138:141], v[186:189], v[10:13]
	v_mfma_f32_16x16x32_bf16 v[62:65], v[134:137], v[166:169], v[62:65]
	v_mfma_f32_16x16x32_bf16 v[58:61], v[142:145], v[166:169], v[58:61]
	v_mfma_f32_16x16x32_bf16 v[50:53], v[134:137], v[174:177], v[50:53]
	v_mfma_f32_16x16x32_bf16 v[42:45], v[142:145], v[174:177], v[42:45]
	v_mfma_f32_16x16x32_bf16 v[34:37], v[134:137], v[182:185], v[34:37]
	v_mfma_f32_16x16x32_bf16 v[26:29], v[142:145], v[182:185], v[26:29]
	v_mfma_f32_16x16x32_bf16 v[18:21], v[134:137], v[190:193], v[18:21]
	v_mfma_f32_16x16x32_bf16 v[10:13], v[142:145], v[190:193], v[10:13]
	v_mfma_f32_16x16x32_bf16 v[54:57], v[146:149], v[162:165], v[54:57]
	v_mfma_f32_16x16x32_bf16 v[46:49], v[154:157], v[162:165], v[46:49]
	v_mfma_f32_16x16x32_bf16 v[38:41], v[146:149], v[170:173], v[38:41]
	v_mfma_f32_16x16x32_bf16 v[30:33], v[154:157], v[170:173], v[30:33]
	v_mfma_f32_16x16x32_bf16 v[22:25], v[146:149], v[178:181], v[22:25]
	v_mfma_f32_16x16x32_bf16 v[14:17], v[154:157], v[178:181], v[14:17]
	v_mfma_f32_16x16x32_bf16 v[6:9], v[146:149], v[186:189], v[6:9]
	v_mfma_f32_16x16x32_bf16 v[2:5], v[154:157], v[186:189], v[2:5]
	v_mfma_f32_16x16x32_bf16 v[54:57], v[150:153], v[166:169], v[54:57]
	v_mfma_f32_16x16x32_bf16 v[46:49], v[158:161], v[166:169], v[46:49]
	v_mfma_f32_16x16x32_bf16 v[38:41], v[150:153], v[174:177], v[38:41]
	v_mfma_f32_16x16x32_bf16 v[30:33], v[158:161], v[174:177], v[30:33]
	v_mfma_f32_16x16x32_bf16 v[22:25], v[150:153], v[182:185], v[22:25]
	v_mfma_f32_16x16x32_bf16 v[14:17], v[158:161], v[182:185], v[14:17]
	v_mfma_f32_16x16x32_bf16 v[6:9], v[150:153], v[190:193], v[6:9]
	v_mfma_f32_16x16x32_bf16 v[2:5], v[158:161], v[190:193], v[2:5]
	s_barrier
	s_add_i32 s52, 0, 0x18000
	s_add_i32 s53, 0, 0x1c000
	v_add_u32_e32 v142, s52, v231
	v_add_u32_e32 v158, s53, v231
	ds_read_b128 v[130:133], v142
	ds_read_b128 v[134:137], v142 offset:1024
	ds_read_b128 v[138:141], v142 offset:2048
	ds_read_b128 v[142:145], v142 offset:3072
	ds_read_b128 v[146:149], v158
	ds_read_b128 v[150:153], v158 offset:1024
	ds_read_b128 v[154:157], v158 offset:2048
	ds_read_b128 v[158:161], v158 offset:3072
	s_add_u32 s22, s22, 0x40000
	s_addc_u32 s23, s23, 0
	s_mov_b32 m0, s31
	v_lshl_add_u64 v[214:215], s[22:23], 0, v[200:201]
	ds_read_b128 v[162:165], v232 offset:32768
	ds_read_b128 v[166:169], v232 offset:33792
	ds_read_b128 v[170:173], v232 offset:34816
	ds_read_b128 v[174:177], v232 offset:35840
	ds_read_b128 v[178:181], v232 offset:36864
	ds_read_b128 v[182:185], v232 offset:37888
	ds_read_b128 v[186:189], v232 offset:38912
	ds_read_b128 v[190:193], v232 offset:39936
	global_load_lds_dwordx4 v[214:215], off
	v_lshl_add_u64 v[214:215], s[22:23], 0, v[196:197]
	s_mov_b32 m0, s34
	s_nop 0
	global_load_lds_dwordx4 v[214:215], off
	s_waitcnt vmcnt(8)
	s_waitcnt lgkmcnt(0)
	s_barrier
	v_mfma_f32_16x16x32_bf16 v[126:129], v[130:133], v[162:165], v[126:129]
	v_mfma_f32_16x16x32_bf16 v[122:125], v[138:141], v[162:165], v[122:125]
	v_mfma_f32_16x16x32_bf16 v[114:117], v[130:133], v[170:173], v[114:117]
	v_mfma_f32_16x16x32_bf16 v[106:109], v[138:141], v[170:173], v[106:109]
	v_mfma_f32_16x16x32_bf16 v[98:101], v[130:133], v[178:181], v[98:101]
	v_mfma_f32_16x16x32_bf16 v[90:93], v[138:141], v[178:181], v[90:93]
	v_mfma_f32_16x16x32_bf16 v[82:85], v[130:133], v[186:189], v[82:85]
	v_mfma_f32_16x16x32_bf16 v[74:77], v[138:141], v[186:189], v[74:77]
	v_mfma_f32_16x16x32_bf16 v[126:129], v[134:137], v[166:169], v[126:129]
	v_mfma_f32_16x16x32_bf16 v[122:125], v[142:145], v[166:169], v[122:125]
	v_mfma_f32_16x16x32_bf16 v[114:117], v[134:137], v[174:177], v[114:117]
	v_mfma_f32_16x16x32_bf16 v[106:109], v[142:145], v[174:177], v[106:109]
	v_mfma_f32_16x16x32_bf16 v[98:101], v[134:137], v[182:185], v[98:101]
	v_mfma_f32_16x16x32_bf16 v[90:93], v[142:145], v[182:185], v[90:93]
	v_mfma_f32_16x16x32_bf16 v[82:85], v[134:137], v[190:193], v[82:85]
	v_mfma_f32_16x16x32_bf16 v[74:77], v[142:145], v[190:193], v[74:77]
	v_mfma_f32_16x16x32_bf16 v[118:121], v[146:149], v[162:165], v[118:121]
	v_mfma_f32_16x16x32_bf16 v[110:113], v[154:157], v[162:165], v[110:113]
	v_mfma_f32_16x16x32_bf16 v[102:105], v[146:149], v[170:173], v[102:105]
	v_mfma_f32_16x16x32_bf16 v[94:97], v[154:157], v[170:173], v[94:97]
	v_mfma_f32_16x16x32_bf16 v[86:89], v[146:149], v[178:181], v[86:89]
	v_mfma_f32_16x16x32_bf16 v[78:81], v[154:157], v[178:181], v[78:81]
	v_mfma_f32_16x16x32_bf16 v[70:73], v[146:149], v[186:189], v[70:73]
	v_mfma_f32_16x16x32_bf16 v[66:69], v[154:157], v[186:189], v[66:69]
	v_mfma_f32_16x16x32_bf16 v[118:121], v[150:153], v[166:169], v[118:121]
	v_mfma_f32_16x16x32_bf16 v[110:113], v[158:161], v[166:169], v[110:113]
	v_mfma_f32_16x16x32_bf16 v[102:105], v[150:153], v[174:177], v[102:105]
	v_mfma_f32_16x16x32_bf16 v[94:97], v[158:161], v[174:177], v[94:97]
	v_mfma_f32_16x16x32_bf16 v[86:89], v[150:153], v[182:185], v[86:89]
	v_mfma_f32_16x16x32_bf16 v[78:81], v[158:161], v[182:185], v[78:81]
	v_mfma_f32_16x16x32_bf16 v[70:73], v[150:153], v[190:193], v[70:73]
	v_mfma_f32_16x16x32_bf16 v[66:69], v[158:161], v[190:193], v[66:69]
	s_barrier
; #define PG8_STAGE(bufoff, gbase, voff) do { _Pragma("unroll") for (int _i = 0; _i < 2; ++_i) \
;         __builtin_amdgcn_global_load_lds((const unsigned*)((const char*)(gbase) + (voff)[_i]), (PG8_LAS unsigned*)(lds + (bufoff) + ldsw + _i * 8192), 16, 0, 0); } while (0)
; #define PG8_LDA(dst, b, h) do { _Pragma("unroll") for (int m = 0; m < 4; ++m) _Pragma("unroll") for (int k = 0; k < 2; ++k) dst[m][k] = *(const PG8_LAS bf16x8*)(lds + PG8_SA(b, h) + aoff + m * 2048 + k * 1024); } while (0)
; #define PG8_MMA(ai, bj, At, Bt) do { __builtin_amdgcn_s_setprio(1); _Pragma("unroll") for (int m = 0; m < 4; ++m) _Pragma("unroll") for (int n = 0; n < 2; ++n) _Pragma("unroll") for (int k = 0; k < 2; ++k) \
;         acc[ai][bj][m][n] = __builtin_amdgcn_mfma_f32_16x16x32_bf16(Bt[n][k], At[m][k], acc[ai][bj][m][n], 0, 0, 0); __builtin_amdgcn_s_setprio(0); } while (0)
; #define PG8_WAIT_V(n) asm volatile("s_waitcnt vmcnt(" #n ")" ::: "memory")
; #define PG8_WAIT_L(n) asm volatile("s_waitcnt lgkmcnt(" #n ")" ::: "memory")
; #define PG8_BAR __builtin_amdgcn_s_barrier()
; #define PG8_SCHED __builtin_amdgcn_sched_barrier(0)
; template <class Epi, class Sched, bool ALIGN_EPI = false, bool SP2 = false>
; __device__ __forceinline__ void gemm_phase(PG8_LAS unsigned char* lds, const Gemm g, const Sched& S, const Epi& E) {
;     ...
;         for (int t = 0; t < nt; t += 2) {
;     ...
;             PG8_LDA(At, 1, 1); PG8_STAGE(PG8_SB(1, 0), b3, voffB); PG8_STAGE(PG8_SB(1, 1), b3 + hstep, voffB); PG8_STAGE(PG8_SA(1, 0), a3, voffA);
;             PG8_WAIT_V(8); PG8_WAIT_L(0); PG8_BAR; PG8_MMA(1, 0, At, B0); PG8_MMA(1, 1, At, B1); PG8_BAR; PG8_SCHED;
	s_add_i32 s22, s52, s28
	v_lshl_add_u64 v[206:207], v[206:207], 0, s[94:95]
	s_mov_b32 m0, s22
	ds_read_b128 v[162:165], v232 offset:49152
	ds_read_b128 v[166:169], v232 offset:50176
	ds_read_b128 v[170:173], v232 offset:51200
	ds_read_b128 v[174:177], v232 offset:52224
	ds_read_b128 v[178:181], v232 offset:53248
	ds_read_b128 v[182:185], v232 offset:54272
	ds_read_b128 v[186:189], v232 offset:55296
	ds_read_b128 v[190:193], v232 offset:56320
	global_load_lds_dwordx4 v[206:207], off
	s_add_i32 m0, s22, 0x2000
	s_add_u32 s16, s16, 0x40080
	v_lshl_add_u64 v[206:207], v[208:209], 0, s[94:95]
	s_addc_u32 s17, s17, 0
	s_add_i32 s22, s53, s28
	global_load_lds_dwordx4 v[206:207], off
	v_lshl_add_u64 v[206:207], s[16:17], 0, v[198:199]
	s_mov_b32 m0, s22
	s_nop 0
	global_load_lds_dwordx4 v[206:207], off
	v_lshl_add_u64 v[206:207], s[16:17], 0, v[194:195]
	s_add_i32 m0, s22, 0x2000
	s_nop 0
	global_load_lds_dwordx4 v[206:207], off
	v_lshl_add_u64 v[206:207], v[210:211], 0, s[94:95]
	s_mov_b32 m0, s33
	s_nop 0
	global_load_lds_dwordx4 v[206:207], off
	v_lshl_add_u64 v[206:207], v[212:213], 0, s[94:95]
	s_mov_b32 m0, s35
	s_nop 0
	global_load_lds_dwordx4 v[206:207], off
	s_waitcnt vmcnt(8)
	s_waitcnt lgkmcnt(0)
	s_barrier
	v_mfma_f32_16x16x32_bf16 v[62:65], v[130:133], v[162:165], v[62:65]
	v_mfma_f32_16x16x32_bf16 v[58:61], v[138:141], v[162:165], v[58:61]
	v_mfma_f32_16x16x32_bf16 v[50:53], v[130:133], v[170:173], v[50:53]
	v_mfma_f32_16x16x32_bf16 v[42:45], v[138:141], v[170:173], v[42:45]
	v_mfma_f32_16x16x32_bf16 v[34:37], v[130:133], v[178:181], v[34:37]
	v_mfma_f32_16x16x32_bf16 v[26:29], v[138:141], v[178:181], v[26:29]
	v_mfma_f32_16x16x32_bf16 v[18:21], v[130:133], v[186:189], v[18:21]
	v_mfma_f32_16x16x32_bf16 v[10:13], v[138:141], v[186:189], v[10:13]
	v_mfma_f32_16x16x32_bf16 v[62:65], v[134:137], v[166:169], v[62:65]
	v_mfma_f32_16x16x32_bf16 v[58:61], v[142:145], v[166:169], v[58:61]
	v_mfma_f32_16x16x32_bf16 v[50:53], v[134:137], v[174:177], v[50:53]
	v_mfma_f32_16x16x32_bf16 v[42:45], v[142:145], v[174:177], v[42:45]
	v_mfma_f32_16x16x32_bf16 v[34:37], v[134:137], v[182:185], v[34:37]
	v_mfma_f32_16x16x32_bf16 v[26:29], v[142:145], v[182:185], v[26:29]
	v_mfma_f32_16x16x32_bf16 v[18:21], v[134:137], v[190:193], v[18:21]
	v_mfma_f32_16x16x32_bf16 v[10:13], v[142:145], v[190:193], v[10:13]
	v_mfma_f32_16x16x32_bf16 v[54:57], v[146:149], v[162:165], v[54:57]
	v_mfma_f32_16x16x32_bf16 v[46:49], v[154:157], v[162:165], v[46:49]
	v_mfma_f32_16x16x32_bf16 v[38:41], v[146:149], v[170:173], v[38:41]
	v_mfma_f32_16x16x32_bf16 v[30:33], v[154:157], v[170:173], v[30:33]
	v_mfma_f32_16x16x32_bf16 v[22:25], v[146:149], v[178:181], v[22:25]
	v_mfma_f32_16x16x32_bf16 v[14:17], v[154:157], v[178:181], v[14:17]
	v_mfma_f32_16x16x32_bf16 v[6:9], v[146:149], v[186:189], v[6:9]
	v_mfma_f32_16x16x32_bf16 v[2:5], v[154:157], v[186:189], v[2:5]
	v_mfma_f32_16x16x32_bf16 v[54:57], v[150:153], v[166:169], v[54:57]
	v_mfma_f32_16x16x32_bf16 v[46:49], v[158:161], v[166:169], v[46:49]
	v_mfma_f32_16x16x32_bf16 v[38:41], v[150:153], v[174:177], v[38:41]
	v_mfma_f32_16x16x32_bf16 v[30:33], v[158:161], v[174:177], v[30:33]
	v_mfma_f32_16x16x32_bf16 v[22:25], v[150:153], v[182:185], v[22:25]
	v_mfma_f32_16x16x32_bf16 v[14:17], v[158:161], v[182:185], v[14:17]
	v_mfma_f32_16x16x32_bf16 v[6:9], v[150:153], v[190:193], v[6:9]
	v_mfma_f32_16x16x32_bf16 v[2:5], v[158:161], v[190:193], v[2:5]
	s_barrier
	s_add_i32 s50, s50, 2
	s_add_u32 s20, s20, 0x100
	s_addc_u32 s21, s21, 0
	s_add_u32 s55, s55, 0x100
	s_addc_u32 s56, s56, 0
	s_cmp_gt_u32 s50, 13
	s_cbranch_scc0 .LBB0_697
	s_and_b64 vcc, exec, s[8:9]
	s_cbranch_vccz .LBB0_700
	s_barrier

; #define PG8_STAGE(bufoff, gbase, voff) do { _Pragma("unroll") for (int _i = 0; _i < 2; ++_i) \
;         __builtin_amdgcn_global_load_lds((const unsigned*)((const char*)(gbase) + (voff)[_i]), (PG8_LAS unsigned*)(lds + (bufoff) + ldsw + _i * 8192), 16, 0, 0); } while (0)
; #define PG8_LDA(dst, b, h) do { _Pragma("unroll") for (int m = 0; m < 4; ++m) _Pragma("unroll") for (int k = 0; k < 2; ++k) dst[m][k] = *(const PG8_LAS bf16x8*)(lds + PG8_SA(b, h) + aoff + m * 2048 + k * 1024); } while (0)
; #define PG8_LDB(dst, b, h) do { _Pragma("unroll") for (int n = 0; n < 2; ++n) _Pragma("unroll") for (int k = 0; k < 2; ++k) dst[n][k] = *(const PG8_LAS bf16x8*)(lds + PG8_SB(b, h) + boff + n * 2048 + k * 1024); } while (0)
; #define PG8_MMA(ai, bj, At, Bt) do { __builtin_amdgcn_s_setprio(1); _Pragma("unroll") for (int m = 0; m < 4; ++m) _Pragma("unroll") for (int n = 0; n < 2; ++n) _Pragma("unroll") for (int k = 0; k < 2; ++k) \
;         acc[ai][bj][m][n] = __builtin_amdgcn_mfma_f32_16x16x32_bf16(Bt[n][k], At[m][k], acc[ai][bj][m][n], 0, 0, 0); __builtin_amdgcn_s_setprio(0); } while (0)
; #define PG8_WAIT_V(n) asm volatile("s_waitcnt vmcnt(" #n ")" ::: "memory")
; #define PG8_WAIT_L(n) asm volatile("s_waitcnt lgkmcnt(" #n ")" ::: "memory")
; #define PG8_BAR __builtin_amdgcn_s_barrier()
; #define PG8_SCHED __builtin_amdgcn_sched_barrier(0)
; template <class Epi, class Sched, bool ALIGN_EPI = false, bool SP2 = false>
; __device__ __forceinline__ void gemm_phase(PG8_LAS unsigned char* lds, const Gemm g, const Sched& S, const Epi& E) {
;     ...
;             const bool last = (t == nt - 2);
;             const char* a1 = cA + (size_t)(t + 1) * kstep;
;             const char* a2 = last ? nA : cA + (size_t)(t + 2) * kstep; const char* b2 = last ? nB : cB + (size_t)(t + 2) * kstep;
;             const char* a3 = a2 + kstep; const char* b3 = b2 + kstep;
;             if (last && has_next) S.a_ready(nxt);
;             if constexpr (SP2) {
;             PG8_LDB(B0, 0, 0); PG8_LDB(B1, 0, 1); PG8_SCHED; PG8_LDA(At, 0, 0); PG8_STAGE(PG8_SA(1, 1), a1 + hstep, voffA);
;             PG8_WAIT_V(8); PG8_WAIT_L(0); PG8_BAR; PG8_MMA(0, 0, At, B0); PG8_MMA(0, 1, At, B1); PG8_BAR; PG8_SCHED;
;             PG8_LDA(At, 0, 1); PG8_STAGE(PG8_SB(0, 0), b2, voffB); PG8_STAGE(PG8_SB(0, 1), b2 + hstep, voffB); PG8_STAGE(PG8_SA(0, 0), a2, voffA);
.Lboff_skip_K:
.LBB0_816:
	s_add_u32 s16, s20, 0xfffc0080
	s_addc_u32 s17, s21, -1
	s_add_i32 s52, 0, 0x10000
	s_cmp_eq_u32 s50, 12
	s_cselect_b32 s23, s13, s17
	s_cselect_b32 s22, s39, s16
	v_add_u32_e32 v142, s52, v145
	s_cselect_b32 s17, s11, s56
	s_cselect_b32 s16, s46, s55
	s_add_i32 s57, 0, 0x14000
	ds_read_b128 v[148:151], v142
	ds_read_b128 v[152:155], v142 offset:1024
	ds_read_b128 v[156:159], v142 offset:2048
	ds_read_b128 v[160:163], v142 offset:3072
	v_add_u32_e32 v142, s57, v145
	ds_read_b128 v[164:167], v142
	ds_read_b128 v[168:171], v142 offset:1024
	ds_read_b128 v[172:175], v142 offset:2048
	ds_read_b128 v[176:179], v142 offset:3072
	v_lshl_add_u64 v[142:143], s[20:21], 0, v[138:139]
	s_add_i32 m0, s29, 0xc000
	ds_read_b128 v[180:183], v146
	ds_read_b128 v[184:187], v146 offset:1024
	ds_read_b128 v[188:191], v146 offset:2048
	ds_read_b128 v[192:195], v146 offset:3072
	ds_read_b128 v[196:199], v146 offset:4096
	ds_read_b128 v[200:203], v146 offset:5120
	ds_read_b128 v[204:207], v146 offset:6144
	ds_read_b128 v[208:211], v146 offset:7168
	global_load_lds_dwordx4 v[142:143], off
	v_lshl_add_u64 v[142:143], s[20:21], 0, v[140:141]
	s_add_i32 m0, s29, 0xe000
	s_nop 0
	global_load_lds_dwordx4 v[142:143], off
	s_waitcnt vmcnt(8)
	s_waitcnt lgkmcnt(0)
	s_barrier
	v_mfma_f32_16x16x32_bf16 v[126:129], v[148:151], v[180:183], v[126:129]
	v_mfma_f32_16x16x32_bf16 v[122:125], v[156:159], v[180:183], v[122:125]
	v_mfma_f32_16x16x32_bf16 v[110:113], v[148:151], v[188:191], v[110:113]
	v_mfma_f32_16x16x32_bf16 v[106:109], v[156:159], v[188:191], v[106:109]
	v_mfma_f32_16x16x32_bf16 v[94:97], v[148:151], v[196:199], v[94:97]
	v_mfma_f32_16x16x32_bf16 v[90:93], v[156:159], v[196:199], v[90:93]
	v_mfma_f32_16x16x32_bf16 v[78:81], v[148:151], v[204:207], v[78:81]
	v_mfma_f32_16x16x32_bf16 v[74:77], v[156:159], v[204:207], v[74:77]
	v_mfma_f32_16x16x32_bf16 v[126:129], v[152:155], v[184:187], v[126:129]
	v_mfma_f32_16x16x32_bf16 v[122:125], v[160:163], v[184:187], v[122:125]
	v_mfma_f32_16x16x32_bf16 v[110:113], v[152:155], v[192:195], v[110:113]
	v_mfma_f32_16x16x32_bf16 v[106:109], v[160:163], v[192:195], v[106:109]
	v_mfma_f32_16x16x32_bf16 v[94:97], v[152:155], v[200:203], v[94:97]
	v_mfma_f32_16x16x32_bf16 v[90:93], v[160:163], v[200:203], v[90:93]
	v_mfma_f32_16x16x32_bf16 v[78:81], v[152:155], v[208:211], v[78:81]
	v_mfma_f32_16x16x32_bf16 v[74:77], v[160:163], v[208:211], v[74:77]
	v_mfma_f32_16x16x32_bf16 v[118:121], v[164:167], v[180:183], v[118:121]
	v_mfma_f32_16x16x32_bf16 v[114:117], v[172:175], v[180:183], v[114:117]
	v_mfma_f32_16x16x32_bf16 v[102:105], v[164:167], v[188:191], v[102:105]
	v_mfma_f32_16x16x32_bf16 v[98:101], v[172:175], v[188:191], v[98:101]
	v_mfma_f32_16x16x32_bf16 v[86:89], v[164:167], v[196:199], v[86:89]
	v_mfma_f32_16x16x32_bf16 v[82:85], v[172:175], v[196:199], v[82:85]
	v_mfma_f32_16x16x32_bf16 v[70:73], v[164:167], v[204:207], v[70:73]
	v_mfma_f32_16x16x32_bf16 v[66:69], v[172:175], v[204:207], v[66:69]
	v_mfma_f32_16x16x32_bf16 v[118:121], v[168:171], v[184:187], v[118:121]
	v_mfma_f32_16x16x32_bf16 v[114:117], v[176:179], v[184:187], v[114:117]
	v_mfma_f32_16x16x32_bf16 v[102:105], v[168:171], v[192:195], v[102:105]
	v_mfma_f32_16x16x32_bf16 v[98:101], v[176:179], v[192:195], v[98:101]
	v_mfma_f32_16x16x32_bf16 v[86:89], v[168:171], v[200:203], v[86:89]
	v_mfma_f32_16x16x32_bf16 v[82:85], v[176:179], v[200:203], v[82:85]
	v_mfma_f32_16x16x32_bf16 v[70:73], v[168:171], v[208:211], v[70:73]
	v_mfma_f32_16x16x32_bf16 v[66:69], v[176:179], v[208:211], v[66:69]
	s_barrier
	s_add_i32 s52, s52, s28
	v_lshl_add_u64 v[142:143], s[16:17], 0, v[134:135]
	s_mov_b32 m0, s52
	ds_read_b128 v[180:183], v146 offset:16384
	ds_read_b128 v[184:187], v146 offset:17408
	ds_read_b128 v[188:191], v146 offset:18432
	ds_read_b128 v[192:195], v146 offset:19456
	ds_read_b128 v[196:199], v146 offset:20480
	ds_read_b128 v[200:203], v146 offset:21504
	ds_read_b128 v[204:207], v146 offset:22528
	ds_read_b128 v[208:211], v146 offset:23552
	global_load_lds_dwordx4 v[142:143], off
	s_add_i32 m0, s52, 0x2000
	s_add_u32 s52, s16, 0x40000
	v_lshl_add_u64 v[212:213], s[16:17], 0, v[130:131]
	s_addc_u32 s53, s17, 0
	s_add_i32 s57, s57, s28
	global_load_lds_dwordx4 v[212:213], off
	v_lshl_add_u64 v[214:215], s[52:53], 0, v[134:135]
	s_mov_b32 m0, s57
	v_lshl_add_u64 v[216:217], s[22:23], 0, v[132:133]
	global_load_lds_dwordx4 v[214:215], off
	v_lshl_add_u64 v[214:215], s[52:53], 0, v[130:131]
	s_add_i32 m0, s57, 0x2000
	s_nop 0
	global_load_lds_dwordx4 v[214:215], off
	v_lshl_add_u64 v[214:215], s[22:23], 0, v[136:137]
	s_mov_b32 m0, s29
	s_nop 0
	global_load_lds_dwordx4 v[214:215], off
	s_mov_b32 m0, s30
	s_nop 0
	global_load_lds_dwordx4 v[216:217], off
	s_waitcnt vmcnt(8)
	s_waitcnt lgkmcnt(0)
	s_barrier
; #define PG8_STAGE(bufoff, gbase, voff) do { _Pragma("unroll") for (int _i = 0; _i < 2; ++_i) \
;         __builtin_amdgcn_global_load_lds((const unsigned*)((const char*)(gbase) + (voff)[_i]), (PG8_LAS unsigned*)(lds + (bufoff) + ldsw + _i * 8192), 16, 0, 0); } while (0)
; #define PG8_LDA(dst, b, h) do { _Pragma("unroll") for (int m = 0; m < 4; ++m) _Pragma("unroll") for (int k = 0; k < 2; ++k) dst[m][k] = *(const PG8_LAS bf16x8*)(lds + PG8_SA(b, h) + aoff + m * 2048 + k * 1024); } while (0)
; #define PG8_LDB(dst, b, h) do { _Pragma("unroll") for (int n = 0; n < 2; ++n) _Pragma("unroll") for (int k = 0; k < 2; ++k) dst[n][k] = *(const PG8_LAS bf16x8*)(lds + PG8_SB(b, h) + boff + n * 2048 + k * 1024); } while (0)
; #define PG8_MMA(ai, bj, At, Bt) do { __builtin_amdgcn_s_setprio(1); _Pragma("unroll") for (int m = 0; m < 4; ++m) _Pragma("unroll") for (int n = 0; n < 2; ++n) _Pragma("unroll") for (int k = 0; k < 2; ++k) \
;         acc[ai][bj][m][n] = __builtin_amdgcn_mfma_f32_16x16x32_bf16(Bt[n][k], At[m][k], acc[ai][bj][m][n], 0, 0, 0); __builtin_amdgcn_s_setprio(0); } while (0)
; #define PG8_WAIT_V(n) asm volatile("s_waitcnt vmcnt(" #n ")" ::: "memory")
; #define PG8_WAIT_L(n) asm volatile("s_waitcnt lgkmcnt(" #n ")" ::: "memory")
; #define PG8_BAR __builtin_amdgcn_s_barrier()
; #define PG8_SCHED __builtin_amdgcn_sched_barrier(0)
; template <class Epi, class Sched, bool ALIGN_EPI = false, bool SP2 = false>
; __device__ __forceinline__ void gemm_phase(PG8_LAS unsigned char* lds, const Gemm g, const Sched& S, const Epi& E) {
;     ...
;             PG8_WAIT_V(8); PG8_WAIT_L(0); PG8_BAR; PG8_MMA(1, 0, At, B0); PG8_MMA(1, 1, At, B1); PG8_BAR; PG8_SCHED;
;             PG8_LDB(B0, 1, 0); PG8_LDB(B1, 1, 1); PG8_SCHED; PG8_LDA(At, 1, 0); PG8_STAGE(PG8_SA(0, 1), a2 + hstep, voffA);
;             PG8_WAIT_V(8); PG8_WAIT_L(0); PG8_BAR; PG8_MMA(0, 0, At, B0); PG8_MMA(0, 1, At, B1); PG8_BAR; PG8_SCHED;
	v_mfma_f32_16x16x32_bf16 v[62:65], v[148:151], v[180:183], v[62:65]
	v_mfma_f32_16x16x32_bf16 v[58:61], v[156:159], v[180:183], v[58:61]
	v_mfma_f32_16x16x32_bf16 v[46:49], v[148:151], v[188:191], v[46:49]
	v_mfma_f32_16x16x32_bf16 v[42:45], v[156:159], v[188:191], v[42:45]
	v_mfma_f32_16x16x32_bf16 v[30:33], v[148:151], v[196:199], v[30:33]
	v_mfma_f32_16x16x32_bf16 v[26:29], v[156:159], v[196:199], v[26:29]
	v_mfma_f32_16x16x32_bf16 v[14:17], v[148:151], v[204:207], v[14:17]
	v_mfma_f32_16x16x32_bf16 v[10:13], v[156:159], v[204:207], v[10:13]
	v_mfma_f32_16x16x32_bf16 v[62:65], v[152:155], v[184:187], v[62:65]
	v_mfma_f32_16x16x32_bf16 v[58:61], v[160:163], v[184:187], v[58:61]
	v_mfma_f32_16x16x32_bf16 v[46:49], v[152:155], v[192:195], v[46:49]
	v_mfma_f32_16x16x32_bf16 v[42:45], v[160:163], v[192:195], v[42:45]
	v_mfma_f32_16x16x32_bf16 v[30:33], v[152:155], v[200:203], v[30:33]
	v_mfma_f32_16x16x32_bf16 v[26:29], v[160:163], v[200:203], v[26:29]
	v_mfma_f32_16x16x32_bf16 v[14:17], v[152:155], v[208:211], v[14:17]
	v_mfma_f32_16x16x32_bf16 v[10:13], v[160:163], v[208:211], v[10:13]
	v_mfma_f32_16x16x32_bf16 v[54:57], v[164:167], v[180:183], v[54:57]
	v_mfma_f32_16x16x32_bf16 v[50:53], v[172:175], v[180:183], v[50:53]
	v_mfma_f32_16x16x32_bf16 v[38:41], v[164:167], v[188:191], v[38:41]
	v_mfma_f32_16x16x32_bf16 v[34:37], v[172:175], v[188:191], v[34:37]
	v_mfma_f32_16x16x32_bf16 v[22:25], v[164:167], v[196:199], v[22:25]
	v_mfma_f32_16x16x32_bf16 v[18:21], v[172:175], v[196:199], v[18:21]
	v_mfma_f32_16x16x32_bf16 v[6:9], v[164:167], v[204:207], v[6:9]
	v_mfma_f32_16x16x32_bf16 v[2:5], v[172:175], v[204:207], v[2:5]
	v_mfma_f32_16x16x32_bf16 v[54:57], v[168:171], v[184:187], v[54:57]
	v_mfma_f32_16x16x32_bf16 v[50:53], v[176:179], v[184:187], v[50:53]
	v_mfma_f32_16x16x32_bf16 v[38:41], v[168:171], v[192:195], v[38:41]
	v_mfma_f32_16x16x32_bf16 v[34:37], v[176:179], v[192:195], v[34:37]
	v_mfma_f32_16x16x32_bf16 v[22:25], v[168:171], v[200:203], v[22:25]
	v_mfma_f32_16x16x32_bf16 v[18:21], v[176:179], v[200:203], v[18:21]
	v_mfma_f32_16x16x32_bf16 v[6:9], v[168:171], v[208:211], v[6:9]
	v_mfma_f32_16x16x32_bf16 v[2:5], v[176:179], v[208:211], v[2:5]
	s_barrier
	s_add_i32 s52, 0, 0x18000
	v_add_u32_e32 v147, s52, v145
	s_add_i32 s53, 0, 0x1c000
	ds_read_b128 v[148:151], v147
	ds_read_b128 v[152:155], v147 offset:1024
	ds_read_b128 v[156:159], v147 offset:2048
	ds_read_b128 v[160:163], v147 offset:3072
	v_add_u32_e32 v147, s53, v145
	ds_read_b128 v[164:167], v147
	ds_read_b128 v[168:171], v147 offset:1024
	ds_read_b128 v[172:175], v147 offset:2048
	ds_read_b128 v[176:179], v147 offset:3072
	s_add_u32 s22, s22, 0x40000
	s_addc_u32 s23, s23, 0
	s_mov_b32 m0, s31
	v_lshl_add_u64 v[218:219], s[22:23], 0, v[136:137]
	ds_read_b128 v[180:183], v146 offset:32768
	ds_read_b128 v[184:187], v146 offset:33792
	ds_read_b128 v[188:191], v146 offset:34816
	ds_read_b128 v[192:195], v146 offset:35840
	ds_read_b128 v[196:199], v146 offset:36864
	ds_read_b128 v[200:203], v146 offset:37888
	ds_read_b128 v[204:207], v146 offset:38912
	ds_read_b128 v[208:211], v146 offset:39936
	global_load_lds_dwordx4 v[218:219], off
	v_lshl_add_u64 v[218:219], s[22:23], 0, v[132:133]
	s_mov_b32 m0, s33
	s_nop 0
	global_load_lds_dwordx4 v[218:219], off
	s_waitcnt vmcnt(8)
	s_waitcnt lgkmcnt(0)
	s_barrier
	v_mfma_f32_16x16x32_bf16 v[126:129], v[148:151], v[180:183], v[126:129]
	v_mfma_f32_16x16x32_bf16 v[122:125], v[156:159], v[180:183], v[122:125]
	v_mfma_f32_16x16x32_bf16 v[110:113], v[148:151], v[188:191], v[110:113]
	v_mfma_f32_16x16x32_bf16 v[106:109], v[156:159], v[188:191], v[106:109]
	v_mfma_f32_16x16x32_bf16 v[94:97], v[148:151], v[196:199], v[94:97]
	v_mfma_f32_16x16x32_bf16 v[90:93], v[156:159], v[196:199], v[90:93]
	v_mfma_f32_16x16x32_bf16 v[78:81], v[148:151], v[204:207], v[78:81]
	v_mfma_f32_16x16x32_bf16 v[74:77], v[156:159], v[204:207], v[74:77]
	v_mfma_f32_16x16x32_bf16 v[126:129], v[152:155], v[184:187], v[126:129]
	v_mfma_f32_16x16x32_bf16 v[122:125], v[160:163], v[184:187], v[122:125]
	v_mfma_f32_16x16x32_bf16 v[110:113], v[152:155], v[192:195], v[110:113]
	v_mfma_f32_16x16x32_bf16 v[106:109], v[160:163], v[192:195], v[106:109]
	v_mfma_f32_16x16x32_bf16 v[94:97], v[152:155], v[200:203], v[94:97]
	v_mfma_f32_16x16x32_bf16 v[90:93], v[160:163], v[200:203], v[90:93]
	v_mfma_f32_16x16x32_bf16 v[78:81], v[152:155], v[208:211], v[78:81]
	v_mfma_f32_16x16x32_bf16 v[74:77], v[160:163], v[208:211], v[74:77]
	v_mfma_f32_16x16x32_bf16 v[118:121], v[164:167], v[180:183], v[118:121]
	v_mfma_f32_16x16x32_bf16 v[114:117], v[172:175], v[180:183], v[114:117]
	v_mfma_f32_16x16x32_bf16 v[102:105], v[164:167], v[188:191], v[102:105]
	v_mfma_f32_16x16x32_bf16 v[98:101], v[172:175], v[188:191], v[98:101]
	v_mfma_f32_16x16x32_bf16 v[86:89], v[164:167], v[196:199], v[86:89]
	v_mfma_f32_16x16x32_bf16 v[82:85], v[172:175], v[196:199], v[82:85]
	v_mfma_f32_16x16x32_bf16 v[70:73], v[164:167], v[204:207], v[70:73]
	v_mfma_f32_16x16x32_bf16 v[66:69], v[172:175], v[204:207], v[66:69]
	v_mfma_f32_16x16x32_bf16 v[118:121], v[168:171], v[184:187], v[118:121]
	v_mfma_f32_16x16x32_bf16 v[114:117], v[176:179], v[184:187], v[114:117]
	v_mfma_f32_16x16x32_bf16 v[102:105], v[168:171], v[192:195], v[102:105]
	v_mfma_f32_16x16x32_bf16 v[98:101], v[176:179], v[192:195], v[98:101]
	v_mfma_f32_16x16x32_bf16 v[86:89], v[168:171], v[200:203], v[86:89]
	v_mfma_f32_16x16x32_bf16 v[82:85], v[176:179], v[200:203], v[82:85]
	v_mfma_f32_16x16x32_bf16 v[70:73], v[168:171], v[208:211], v[70:73]
	v_mfma_f32_16x16x32_bf16 v[66:69], v[176:179], v[208:211], v[66:69]
	s_barrier
; #define PG8_STAGE(bufoff, gbase, voff) do { _Pragma("unroll") for (int _i = 0; _i < 2; ++_i) \
;         __builtin_amdgcn_global_load_lds((const unsigned*)((const char*)(gbase) + (voff)[_i]), (PG8_LAS unsigned*)(lds + (bufoff) + ldsw + _i * 8192), 16, 0, 0); } while (0)
; #define PG8_LDA(dst, b, h) do { _Pragma("unroll") for (int m = 0; m < 4; ++m) _Pragma("unroll") for (int k = 0; k < 2; ++k) dst[m][k] = *(const PG8_LAS bf16x8*)(lds + PG8_SA(b, h) + aoff + m * 2048 + k * 1024); } while (0)
; #define PG8_MMA(ai, bj, At, Bt) do { __builtin_amdgcn_s_setprio(1); _Pragma("unroll") for (int m = 0; m < 4; ++m) _Pragma("unroll") for (int n = 0; n < 2; ++n) _Pragma("unroll") for (int k = 0; k < 2; ++k) \
;         acc[ai][bj][m][n] = __builtin_amdgcn_mfma_f32_16x16x32_bf16(Bt[n][k], At[m][k], acc[ai][bj][m][n], 0, 0, 0); __builtin_amdgcn_s_setprio(0); } while (0)
; #define PG8_WAIT_V(n) asm volatile("s_waitcnt vmcnt(" #n ")" ::: "memory")
; #define PG8_WAIT_L(n) asm volatile("s_waitcnt lgkmcnt(" #n ")" ::: "memory")
; #define PG8_BAR __builtin_amdgcn_s_barrier()
; #define PG8_SCHED __builtin_amdgcn_sched_barrier(0)
; template <class Epi, class Sched, bool ALIGN_EPI = false, bool SP2 = false>
; __device__ __forceinline__ void gemm_phase(PG8_LAS unsigned char* lds, const Gemm g, const Sched& S, const Epi& E) {
;     ...
;         for (int t = 0; t < nt; t += 2) {
;     ...
;             PG8_LDA(At, 1, 1); PG8_STAGE(PG8_SB(1, 0), b3, voffB); PG8_STAGE(PG8_SB(1, 1), b3 + hstep, voffB); PG8_STAGE(PG8_SA(1, 0), a3, voffA);
;             PG8_WAIT_V(8); PG8_WAIT_L(0); PG8_BAR; PG8_MMA(1, 0, At, B0); PG8_MMA(1, 1, At, B1); PG8_BAR; PG8_SCHED;
	s_add_i32 s22, s52, s28
	v_lshl_add_u64 v[142:143], v[142:143], 0, s[94:95]
	s_mov_b32 m0, s22
	ds_read_b128 v[180:183], v146 offset:49152
	ds_read_b128 v[184:187], v146 offset:50176
	ds_read_b128 v[188:191], v146 offset:51200
	ds_read_b128 v[192:195], v146 offset:52224
	ds_read_b128 v[196:199], v146 offset:53248
	ds_read_b128 v[200:203], v146 offset:54272
	ds_read_b128 v[204:207], v146 offset:55296
	ds_read_b128 v[208:211], v146 offset:56320
	global_load_lds_dwordx4 v[142:143], off
	s_add_i32 m0, s22, 0x2000
	s_add_u32 s16, s16, 0x40080
	v_lshl_add_u64 v[142:143], v[212:213], 0, s[94:95]
	s_addc_u32 s17, s17, 0
	s_add_i32 s22, s53, s28
	global_load_lds_dwordx4 v[142:143], off
	v_lshl_add_u64 v[142:143], s[16:17], 0, v[134:135]
	s_mov_b32 m0, s22
	s_nop 0
	global_load_lds_dwordx4 v[142:143], off
	v_lshl_add_u64 v[142:143], s[16:17], 0, v[130:131]
	s_add_i32 m0, s22, 0x2000
	s_nop 0
	global_load_lds_dwordx4 v[142:143], off
	v_lshl_add_u64 v[142:143], v[214:215], 0, s[94:95]
	s_mov_b32 m0, s34
	s_nop 0
	global_load_lds_dwordx4 v[142:143], off
	v_lshl_add_u64 v[142:143], v[216:217], 0, s[94:95]
	s_mov_b32 m0, s35
	s_nop 0
	global_load_lds_dwordx4 v[142:143], off
	s_waitcnt vmcnt(8)
	s_waitcnt lgkmcnt(0)
	s_barrier
	v_mfma_f32_16x16x32_bf16 v[62:65], v[148:151], v[180:183], v[62:65]
	v_mfma_f32_16x16x32_bf16 v[58:61], v[156:159], v[180:183], v[58:61]
	v_mfma_f32_16x16x32_bf16 v[46:49], v[148:151], v[188:191], v[46:49]
	v_mfma_f32_16x16x32_bf16 v[42:45], v[156:159], v[188:191], v[42:45]
	v_mfma_f32_16x16x32_bf16 v[30:33], v[148:151], v[196:199], v[30:33]
	v_mfma_f32_16x16x32_bf16 v[26:29], v[156:159], v[196:199], v[26:29]
	v_mfma_f32_16x16x32_bf16 v[14:17], v[148:151], v[204:207], v[14:17]
	v_mfma_f32_16x16x32_bf16 v[10:13], v[156:159], v[204:207], v[10:13]
	v_mfma_f32_16x16x32_bf16 v[62:65], v[152:155], v[184:187], v[62:65]
	v_mfma_f32_16x16x32_bf16 v[58:61], v[160:163], v[184:187], v[58:61]
	v_mfma_f32_16x16x32_bf16 v[46:49], v[152:155], v[192:195], v[46:49]
	v_mfma_f32_16x16x32_bf16 v[42:45], v[160:163], v[192:195], v[42:45]
	v_mfma_f32_16x16x32_bf16 v[30:33], v[152:155], v[200:203], v[30:33]
	v_mfma_f32_16x16x32_bf16 v[26:29], v[160:163], v[200:203], v[26:29]
	v_mfma_f32_16x16x32_bf16 v[14:17], v[152:155], v[208:211], v[14:17]
	v_mfma_f32_16x16x32_bf16 v[10:13], v[160:163], v[208:211], v[10:13]
	v_mfma_f32_16x16x32_bf16 v[54:57], v[164:167], v[180:183], v[54:57]
	v_mfma_f32_16x16x32_bf16 v[50:53], v[172:175], v[180:183], v[50:53]
	v_mfma_f32_16x16x32_bf16 v[38:41], v[164:167], v[188:191], v[38:41]
	v_mfma_f32_16x16x32_bf16 v[34:37], v[172:175], v[188:191], v[34:37]
	v_mfma_f32_16x16x32_bf16 v[22:25], v[164:167], v[196:199], v[22:25]
	v_mfma_f32_16x16x32_bf16 v[18:21], v[172:175], v[196:199], v[18:21]
	v_mfma_f32_16x16x32_bf16 v[6:9], v[164:167], v[204:207], v[6:9]
	v_mfma_f32_16x16x32_bf16 v[2:5], v[172:175], v[204:207], v[2:5]
	v_mfma_f32_16x16x32_bf16 v[54:57], v[168:171], v[184:187], v[54:57]
	v_mfma_f32_16x16x32_bf16 v[50:53], v[176:179], v[184:187], v[50:53]
	v_mfma_f32_16x16x32_bf16 v[38:41], v[168:171], v[192:195], v[38:41]
	v_mfma_f32_16x16x32_bf16 v[34:37], v[176:179], v[192:195], v[34:37]
	v_mfma_f32_16x16x32_bf16 v[22:25], v[168:171], v[200:203], v[22:25]
	v_mfma_f32_16x16x32_bf16 v[18:21], v[176:179], v[200:203], v[18:21]
	v_mfma_f32_16x16x32_bf16 v[6:9], v[168:171], v[208:211], v[6:9]
	v_mfma_f32_16x16x32_bf16 v[2:5], v[176:179], v[208:211], v[2:5]
	s_barrier
	s_add_i32 s50, s50, 2
	s_add_u32 s20, s20, 0x100
	s_addc_u32 s21, s21, 0
	s_add_u32 s55, s55, 0x100
	s_addc_u32 s56, s56, 0
	s_cmp_gt_u32 s50, 13
	s_cbranch_scc0 .LBB0_816
	s_and_b64 vcc, exec, s[8:9]
	s_cbranch_vccz .LBB0_819
	s_barrier

; #define PG8_STAGE(bufoff, gbase, voff) do { _Pragma("unroll") for (int _i = 0; _i < 2; ++_i) \
;         __builtin_amdgcn_global_load_lds((const unsigned*)((const char*)(gbase) + (voff)[_i]), (PG8_LAS unsigned*)(lds + (bufoff) + ldsw + _i * 8192), 16, 0, 0); } while (0)
; #define PG8_LDA(dst, b, h) do { _Pragma("unroll") for (int m = 0; m < 4; ++m) _Pragma("unroll") for (int k = 0; k < 2; ++k) dst[m][k] = *(const PG8_LAS bf16x8*)(lds + PG8_SA(b, h) + aoff + m * 2048 + k * 1024); } while (0)
; #define PG8_LDB(dst, b, h) do { _Pragma("unroll") for (int n = 0; n < 2; ++n) _Pragma("unroll") for (int k = 0; k < 2; ++k) dst[n][k] = *(const PG8_LAS bf16x8*)(lds + PG8_SB(b, h) + boff + n * 2048 + k * 1024); } while (0)
; #define PG8_MMA(ai, bj, At, Bt) do { __builtin_amdgcn_s_setprio(1); _Pragma("unroll") for (int m = 0; m < 4; ++m) _Pragma("unroll") for (int n = 0; n < 2; ++n) _Pragma("unroll") for (int k = 0; k < 2; ++k) \
;         acc[ai][bj][m][n] = __builtin_amdgcn_mfma_f32_16x16x32_bf16(Bt[n][k], At[m][k], acc[ai][bj][m][n], 0, 0, 0); __builtin_amdgcn_s_setprio(0); } while (0)
; #define PG8_WAIT_V(n) asm volatile("s_waitcnt vmcnt(" #n ")" ::: "memory")
; #define PG8_WAIT_L(n) asm volatile("s_waitcnt lgkmcnt(" #n ")" ::: "memory")
; #define PG8_BAR __builtin_amdgcn_s_barrier()
; #define PG8_SCHED __builtin_amdgcn_sched_barrier(0)
; template <class Epi, class Sched, bool ALIGN_EPI = false, bool SP2 = false>
; __device__ __forceinline__ void gemm_phase(PG8_LAS unsigned char* lds, const Gemm g, const Sched& S, const Epi& E) {
;     ...
;             const bool last = (t == nt - 2);
;             const char* a1 = cA + (size_t)(t + 1) * kstep;
;             const char* a2 = last ? nA : cA + (size_t)(t + 2) * kstep; const char* b2 = last ? nB : cB + (size_t)(t + 2) * kstep;
;             const char* a3 = a2 + kstep; const char* b3 = b2 + kstep;
;             if (last && has_next) S.a_ready(nxt);
;             if constexpr (SP2) {
;             PG8_LDB(B0, 0, 0); PG8_LDB(B1, 0, 1); PG8_SCHED; PG8_LDA(At, 0, 0); PG8_STAGE(PG8_SA(1, 1), a1 + hstep, voffA);
;             PG8_WAIT_V(8); PG8_WAIT_L(0); PG8_BAR; PG8_MMA(0, 0, At, B0); PG8_MMA(0, 1, At, B1); PG8_BAR; PG8_SCHED;
;             PG8_LDA(At, 0, 1); PG8_STAGE(PG8_SB(0, 0), b2, voffB); PG8_STAGE(PG8_SB(0, 1), b2 + hstep, voffB); PG8_STAGE(PG8_SA(0, 0), a2, voffA);
.Lboff_skip_L:
.LBB0_881:
	s_add_u32 s16, s20, 0xfff00080
	s_addc_u32 s17, s21, -1
	s_add_i32 s52, 0, 0x10000
	s_cmp_eq_u32 s50, 60
	s_cselect_b32 s23, s13, s17
	s_cselect_b32 s22, s39, s16
	s_cselect_b32 s17, s11, s56
	s_cselect_b32 s16, s46, s55
	s_add_i32 s57, 0, 0x14000
	v_add_u32_e32 v142, s52, v231
	v_add_u32_e32 v158, s57, v231
	ds_read_b128 v[130:133], v142
	ds_read_b128 v[134:137], v142 offset:1024
	ds_read_b128 v[138:141], v142 offset:2048
	ds_read_b128 v[142:145], v142 offset:3072
	ds_read_b128 v[146:149], v158
	ds_read_b128 v[150:153], v158 offset:1024
	ds_read_b128 v[154:157], v158 offset:2048
	ds_read_b128 v[158:161], v158 offset:3072
	v_lshl_add_u64 v[206:207], s[20:21], 0, v[202:203]
	s_add_i32 m0, s29, 0xc000
	ds_read_b128 v[162:165], v232
	ds_read_b128 v[166:169], v232 offset:1024
	ds_read_b128 v[170:173], v232 offset:2048
	ds_read_b128 v[174:177], v232 offset:3072
	ds_read_b128 v[178:181], v232 offset:4096
	ds_read_b128 v[182:185], v232 offset:5120
	ds_read_b128 v[186:189], v232 offset:6144
	ds_read_b128 v[190:193], v232 offset:7168
	global_load_lds_dwordx4 v[206:207], off
	v_lshl_add_u64 v[206:207], s[20:21], 0, v[204:205]
	s_add_i32 m0, s29, 0xe000
	s_nop 0
	global_load_lds_dwordx4 v[206:207], off
	s_waitcnt vmcnt(8)
	s_waitcnt lgkmcnt(0)
	s_barrier
	v_mfma_f32_16x16x32_bf16 v[126:129], v[130:133], v[162:165], v[126:129]
	v_mfma_f32_16x16x32_bf16 v[122:125], v[138:141], v[162:165], v[122:125]
	v_mfma_f32_16x16x32_bf16 v[114:117], v[130:133], v[170:173], v[114:117]
	v_mfma_f32_16x16x32_bf16 v[106:109], v[138:141], v[170:173], v[106:109]
	v_mfma_f32_16x16x32_bf16 v[98:101], v[130:133], v[178:181], v[98:101]
	v_mfma_f32_16x16x32_bf16 v[90:93], v[138:141], v[178:181], v[90:93]
	v_mfma_f32_16x16x32_bf16 v[82:85], v[130:133], v[186:189], v[82:85]
	v_mfma_f32_16x16x32_bf16 v[74:77], v[138:141], v[186:189], v[74:77]
	v_mfma_f32_16x16x32_bf16 v[126:129], v[134:137], v[166:169], v[126:129]
	v_mfma_f32_16x16x32_bf16 v[122:125], v[142:145], v[166:169], v[122:125]
	v_mfma_f32_16x16x32_bf16 v[114:117], v[134:137], v[174:177], v[114:117]
	v_mfma_f32_16x16x32_bf16 v[106:109], v[142:145], v[174:177], v[106:109]
	v_mfma_f32_16x16x32_bf16 v[98:101], v[134:137], v[182:185], v[98:101]
	v_mfma_f32_16x16x32_bf16 v[90:93], v[142:145], v[182:185], v[90:93]
	v_mfma_f32_16x16x32_bf16 v[82:85], v[134:137], v[190:193], v[82:85]
	v_mfma_f32_16x16x32_bf16 v[74:77], v[142:145], v[190:193], v[74:77]
	v_mfma_f32_16x16x32_bf16 v[118:121], v[146:149], v[162:165], v[118:121]
	v_mfma_f32_16x16x32_bf16 v[110:113], v[154:157], v[162:165], v[110:113]
	v_mfma_f32_16x16x32_bf16 v[102:105], v[146:149], v[170:173], v[102:105]
	v_mfma_f32_16x16x32_bf16 v[94:97], v[154:157], v[170:173], v[94:97]
	v_mfma_f32_16x16x32_bf16 v[86:89], v[146:149], v[178:181], v[86:89]
	v_mfma_f32_16x16x32_bf16 v[78:81], v[154:157], v[178:181], v[78:81]
	v_mfma_f32_16x16x32_bf16 v[70:73], v[146:149], v[186:189], v[70:73]
	v_mfma_f32_16x16x32_bf16 v[66:69], v[154:157], v[186:189], v[66:69]
	v_mfma_f32_16x16x32_bf16 v[118:121], v[150:153], v[166:169], v[118:121]
	v_mfma_f32_16x16x32_bf16 v[110:113], v[158:161], v[166:169], v[110:113]
	v_mfma_f32_16x16x32_bf16 v[102:105], v[150:153], v[174:177], v[102:105]
	v_mfma_f32_16x16x32_bf16 v[94:97], v[158:161], v[174:177], v[94:97]
	v_mfma_f32_16x16x32_bf16 v[86:89], v[150:153], v[182:185], v[86:89]
	v_mfma_f32_16x16x32_bf16 v[78:81], v[158:161], v[182:185], v[78:81]
	v_mfma_f32_16x16x32_bf16 v[70:73], v[150:153], v[190:193], v[70:73]
	v_mfma_f32_16x16x32_bf16 v[66:69], v[158:161], v[190:193], v[66:69]
	s_barrier
	s_add_i32 s52, s52, s28
	v_lshl_add_u64 v[206:207], s[16:17], 0, v[198:199]
	s_mov_b32 m0, s52
	ds_read_b128 v[162:165], v232 offset:16384
	ds_read_b128 v[166:169], v232 offset:17408
	ds_read_b128 v[170:173], v232 offset:18432
	ds_read_b128 v[174:177], v232 offset:19456
	ds_read_b128 v[178:181], v232 offset:20480
	ds_read_b128 v[182:185], v232 offset:21504
	ds_read_b128 v[186:189], v232 offset:22528
	ds_read_b128 v[190:193], v232 offset:23552
	global_load_lds_dwordx4 v[206:207], off
	s_add_i32 m0, s52, 0x2000
	s_add_u32 s52, s16, 0x100000
	v_lshl_add_u64 v[208:209], s[16:17], 0, v[194:195]
	s_addc_u32 s53, s17, 0
	s_add_i32 s57, s57, s28
	global_load_lds_dwordx4 v[208:209], off
	v_lshl_add_u64 v[210:211], s[52:53], 0, v[198:199]
	s_mov_b32 m0, s57
	v_lshl_add_u64 v[212:213], s[22:23], 0, v[196:197]
	global_load_lds_dwordx4 v[210:211], off
	v_lshl_add_u64 v[210:211], s[52:53], 0, v[194:195]
	s_add_i32 m0, s57, 0x2000
	s_nop 0
	global_load_lds_dwordx4 v[210:211], off
	v_lshl_add_u64 v[210:211], s[22:23], 0, v[200:201]
	s_mov_b32 m0, s29
	s_nop 0
	global_load_lds_dwordx4 v[210:211], off
	s_mov_b32 m0, s30
	s_nop 0
	global_load_lds_dwordx4 v[212:213], off
	s_waitcnt vmcnt(8)
	s_waitcnt lgkmcnt(0)
	s_barrier
; #define PG8_STAGE(bufoff, gbase, voff) do { _Pragma("unroll") for (int _i = 0; _i < 2; ++_i) \
;         __builtin_amdgcn_global_load_lds((const unsigned*)((const char*)(gbase) + (voff)[_i]), (PG8_LAS unsigned*)(lds + (bufoff) + ldsw + _i * 8192), 16, 0, 0); } while (0)
; #define PG8_LDA(dst, b, h) do { _Pragma("unroll") for (int m = 0; m < 4; ++m) _Pragma("unroll") for (int k = 0; k < 2; ++k) dst[m][k] = *(const PG8_LAS bf16x8*)(lds + PG8_SA(b, h) + aoff + m * 2048 + k * 1024); } while (0)
; #define PG8_LDB(dst, b, h) do { _Pragma("unroll") for (int n = 0; n < 2; ++n) _Pragma("unroll") for (int k = 0; k < 2; ++k) dst[n][k] = *(const PG8_LAS bf16x8*)(lds + PG8_SB(b, h) + boff + n * 2048 + k * 1024); } while (0)
; #define PG8_MMA(ai, bj, At, Bt) do { __builtin_amdgcn_s_setprio(1); _Pragma("unroll") for (int m = 0; m < 4; ++m) _Pragma("unroll") for (int n = 0; n < 2; ++n) _Pragma("unroll") for (int k = 0; k < 2; ++k) \
;         acc[ai][bj][m][n] = __builtin_amdgcn_mfma_f32_16x16x32_bf16(Bt[n][k], At[m][k], acc[ai][bj][m][n], 0, 0, 0); __builtin_amdgcn_s_setprio(0); } while (0)
; #define PG8_WAIT_V(n) asm volatile("s_waitcnt vmcnt(" #n ")" ::: "memory")
; #define PG8_WAIT_L(n) asm volatile("s_waitcnt lgkmcnt(" #n ")" ::: "memory")
; #define PG8_BAR __builtin_amdgcn_s_barrier()
; #define PG8_SCHED __builtin_amdgcn_sched_barrier(0)
; template <class Epi, class Sched, bool ALIGN_EPI = false, bool SP2 = false>
; __device__ __forceinline__ void gemm_phase(PG8_LAS unsigned char* lds, const Gemm g, const Sched& S, const Epi& E) {
;     ...
;             PG8_WAIT_V(8); PG8_WAIT_L(0); PG8_BAR; PG8_MMA(1, 0, At, B0); PG8_MMA(1, 1, At, B1); PG8_BAR; PG8_SCHED;
;             PG8_LDB(B0, 1, 0); PG8_LDB(B1, 1, 1); PG8_SCHED; PG8_LDA(At, 1, 0); PG8_STAGE(PG8_SA(0, 1), a2 + hstep, voffA);
;             PG8_WAIT_V(8); PG8_WAIT_L(0); PG8_BAR; PG8_MMA(0, 0, At, B0); PG8_MMA(0, 1, At, B1); PG8_BAR; PG8_SCHED;
	v_mfma_f32_16x16x32_bf16 v[62:65], v[130:133], v[162:165], v[62:65]
	v_mfma_f32_16x16x32_bf16 v[58:61], v[138:141], v[162:165], v[58:61]
	v_mfma_f32_16x16x32_bf16 v[50:53], v[130:133], v[170:173], v[50:53]
	v_mfma_f32_16x16x32_bf16 v[42:45], v[138:141], v[170:173], v[42:45]
	v_mfma_f32_16x16x32_bf16 v[34:37], v[130:133], v[178:181], v[34:37]
	v_mfma_f32_16x16x32_bf16 v[26:29], v[138:141], v[178:181], v[26:29]
	v_mfma_f32_16x16x32_bf16 v[18:21], v[130:133], v[186:189], v[18:21]
	v_mfma_f32_16x16x32_bf16 v[10:13], v[138:141], v[186:189], v[10:13]
	v_mfma_f32_16x16x32_bf16 v[62:65], v[134:137], v[166:169], v[62:65]
	v_mfma_f32_16x16x32_bf16 v[58:61], v[142:145], v[166:169], v[58:61]
	v_mfma_f32_16x16x32_bf16 v[50:53], v[134:137], v[174:177], v[50:53]
	v_mfma_f32_16x16x32_bf16 v[42:45], v[142:145], v[174:177], v[42:45]
	v_mfma_f32_16x16x32_bf16 v[34:37], v[134:137], v[182:185], v[34:37]
	v_mfma_f32_16x16x32_bf16 v[26:29], v[142:145], v[182:185], v[26:29]
	v_mfma_f32_16x16x32_bf16 v[18:21], v[134:137], v[190:193], v[18:21]
	v_mfma_f32_16x16x32_bf16 v[10:13], v[142:145], v[190:193], v[10:13]
	v_mfma_f32_16x16x32_bf16 v[54:57], v[146:149], v[162:165], v[54:57]
	v_mfma_f32_16x16x32_bf16 v[46:49], v[154:157], v[162:165], v[46:49]
	v_mfma_f32_16x16x32_bf16 v[38:41], v[146:149], v[170:173], v[38:41]
	v_mfma_f32_16x16x32_bf16 v[30:33], v[154:157], v[170:173], v[30:33]
	v_mfma_f32_16x16x32_bf16 v[22:25], v[146:149], v[178:181], v[22:25]
	v_mfma_f32_16x16x32_bf16 v[14:17], v[154:157], v[178:181], v[14:17]
	v_mfma_f32_16x16x32_bf16 v[6:9], v[146:149], v[186:189], v[6:9]
	v_mfma_f32_16x16x32_bf16 v[2:5], v[154:157], v[186:189], v[2:5]
	v_mfma_f32_16x16x32_bf16 v[54:57], v[150:153], v[166:169], v[54:57]
	v_mfma_f32_16x16x32_bf16 v[46:49], v[158:161], v[166:169], v[46:49]
	v_mfma_f32_16x16x32_bf16 v[38:41], v[150:153], v[174:177], v[38:41]
	v_mfma_f32_16x16x32_bf16 v[30:33], v[158:161], v[174:177], v[30:33]
	v_mfma_f32_16x16x32_bf16 v[22:25], v[150:153], v[182:185], v[22:25]
	v_mfma_f32_16x16x32_bf16 v[14:17], v[158:161], v[182:185], v[14:17]
	v_mfma_f32_16x16x32_bf16 v[6:9], v[150:153], v[190:193], v[6:9]
	v_mfma_f32_16x16x32_bf16 v[2:5], v[158:161], v[190:193], v[2:5]
	s_barrier
	s_add_i32 s52, 0, 0x18000
	s_add_i32 s53, 0, 0x1c000
	v_add_u32_e32 v142, s52, v231
	v_add_u32_e32 v158, s53, v231
	ds_read_b128 v[130:133], v142
	ds_read_b128 v[134:137], v142 offset:1024
	ds_read_b128 v[138:141], v142 offset:2048
	ds_read_b128 v[142:145], v142 offset:3072
	ds_read_b128 v[146:149], v158
	ds_read_b128 v[150:153], v158 offset:1024
	ds_read_b128 v[154:157], v158 offset:2048
	ds_read_b128 v[158:161], v158 offset:3072
	s_add_u32 s22, s22, 0x100000
	s_addc_u32 s23, s23, 0
	s_mov_b32 m0, s31
	v_lshl_add_u64 v[214:215], s[22:23], 0, v[200:201]
	ds_read_b128 v[162:165], v232 offset:32768
	ds_read_b128 v[166:169], v232 offset:33792
	ds_read_b128 v[170:173], v232 offset:34816
	ds_read_b128 v[174:177], v232 offset:35840
	ds_read_b128 v[178:181], v232 offset:36864
	ds_read_b128 v[182:185], v232 offset:37888
	ds_read_b128 v[186:189], v232 offset:38912
	ds_read_b128 v[190:193], v232 offset:39936
	global_load_lds_dwordx4 v[214:215], off
	v_lshl_add_u64 v[214:215], s[22:23], 0, v[196:197]
	s_mov_b32 m0, s34
	s_nop 0
	global_load_lds_dwordx4 v[214:215], off
	s_waitcnt vmcnt(8)
	s_waitcnt lgkmcnt(0)
	s_barrier
	v_mfma_f32_16x16x32_bf16 v[126:129], v[130:133], v[162:165], v[126:129]
	v_mfma_f32_16x16x32_bf16 v[122:125], v[138:141], v[162:165], v[122:125]
	v_mfma_f32_16x16x32_bf16 v[114:117], v[130:133], v[170:173], v[114:117]
	v_mfma_f32_16x16x32_bf16 v[106:109], v[138:141], v[170:173], v[106:109]
	v_mfma_f32_16x16x32_bf16 v[98:101], v[130:133], v[178:181], v[98:101]
	v_mfma_f32_16x16x32_bf16 v[90:93], v[138:141], v[178:181], v[90:93]
	v_mfma_f32_16x16x32_bf16 v[82:85], v[130:133], v[186:189], v[82:85]
	v_mfma_f32_16x16x32_bf16 v[74:77], v[138:141], v[186:189], v[74:77]
	v_mfma_f32_16x16x32_bf16 v[126:129], v[134:137], v[166:169], v[126:129]
	v_mfma_f32_16x16x32_bf16 v[122:125], v[142:145], v[166:169], v[122:125]
	v_mfma_f32_16x16x32_bf16 v[114:117], v[134:137], v[174:177], v[114:117]
	v_mfma_f32_16x16x32_bf16 v[106:109], v[142:145], v[174:177], v[106:109]
	v_mfma_f32_16x16x32_bf16 v[98:101], v[134:137], v[182:185], v[98:101]
	v_mfma_f32_16x16x32_bf16 v[90:93], v[142:145], v[182:185], v[90:93]
	v_mfma_f32_16x16x32_bf16 v[82:85], v[134:137], v[190:193], v[82:85]
	v_mfma_f32_16x16x32_bf16 v[74:77], v[142:145], v[190:193], v[74:77]
	v_mfma_f32_16x16x32_bf16 v[118:121], v[146:149], v[162:165], v[118:121]
	v_mfma_f32_16x16x32_bf16 v[110:113], v[154:157], v[162:165], v[110:113]
	v_mfma_f32_16x16x32_bf16 v[102:105], v[146:149], v[170:173], v[102:105]
	v_mfma_f32_16x16x32_bf16 v[94:97], v[154:157], v[170:173], v[94:97]
	v_mfma_f32_16x16x32_bf16 v[86:89], v[146:149], v[178:181], v[86:89]
	v_mfma_f32_16x16x32_bf16 v[78:81], v[154:157], v[178:181], v[78:81]
	v_mfma_f32_16x16x32_bf16 v[70:73], v[146:149], v[186:189], v[70:73]
	v_mfma_f32_16x16x32_bf16 v[66:69], v[154:157], v[186:189], v[66:69]
	v_mfma_f32_16x16x32_bf16 v[118:121], v[150:153], v[166:169], v[118:121]
	v_mfma_f32_16x16x32_bf16 v[110:113], v[158:161], v[166:169], v[110:113]
	v_mfma_f32_16x16x32_bf16 v[102:105], v[150:153], v[174:177], v[102:105]
	v_mfma_f32_16x16x32_bf16 v[94:97], v[158:161], v[174:177], v[94:97]
	v_mfma_f32_16x16x32_bf16 v[86:89], v[150:153], v[182:185], v[86:89]
	v_mfma_f32_16x16x32_bf16 v[78:81], v[158:161], v[182:185], v[78:81]
	v_mfma_f32_16x16x32_bf16 v[70:73], v[150:153], v[190:193], v[70:73]
	v_mfma_f32_16x16x32_bf16 v[66:69], v[158:161], v[190:193], v[66:69]
	s_barrier
; #define PG8_STAGE(bufoff, gbase, voff) do { _Pragma("unroll") for (int _i = 0; _i < 2; ++_i) \
;         __builtin_amdgcn_global_load_lds((const unsigned*)((const char*)(gbase) + (voff)[_i]), (PG8_LAS unsigned*)(lds + (bufoff) + ldsw + _i * 8192), 16, 0, 0); } while (0)
; #define PG8_LDA(dst, b, h) do { _Pragma("unroll") for (int m = 0; m < 4; ++m) _Pragma("unroll") for (int k = 0; k < 2; ++k) dst[m][k] = *(const PG8_LAS bf16x8*)(lds + PG8_SA(b, h) + aoff + m * 2048 + k * 1024); } while (0)
; #define PG8_MMA(ai, bj, At, Bt) do { __builtin_amdgcn_s_setprio(1); _Pragma("unroll") for (int m = 0; m < 4; ++m) _Pragma("unroll") for (int n = 0; n < 2; ++n) _Pragma("unroll") for (int k = 0; k < 2; ++k) \
;         acc[ai][bj][m][n] = __builtin_amdgcn_mfma_f32_16x16x32_bf16(Bt[n][k], At[m][k], acc[ai][bj][m][n], 0, 0, 0); __builtin_amdgcn_s_setprio(0); } while (0)
; #define PG8_WAIT_V(n) asm volatile("s_waitcnt vmcnt(" #n ")" ::: "memory")
; #define PG8_WAIT_L(n) asm volatile("s_waitcnt lgkmcnt(" #n ")" ::: "memory")
; #define PG8_BAR __builtin_amdgcn_s_barrier()
; #define PG8_SCHED __builtin_amdgcn_sched_barrier(0)
; template <class Epi, class Sched, bool ALIGN_EPI = false, bool SP2 = false>
; __device__ __forceinline__ void gemm_phase(PG8_LAS unsigned char* lds, const Gemm g, const Sched& S, const Epi& E) {
;     ...
;         for (int t = 0; t < nt; t += 2) {
;     ...
;             PG8_LDA(At, 1, 1); PG8_STAGE(PG8_SB(1, 0), b3, voffB); PG8_STAGE(PG8_SB(1, 1), b3 + hstep, voffB); PG8_STAGE(PG8_SA(1, 0), a3, voffA);
;             PG8_WAIT_V(8); PG8_WAIT_L(0); PG8_BAR; PG8_MMA(1, 0, At, B0); PG8_MMA(1, 1, At, B1); PG8_BAR; PG8_SCHED;
	s_add_i32 s22, s52, s28
	v_lshl_add_u64 v[206:207], v[206:207], 0, s[94:95]
	s_mov_b32 m0, s22
	ds_read_b128 v[162:165], v232 offset:49152
	ds_read_b128 v[166:169], v232 offset:50176
	ds_read_b128 v[170:173], v232 offset:51200
	ds_read_b128 v[174:177], v232 offset:52224
	ds_read_b128 v[178:181], v232 offset:53248
	ds_read_b128 v[182:185], v232 offset:54272
	ds_read_b128 v[186:189], v232 offset:55296
	ds_read_b128 v[190:193], v232 offset:56320
	global_load_lds_dwordx4 v[206:207], off
	s_add_i32 m0, s22, 0x2000
	s_add_u32 s16, s16, 0x100080
	v_lshl_add_u64 v[206:207], v[208:209], 0, s[94:95]
	s_addc_u32 s17, s17, 0
	s_add_i32 s22, s53, s28
	global_load_lds_dwordx4 v[206:207], off
	v_lshl_add_u64 v[206:207], s[16:17], 0, v[198:199]
	s_mov_b32 m0, s22
	s_nop 0
	global_load_lds_dwordx4 v[206:207], off
	v_lshl_add_u64 v[206:207], s[16:17], 0, v[194:195]
	s_add_i32 m0, s22, 0x2000
	s_nop 0
	global_load_lds_dwordx4 v[206:207], off
	v_lshl_add_u64 v[206:207], v[210:211], 0, s[94:95]
	s_mov_b32 m0, s33
	s_nop 0
	global_load_lds_dwordx4 v[206:207], off
	v_lshl_add_u64 v[206:207], v[212:213], 0, s[94:95]
	s_mov_b32 m0, s35
	s_nop 0
	global_load_lds_dwordx4 v[206:207], off
	s_waitcnt vmcnt(8)
	s_waitcnt lgkmcnt(0)
	s_barrier
	v_mfma_f32_16x16x32_bf16 v[62:65], v[130:133], v[162:165], v[62:65]
	v_mfma_f32_16x16x32_bf16 v[58:61], v[138:141], v[162:165], v[58:61]
	v_mfma_f32_16x16x32_bf16 v[50:53], v[130:133], v[170:173], v[50:53]
	v_mfma_f32_16x16x32_bf16 v[42:45], v[138:141], v[170:173], v[42:45]
	v_mfma_f32_16x16x32_bf16 v[34:37], v[130:133], v[178:181], v[34:37]
	v_mfma_f32_16x16x32_bf16 v[26:29], v[138:141], v[178:181], v[26:29]
	v_mfma_f32_16x16x32_bf16 v[18:21], v[130:133], v[186:189], v[18:21]
	v_mfma_f32_16x16x32_bf16 v[10:13], v[138:141], v[186:189], v[10:13]
	v_mfma_f32_16x16x32_bf16 v[62:65], v[134:137], v[166:169], v[62:65]
	v_mfma_f32_16x16x32_bf16 v[58:61], v[142:145], v[166:169], v[58:61]
	v_mfma_f32_16x16x32_bf16 v[50:53], v[134:137], v[174:177], v[50:53]
	v_mfma_f32_16x16x32_bf16 v[42:45], v[142:145], v[174:177], v[42:45]
	v_mfma_f32_16x16x32_bf16 v[34:37], v[134:137], v[182:185], v[34:37]
	v_mfma_f32_16x16x32_bf16 v[26:29], v[142:145], v[182:185], v[26:29]
	v_mfma_f32_16x16x32_bf16 v[18:21], v[134:137], v[190:193], v[18:21]
	v_mfma_f32_16x16x32_bf16 v[10:13], v[142:145], v[190:193], v[10:13]
	v_mfma_f32_16x16x32_bf16 v[54:57], v[146:149], v[162:165], v[54:57]
	v_mfma_f32_16x16x32_bf16 v[46:49], v[154:157], v[162:165], v[46:49]
	v_mfma_f32_16x16x32_bf16 v[38:41], v[146:149], v[170:173], v[38:41]
	v_mfma_f32_16x16x32_bf16 v[30:33], v[154:157], v[170:173], v[30:33]
	v_mfma_f32_16x16x32_bf16 v[22:25], v[146:149], v[178:181], v[22:25]
	v_mfma_f32_16x16x32_bf16 v[14:17], v[154:157], v[178:181], v[14:17]
	v_mfma_f32_16x16x32_bf16 v[6:9], v[146:149], v[186:189], v[6:9]
	v_mfma_f32_16x16x32_bf16 v[2:5], v[154:157], v[186:189], v[2:5]
	v_mfma_f32_16x16x32_bf16 v[54:57], v[150:153], v[166:169], v[54:57]
	v_mfma_f32_16x16x32_bf16 v[46:49], v[158:161], v[166:169], v[46:49]
	v_mfma_f32_16x16x32_bf16 v[38:41], v[150:153], v[174:177], v[38:41]
	v_mfma_f32_16x16x32_bf16 v[30:33], v[158:161], v[174:177], v[30:33]
	v_mfma_f32_16x16x32_bf16 v[22:25], v[150:153], v[182:185], v[22:25]
	v_mfma_f32_16x16x32_bf16 v[14:17], v[158:161], v[182:185], v[14:17]
	v_mfma_f32_16x16x32_bf16 v[6:9], v[150:153], v[190:193], v[6:9]
	v_mfma_f32_16x16x32_bf16 v[2:5], v[158:161], v[190:193], v[2:5]
	s_barrier
	s_add_i32 s50, s50, 2
	s_add_u32 s20, s20, 0x100
	s_addc_u32 s21, s21, 0
	s_add_u32 s55, s55, 0x100
	s_addc_u32 s56, s56, 0
	s_cmp_gt_u32 s50, 61
	s_cbranch_scc0 .LBB0_881
	s_and_b64 vcc, exec, s[8:9]
	s_cbranch_vccz .LBB0_884
	s_barrier
